# strategy 8: B1-fragment ds_reads of load segments 1,3 moved into the MFMA shadow of the following compute segment (lgkmcnt(0) before first consumer)
# baseline (speedup 1.0000x reference)
; #define PG8_STAGE(bufoff, gbase, voff) do { _Pragma("unroll") for (int _i = 0; _i < 2; ++_i) \
;         __builtin_amdgcn_global_load_lds((const unsigned*)((const char*)(gbase) + (voff)[_i]), (LAS unsigned*)(lds + (bufoff) + ldsw + _i * 8192), 16, 0, 0); } while (0)
; #define PG8_LDA(dst, b, h) do { _Pragma("unroll") for (int m = 0; m < 4; ++m) _Pragma("unroll") for (int k = 0; k < 2; ++k) dst[m][k] = *(const LAS bf16x8*)(lds + PG8_SA(b, h) + aoff + m * 2048 + k * 1024); } while (0)
; #define PG8_LDB(dst, b, h) do { _Pragma("unroll") for (int n = 0; n < 2; ++n) _Pragma("unroll") for (int k = 0; k < 2; ++k) dst[n][k] = *(const LAS bf16x8*)(lds + PG8_SB(b, h) + boff + n * 2048 + k * 1024); } while (0)
; #define PG8_MMA(ai, bj, At, Bt) do { __builtin_amdgcn_s_setprio(1); _Pragma("unroll") for (int m = 0; m < 4; ++m) _Pragma("unroll") for (int n = 0; n < 2; ++n) _Pragma("unroll") for (int k = 0; k < 2; ++k) \
;         acc[ai][bj][m][n] = __builtin_amdgcn_mfma_f32_16x16x32_bf16(Bt[n][k], At[m][k], acc[ai][bj][m][n], 0, 0, 0); __builtin_amdgcn_s_setprio(0); } while (0)
; #define PG8_WAIT_V(n) asm volatile("s_waitcnt vmcnt(" #n ")" ::: "memory")
; #define PG8_WAIT_L(n) asm volatile("s_waitcnt lgkmcnt(" #n ")" ::: "memory")
; #define PG8_BAR __builtin_amdgcn_s_barrier()
; #define PG8_SCHED __builtin_amdgcn_sched_barrier(0)
; template <class Epi, class Sched>
; __device__ __forceinline__ void gemm_phase(LAS unsigned char* lds, const Gemm g, const Sched& S, const Epi& E) {
;     ...
;             PG8_LDB(B0, 0, 0); PG8_SCHED; PG8_LDA(At, 0, 0); PG8_STAGE(PG8_SA(1, 1), a1 + hstep, voffA);
;             PG8_WAIT_L(8); PG8_BAR; PG8_WAIT_L(0); PG8_MMA(0, 0, At, B0); PG8_BAR; PG8_SCHED;
;             PG8_LDB(B1, 0, 1); PG8_STAGE(PG8_SB(0, 0), b2, voffB);
;             PG8_BAR; PG8_WAIT_L(0); PG8_MMA(0, 1, At, B1); PG8_BAR;
;             PG8_LDA(At, 0, 1); PG8_STAGE(PG8_SA(0, 0), a2, voffA);
;             PG8_BAR; PG8_WAIT_L(0); PG8_MMA(1, 0, At, B0); PG8_BAR; PG8_SCHED;
;             PG8_STAGE(PG8_SB(0, 1), b2 + hstep, voffB);
;             PG8_WAIT_V(6); PG8_BAR; PG8_MMA(1, 1, At, B1); PG8_BAR;
.LBB0_44:
	s_add_u32 s50, s28, 0x100
	s_addc_u32 s51, s29, 0
	s_cmpk_eq_i32 s75, 0x7c
	s_cselect_b32 s55, s27, s51
	s_cselect_b32 s54, s71, s50
	s_cselect_b32 s53, s25, s74
	s_cselect_b32 s52, s72, s73
	s_add_i32 m0, s9, 0xc000
	s_nop 0
	global_load_lds_dwordx4 v150, s[28:29]
	s_add_i32 m0, s9, 0xe000
	s_nop 0
	global_load_lds_dwordx4 v148, s[28:29]
	s_add_i32 s38, 0, 0x10000
	ds_read_b128 v[66:69], v226
	ds_read_b128 v[70:73], v226 offset:1024
	ds_read_b128 v[74:77], v226 offset:2048
	ds_read_b128 v[78:81], v226 offset:3072
	ds_read_b128 v[152:155], v165
	ds_read_b128 v[166:169], v165 offset:1024
	ds_read_b128 v[170:173], v165 offset:2048
	ds_read_b128 v[174:177], v165 offset:3072
	ds_read_b128 v[178:181], v165 offset:4096
	ds_read_b128 v[182:185], v165 offset:5120
	ds_read_b128 v[186:189], v165 offset:6144
	ds_read_b128 v[190:193], v165 offset:7168
	s_add_i32 s39, 0, 0x14000
	s_waitcnt lgkmcnt(0)
	s_barrier
	v_mfma_f32_16x16x32_bf16 v[142:145], v[66:69], v[152:155], v[142:145]
	v_mfma_f32_16x16x32_bf16 v[138:141], v[74:77], v[152:155], v[138:141]
	ds_read_b128 v[194:197], v226 offset:16384
	v_mfma_f32_16x16x32_bf16 v[126:129], v[66:69], v[170:173], v[126:129]
	v_mfma_f32_16x16x32_bf16 v[122:125], v[74:77], v[170:173], v[122:125]
	ds_read_b128 v[198:201], v226 offset:17408
	v_mfma_f32_16x16x32_bf16 v[110:113], v[66:69], v[178:181], v[110:113]
	v_mfma_f32_16x16x32_bf16 v[106:109], v[74:77], v[178:181], v[106:109]
	ds_read_b128 v[202:205], v226 offset:18432
	v_mfma_f32_16x16x32_bf16 v[102:105], v[66:69], v[186:189], v[102:105]
	v_mfma_f32_16x16x32_bf16 v[98:101], v[74:77], v[186:189], v[98:101]
	ds_read_b128 v[210:213], v226 offset:19456
	v_mfma_f32_16x16x32_bf16 v[142:145], v[70:73], v[166:169], v[142:145]
	v_mfma_f32_16x16x32_bf16 v[138:141], v[78:81], v[166:169], v[138:141]
	v_mfma_f32_16x16x32_bf16 v[126:129], v[70:73], v[174:177], v[126:129]
	v_mfma_f32_16x16x32_bf16 v[122:125], v[78:81], v[174:177], v[122:125]
	v_mfma_f32_16x16x32_bf16 v[110:113], v[70:73], v[182:185], v[110:113]
	v_mfma_f32_16x16x32_bf16 v[106:109], v[78:81], v[182:185], v[106:109]
	v_mfma_f32_16x16x32_bf16 v[102:105], v[70:73], v[190:193], v[102:105]
	v_mfma_f32_16x16x32_bf16 v[98:101], v[78:81], v[190:193], v[98:101]
	s_waitcnt lgkmcnt(0)
	v_mfma_f32_16x16x32_bf16 v[134:137], v[194:197], v[152:155], v[134:137]
	v_mfma_f32_16x16x32_bf16 v[130:133], v[202:205], v[152:155], v[130:133]
	v_mfma_f32_16x16x32_bf16 v[118:121], v[194:197], v[170:173], v[118:121]
	v_mfma_f32_16x16x32_bf16 v[114:117], v[202:205], v[170:173], v[114:117]
	v_mfma_f32_16x16x32_bf16 v[94:97], v[194:197], v[178:181], v[94:97]
	v_mfma_f32_16x16x32_bf16 v[90:93], v[202:205], v[178:181], v[90:93]
	v_mfma_f32_16x16x32_bf16 v[86:89], v[194:197], v[186:189], v[86:89]
	v_mfma_f32_16x16x32_bf16 v[82:85], v[202:205], v[186:189], v[82:85]
	v_mfma_f32_16x16x32_bf16 v[134:137], v[198:201], v[166:169], v[134:137]
	v_mfma_f32_16x16x32_bf16 v[130:133], v[210:213], v[166:169], v[130:133]
	v_mfma_f32_16x16x32_bf16 v[118:121], v[198:201], v[174:177], v[118:121]
	v_mfma_f32_16x16x32_bf16 v[114:117], v[210:213], v[174:177], v[114:117]
	v_mfma_f32_16x16x32_bf16 v[94:97], v[198:201], v[182:185], v[94:97]
	v_mfma_f32_16x16x32_bf16 v[90:93], v[210:213], v[182:185], v[90:93]
	v_mfma_f32_16x16x32_bf16 v[86:89], v[198:201], v[190:193], v[86:89]
	v_mfma_f32_16x16x32_bf16 v[82:85], v[210:213], v[190:193], v[82:85]
	s_barrier
	s_add_i32 s28, s38, s60
	s_mov_b32 m0, s28
	s_nop 0
	global_load_lds_dwordx4 v0, s[52:53]
	s_add_i32 m0, s28, 0x2000
	s_nop 0
	global_load_lds_dwordx4 v146, s[52:53]
	s_mov_b32 m0, s9
	s_nop 0
	global_load_lds_dwordx4 v0, s[54:55]
	s_mov_b32 m0, s61
	s_nop 0
	global_load_lds_dwordx4 v146, s[54:55]
	ds_read_b128 v[152:155], v165 offset:16384
	ds_read_b128 v[166:169], v165 offset:17408
	ds_read_b128 v[170:173], v165 offset:18432
	ds_read_b128 v[174:177], v165 offset:19456
	ds_read_b128 v[178:181], v165 offset:20480
	ds_read_b128 v[182:185], v165 offset:21504
	ds_read_b128 v[186:189], v165 offset:22528
	ds_read_b128 v[190:193], v165 offset:23552
	s_waitcnt vmcnt(4)
	s_waitcnt lgkmcnt(0)
	s_barrier
	v_mfma_f32_16x16x32_bf16 v[62:65], v[66:69], v[152:155], v[62:65]
	v_mfma_f32_16x16x32_bf16 v[58:61], v[74:77], v[152:155], v[58:61]
	v_mfma_f32_16x16x32_bf16 v[46:49], v[66:69], v[170:173], v[46:49]
	v_mfma_f32_16x16x32_bf16 v[42:45], v[74:77], v[170:173], v[42:45]
	v_mfma_f32_16x16x32_bf16 v[30:33], v[66:69], v[178:181], v[30:33]
	v_mfma_f32_16x16x32_bf16 v[26:29], v[74:77], v[178:181], v[26:29]
	v_mfma_f32_16x16x32_bf16 v[22:25], v[66:69], v[186:189], v[22:25]
	v_mfma_f32_16x16x32_bf16 v[14:17], v[74:77], v[186:189], v[14:17]
	v_mfma_f32_16x16x32_bf16 v[62:65], v[70:73], v[166:169], v[62:65]
	v_mfma_f32_16x16x32_bf16 v[58:61], v[78:81], v[166:169], v[58:61]
	v_mfma_f32_16x16x32_bf16 v[46:49], v[70:73], v[174:177], v[46:49]
	v_mfma_f32_16x16x32_bf16 v[42:45], v[78:81], v[174:177], v[42:45]
	v_mfma_f32_16x16x32_bf16 v[30:33], v[70:73], v[182:185], v[30:33]
	v_mfma_f32_16x16x32_bf16 v[26:29], v[78:81], v[182:185], v[26:29]
	v_mfma_f32_16x16x32_bf16 v[22:25], v[70:73], v[190:193], v[22:25]
	v_mfma_f32_16x16x32_bf16 v[14:17], v[78:81], v[190:193], v[14:17]
	v_mfma_f32_16x16x32_bf16 v[54:57], v[194:197], v[152:155], v[54:57]
	v_mfma_f32_16x16x32_bf16 v[50:53], v[202:205], v[152:155], v[50:53]
	v_mfma_f32_16x16x32_bf16 v[38:41], v[194:197], v[170:173], v[38:41]
	v_mfma_f32_16x16x32_bf16 v[34:37], v[202:205], v[170:173], v[34:37]
	v_mfma_f32_16x16x32_bf16 v[18:21], v[194:197], v[178:181], v[18:21]
	v_mfma_f32_16x16x32_bf16 v[10:13], v[202:205], v[178:181], v[10:13]
	v_mfma_f32_16x16x32_bf16 v[6:9], v[194:197], v[186:189], v[6:9]
	v_mfma_f32_16x16x32_bf16 v[2:5], v[202:205], v[186:189], v[2:5]
	v_mfma_f32_16x16x32_bf16 v[54:57], v[198:201], v[166:169], v[54:57]
	v_mfma_f32_16x16x32_bf16 v[50:53], v[210:213], v[166:169], v[50:53]
	v_mfma_f32_16x16x32_bf16 v[38:41], v[198:201], v[174:177], v[38:41]
	v_mfma_f32_16x16x32_bf16 v[34:37], v[210:213], v[174:177], v[34:37]
	v_mfma_f32_16x16x32_bf16 v[18:21], v[198:201], v[182:185], v[18:21]
	v_mfma_f32_16x16x32_bf16 v[10:13], v[210:213], v[182:185], v[10:13]
	v_mfma_f32_16x16x32_bf16 v[6:9], v[198:201], v[190:193], v[6:9]
	v_mfma_f32_16x16x32_bf16 v[2:5], v[210:213], v[190:193], v[2:5]
	s_barrier
; #define PG8_STAGE(bufoff, gbase, voff) do { _Pragma("unroll") for (int _i = 0; _i < 2; ++_i) \
;         __builtin_amdgcn_global_load_lds((const unsigned*)((const char*)(gbase) + (voff)[_i]), (LAS unsigned*)(lds + (bufoff) + ldsw + _i * 8192), 16, 0, 0); } while (0)
; #define PG8_LDA(dst, b, h) do { _Pragma("unroll") for (int m = 0; m < 4; ++m) _Pragma("unroll") for (int k = 0; k < 2; ++k) dst[m][k] = *(const LAS bf16x8*)(lds + PG8_SA(b, h) + aoff + m * 2048 + k * 1024); } while (0)
; #define PG8_LDB(dst, b, h) do { _Pragma("unroll") for (int n = 0; n < 2; ++n) _Pragma("unroll") for (int k = 0; k < 2; ++k) dst[n][k] = *(const LAS bf16x8*)(lds + PG8_SB(b, h) + boff + n * 2048 + k * 1024); } while (0)
; #define PG8_MMA(ai, bj, At, Bt) do { __builtin_amdgcn_s_setprio(1); _Pragma("unroll") for (int m = 0; m < 4; ++m) _Pragma("unroll") for (int n = 0; n < 2; ++n) _Pragma("unroll") for (int k = 0; k < 2; ++k) \
;         acc[ai][bj][m][n] = __builtin_amdgcn_mfma_f32_16x16x32_bf16(Bt[n][k], At[m][k], acc[ai][bj][m][n], 0, 0, 0); __builtin_amdgcn_s_setprio(0); } while (0)
; #define PG8_WAIT_V(n) asm volatile("s_waitcnt vmcnt(" #n ")" ::: "memory")
; #define PG8_WAIT_L(n) asm volatile("s_waitcnt lgkmcnt(" #n ")" ::: "memory")
; #define PG8_BAR __builtin_amdgcn_s_barrier()
; #define PG8_SCHED __builtin_amdgcn_sched_barrier(0)
; template <class Epi, class Sched>
; __device__ __forceinline__ void gemm_phase(LAS unsigned char* lds, const Gemm g, const Sched& S, const Epi& E) {
;     ...
;             PG8_LDB(B0, 1, 0); PG8_SCHED; PG8_LDA(At, 1, 0); PG8_STAGE(PG8_SA(0, 1), a2 + hstep, voffA);
;             PG8_WAIT_L(8); PG8_BAR; PG8_WAIT_L(0); PG8_MMA(0, 0, At, B0); PG8_BAR; PG8_SCHED;
;             PG8_LDB(B1, 1, 1); PG8_STAGE(PG8_SB(1, 0), b3, voffB);
;             PG8_BAR; PG8_WAIT_L(0); PG8_MMA(0, 1, At, B1); PG8_BAR;
;             PG8_LDA(At, 1, 1); PG8_STAGE(PG8_SA(1, 0), a3, voffA);
;             PG8_BAR; PG8_WAIT_L(0); PG8_MMA(1, 0, At, B0); PG8_BAR; PG8_SCHED;
;             PG8_STAGE(PG8_SB(1, 1), b3 + hstep, voffB);
;             PG8_WAIT_V(6); PG8_BAR; PG8_MMA(1, 1, At, B1); PG8_BAR;
	s_add_u32 s28, s52, 0x200000
	s_addc_u32 s29, s53, 0
	s_add_i32 s38, s39, s60
	s_mov_b32 m0, s38
	s_nop 0
	global_load_lds_dwordx4 v0, s[28:29]
	s_add_i32 m0, s38, 0x2000
	s_nop 0
	global_load_lds_dwordx4 v146, s[28:29]
	s_add_u32 s28, s54, 0x200000
	s_addc_u32 s29, s55, 0
	s_mov_b32 m0, s62
	s_nop 0
	global_load_lds_dwordx4 v0, s[28:29]
	s_mov_b32 m0, s63
	s_nop 0
	global_load_lds_dwordx4 v146, s[28:29]
	s_add_i32 s38, 0, 0x18000
	ds_read_b128 v[66:69], v226 offset:32768
	ds_read_b128 v[70:73], v226 offset:33792
	ds_read_b128 v[74:77], v226 offset:34816
	ds_read_b128 v[78:81], v226 offset:35840
	ds_read_b128 v[152:155], v165 offset:32768
	ds_read_b128 v[166:169], v165 offset:33792
	ds_read_b128 v[170:173], v165 offset:34816
	ds_read_b128 v[174:177], v165 offset:35840
	ds_read_b128 v[178:181], v165 offset:36864
	ds_read_b128 v[182:185], v165 offset:37888
	ds_read_b128 v[186:189], v165 offset:38912
	ds_read_b128 v[190:193], v165 offset:39936
	s_add_i32 s39, 0, 0x1c000
	s_waitcnt lgkmcnt(0)
	s_barrier
	v_mfma_f32_16x16x32_bf16 v[142:145], v[66:69], v[152:155], v[142:145]
	v_mfma_f32_16x16x32_bf16 v[138:141], v[74:77], v[152:155], v[138:141]
	ds_read_b128 v[194:197], v226 offset:49152
	v_mfma_f32_16x16x32_bf16 v[126:129], v[66:69], v[170:173], v[126:129]
	v_mfma_f32_16x16x32_bf16 v[122:125], v[74:77], v[170:173], v[122:125]
	ds_read_b128 v[198:201], v226 offset:50176
	v_mfma_f32_16x16x32_bf16 v[110:113], v[66:69], v[178:181], v[110:113]
	v_mfma_f32_16x16x32_bf16 v[106:109], v[74:77], v[178:181], v[106:109]
	ds_read_b128 v[202:205], v226 offset:51200
	v_mfma_f32_16x16x32_bf16 v[102:105], v[66:69], v[186:189], v[102:105]
	v_mfma_f32_16x16x32_bf16 v[98:101], v[74:77], v[186:189], v[98:101]
	ds_read_b128 v[210:213], v226 offset:52224
	v_mfma_f32_16x16x32_bf16 v[142:145], v[70:73], v[166:169], v[142:145]
	v_mfma_f32_16x16x32_bf16 v[138:141], v[78:81], v[166:169], v[138:141]
	v_mfma_f32_16x16x32_bf16 v[126:129], v[70:73], v[174:177], v[126:129]
	v_mfma_f32_16x16x32_bf16 v[122:125], v[78:81], v[174:177], v[122:125]
	v_mfma_f32_16x16x32_bf16 v[110:113], v[70:73], v[182:185], v[110:113]
	v_mfma_f32_16x16x32_bf16 v[106:109], v[78:81], v[182:185], v[106:109]
	v_mfma_f32_16x16x32_bf16 v[102:105], v[70:73], v[190:193], v[102:105]
	v_mfma_f32_16x16x32_bf16 v[98:101], v[78:81], v[190:193], v[98:101]
	s_waitcnt lgkmcnt(0)
	v_mfma_f32_16x16x32_bf16 v[134:137], v[194:197], v[152:155], v[134:137]
	v_mfma_f32_16x16x32_bf16 v[130:133], v[202:205], v[152:155], v[130:133]
	v_mfma_f32_16x16x32_bf16 v[118:121], v[194:197], v[170:173], v[118:121]
	v_mfma_f32_16x16x32_bf16 v[114:117], v[202:205], v[170:173], v[114:117]
	v_mfma_f32_16x16x32_bf16 v[94:97], v[194:197], v[178:181], v[94:97]
	v_mfma_f32_16x16x32_bf16 v[90:93], v[202:205], v[178:181], v[90:93]
	v_mfma_f32_16x16x32_bf16 v[86:89], v[194:197], v[186:189], v[86:89]
	v_mfma_f32_16x16x32_bf16 v[82:85], v[202:205], v[186:189], v[82:85]
	v_mfma_f32_16x16x32_bf16 v[134:137], v[198:201], v[166:169], v[134:137]
	v_mfma_f32_16x16x32_bf16 v[130:133], v[210:213], v[166:169], v[130:133]
	v_mfma_f32_16x16x32_bf16 v[118:121], v[198:201], v[174:177], v[118:121]
	v_mfma_f32_16x16x32_bf16 v[114:117], v[210:213], v[174:177], v[114:117]
	v_mfma_f32_16x16x32_bf16 v[94:97], v[198:201], v[182:185], v[94:97]
	v_mfma_f32_16x16x32_bf16 v[90:93], v[210:213], v[182:185], v[90:93]
	v_mfma_f32_16x16x32_bf16 v[86:89], v[198:201], v[190:193], v[86:89]
	v_mfma_f32_16x16x32_bf16 v[82:85], v[210:213], v[190:193], v[82:85]
	s_barrier
	s_add_i32 s28, s38, s60
	s_add_u32 s100, s52, s36
	s_addc_u32 s101, s53, s37
	s_mov_b32 m0, s28
	s_nop 0
	global_load_lds_dwordx4 v0, s[100:101]
	s_add_i32 m0, s28, 0x2000
	s_nop 0
	global_load_lds_dwordx4 v146, s[100:101]
	s_mov_b32 m0, s66
	s_add_u32 s100, s54, s36
	s_addc_u32 s101, s55, s37
	global_load_lds_dwordx4 v0, s[100:101]
	s_mov_b32 m0, s67
	s_nop 0
	global_load_lds_dwordx4 v146, s[100:101]
	ds_read_b128 v[152:155], v165 offset:49152
	ds_read_b128 v[166:169], v165 offset:50176
	ds_read_b128 v[170:173], v165 offset:51200
	ds_read_b128 v[174:177], v165 offset:52224
	ds_read_b128 v[178:181], v165 offset:53248
	ds_read_b128 v[182:185], v165 offset:54272
	ds_read_b128 v[186:189], v165 offset:55296
	ds_read_b128 v[190:193], v165 offset:56320
	s_waitcnt vmcnt(4)
	s_waitcnt lgkmcnt(0)
	s_barrier
	v_mfma_f32_16x16x32_bf16 v[62:65], v[66:69], v[152:155], v[62:65]
	v_mfma_f32_16x16x32_bf16 v[58:61], v[74:77], v[152:155], v[58:61]
	v_mfma_f32_16x16x32_bf16 v[46:49], v[66:69], v[170:173], v[46:49]
	v_mfma_f32_16x16x32_bf16 v[42:45], v[74:77], v[170:173], v[42:45]
	v_mfma_f32_16x16x32_bf16 v[30:33], v[66:69], v[178:181], v[30:33]
	v_mfma_f32_16x16x32_bf16 v[26:29], v[74:77], v[178:181], v[26:29]
	v_mfma_f32_16x16x32_bf16 v[22:25], v[66:69], v[186:189], v[22:25]
	v_mfma_f32_16x16x32_bf16 v[14:17], v[74:77], v[186:189], v[14:17]
	v_mfma_f32_16x16x32_bf16 v[62:65], v[70:73], v[166:169], v[62:65]
	v_mfma_f32_16x16x32_bf16 v[58:61], v[78:81], v[166:169], v[58:61]
	v_mfma_f32_16x16x32_bf16 v[46:49], v[70:73], v[174:177], v[46:49]
	v_mfma_f32_16x16x32_bf16 v[42:45], v[78:81], v[174:177], v[42:45]
	v_mfma_f32_16x16x32_bf16 v[30:33], v[70:73], v[182:185], v[30:33]
	v_mfma_f32_16x16x32_bf16 v[26:29], v[78:81], v[182:185], v[26:29]
	v_mfma_f32_16x16x32_bf16 v[22:25], v[70:73], v[190:193], v[22:25]
	v_mfma_f32_16x16x32_bf16 v[14:17], v[78:81], v[190:193], v[14:17]
	s_add_u32 s28, s52, 0x200080
	s_addc_u32 s29, s53, 0
	s_add_i32 s38, s39, s60
	s_mov_b32 m0, s38
	s_nop 0
	global_load_lds_dwordx4 v0, s[28:29]
	s_add_i32 m0, s38, 0x2000
	s_nop 0
	global_load_lds_dwordx4 v146, s[28:29]
	v_mfma_f32_16x16x32_bf16 v[54:57], v[194:197], v[152:155], v[54:57]
	v_mfma_f32_16x16x32_bf16 v[50:53], v[202:205], v[152:155], v[50:53]
	v_mfma_f32_16x16x32_bf16 v[38:41], v[194:197], v[170:173], v[38:41]
	v_mfma_f32_16x16x32_bf16 v[34:37], v[202:205], v[170:173], v[34:37]
	v_mfma_f32_16x16x32_bf16 v[18:21], v[194:197], v[178:181], v[18:21]
	v_mfma_f32_16x16x32_bf16 v[10:13], v[202:205], v[178:181], v[10:13]
	v_mfma_f32_16x16x32_bf16 v[6:9], v[194:197], v[186:189], v[6:9]
	v_mfma_f32_16x16x32_bf16 v[2:5], v[202:205], v[186:189], v[2:5]
	v_mfma_f32_16x16x32_bf16 v[54:57], v[198:201], v[166:169], v[54:57]
	v_mfma_f32_16x16x32_bf16 v[50:53], v[210:213], v[166:169], v[50:53]
	v_mfma_f32_16x16x32_bf16 v[38:41], v[198:201], v[174:177], v[38:41]
	v_mfma_f32_16x16x32_bf16 v[34:37], v[210:213], v[174:177], v[34:37]
	v_mfma_f32_16x16x32_bf16 v[18:21], v[198:201], v[182:185], v[18:21]
	v_mfma_f32_16x16x32_bf16 v[10:13], v[210:213], v[182:185], v[10:13]
	v_mfma_f32_16x16x32_bf16 v[6:9], v[198:201], v[190:193], v[6:9]
	v_mfma_f32_16x16x32_bf16 v[2:5], v[210:213], v[190:193], v[2:5]
	s_add_i32 s75, s75, 2
	s_add_u32 s73, s73, 0x100
	s_addc_u32 s74, s74, 0
	s_cmpk_gt_u32 s75, 0x7d
	s_mov_b64 s[28:29], s[50:51]
	s_barrier
	s_cbranch_scc0 .LBB0_44
	s_cmp_lt_i32 s8, 64
	s_cselect_b64 s[50:51], -1, 0
	s_cmp_gt_i32 s8, 63
	s_cbranch_scc0 .LBB0_35
	s_mov_b64 s[52:53], 0x18000
	s_mov_b64 s[28:29], s[46:47]
	s_branch .LBB0_36

; #define PG8_STAGE(bufoff, gbase, voff) do { _Pragma("unroll") for (int _i = 0; _i < 2; ++_i) \
;         __builtin_amdgcn_global_load_lds((const unsigned*)((const char*)(gbase) + (voff)[_i]), (LAS unsigned*)(lds + (bufoff) + ldsw + _i * 8192), 16, 0, 0); } while (0)
; #define PG8_LDA(dst, b, h) do { _Pragma("unroll") for (int m = 0; m < 4; ++m) _Pragma("unroll") for (int k = 0; k < 2; ++k) dst[m][k] = *(const LAS bf16x8*)(lds + PG8_SA(b, h) + aoff + m * 2048 + k * 1024); } while (0)
; #define PG8_LDB(dst, b, h) do { _Pragma("unroll") for (int n = 0; n < 2; ++n) _Pragma("unroll") for (int k = 0; k < 2; ++k) dst[n][k] = *(const LAS bf16x8*)(lds + PG8_SB(b, h) + boff + n * 2048 + k * 1024); } while (0)
; #define PG8_MMA(ai, bj, At, Bt) do { __builtin_amdgcn_s_setprio(1); _Pragma("unroll") for (int m = 0; m < 4; ++m) _Pragma("unroll") for (int n = 0; n < 2; ++n) _Pragma("unroll") for (int k = 0; k < 2; ++k) \
;         acc[ai][bj][m][n] = __builtin_amdgcn_mfma_f32_16x16x32_bf16(Bt[n][k], At[m][k], acc[ai][bj][m][n], 0, 0, 0); __builtin_amdgcn_s_setprio(0); } while (0)
; #define PG8_WAIT_V(n) asm volatile("s_waitcnt vmcnt(" #n ")" ::: "memory")
; #define PG8_WAIT_L(n) asm volatile("s_waitcnt lgkmcnt(" #n ")" ::: "memory")
; #define PG8_BAR __builtin_amdgcn_s_barrier()
; #define PG8_SCHED __builtin_amdgcn_sched_barrier(0)
; template <class Epi, class Sched>
; __device__ __forceinline__ void gemm_phase(LAS unsigned char* lds, const Gemm g, const Sched& S, const Epi& E) {
;     ...
;             PG8_LDB(B0, 0, 0); PG8_SCHED; PG8_LDA(At, 0, 0); PG8_STAGE(PG8_SA(1, 1), a1 + hstep, voffA);
;             PG8_WAIT_L(8); PG8_BAR; PG8_WAIT_L(0); PG8_MMA(0, 0, At, B0); PG8_BAR; PG8_SCHED;
;             PG8_LDB(B1, 0, 1); PG8_STAGE(PG8_SB(0, 0), b2, voffB);
;             PG8_BAR; PG8_WAIT_L(0); PG8_MMA(0, 1, At, B1); PG8_BAR;
;             PG8_LDA(At, 0, 1); PG8_STAGE(PG8_SA(0, 0), a2, voffA);
;             PG8_BAR; PG8_WAIT_L(0); PG8_MMA(1, 0, At, B0); PG8_BAR; PG8_SCHED;
;             PG8_STAGE(PG8_SB(0, 1), b2 + hstep, voffB);
;             PG8_WAIT_V(6); PG8_BAR; PG8_MMA(1, 1, At, B1); PG8_BAR;
.LBB0_58:
	s_add_u32 s52, s50, 0x100
	s_addc_u32 s53, s51, 0
	s_cmp_eq_u32 s71, 28
	s_cselect_b32 s57, s11, s53
	s_cselect_b32 s56, s29, s52
	s_cselect_b32 s55, s41, s70
	s_cselect_b32 s54, s43, s69
	s_add_i32 m0, s25, 0xc000
	s_nop 0
	global_load_lds_dwordx4 v134, s[50:51]
	s_add_i32 m0, s25, 0xe000
	s_nop 0
	global_load_lds_dwordx4 v132, s[50:51]
	s_add_i32 s38, 0, 0x10000
	ds_read_b128 v[140:143], v226
	ds_read_b128 v[144:147], v226 offset:1024
	ds_read_b128 v[148:151], v226 offset:2048
	ds_read_b128 v[152:155], v226 offset:3072
	ds_read_b128 v[160:163], v139
	ds_read_b128 v[164:167], v139 offset:1024
	ds_read_b128 v[168:171], v139 offset:2048
	ds_read_b128 v[172:175], v139 offset:3072
	ds_read_b128 v[176:179], v139 offset:4096
	ds_read_b128 v[180:183], v139 offset:5120
	ds_read_b128 v[184:187], v139 offset:6144
	ds_read_b128 v[188:191], v139 offset:7168
	s_add_i32 s50, 0, 0x14000
	s_waitcnt lgkmcnt(0)
	s_barrier
	v_mfma_f32_16x16x32_bf16 v[126:129], v[140:143], v[160:163], v[126:129]
	v_mfma_f32_16x16x32_bf16 v[122:125], v[148:151], v[160:163], v[122:125]
	ds_read_b128 v[192:195], v226 offset:16384
	v_mfma_f32_16x16x32_bf16 v[118:121], v[140:143], v[168:171], v[118:121]
	v_mfma_f32_16x16x32_bf16 v[114:117], v[148:151], v[168:171], v[114:117]
	ds_read_b128 v[196:199], v226 offset:17408
	v_mfma_f32_16x16x32_bf16 v[106:109], v[140:143], v[176:179], v[106:109]
	v_mfma_f32_16x16x32_bf16 v[98:101], v[148:151], v[176:179], v[98:101]
	ds_read_b128 v[200:203], v226 offset:18432
	v_mfma_f32_16x16x32_bf16 v[90:93], v[140:143], v[184:187], v[90:93]
	v_mfma_f32_16x16x32_bf16 v[82:85], v[148:151], v[184:187], v[82:85]
	ds_read_b128 v[204:207], v226 offset:19456
	v_mfma_f32_16x16x32_bf16 v[126:129], v[144:147], v[164:167], v[126:129]
	v_mfma_f32_16x16x32_bf16 v[122:125], v[152:155], v[164:167], v[122:125]
	v_mfma_f32_16x16x32_bf16 v[118:121], v[144:147], v[172:175], v[118:121]
	v_mfma_f32_16x16x32_bf16 v[114:117], v[152:155], v[172:175], v[114:117]
	v_mfma_f32_16x16x32_bf16 v[106:109], v[144:147], v[180:183], v[106:109]
	v_mfma_f32_16x16x32_bf16 v[98:101], v[152:155], v[180:183], v[98:101]
	v_mfma_f32_16x16x32_bf16 v[90:93], v[144:147], v[188:191], v[90:93]
	v_mfma_f32_16x16x32_bf16 v[82:85], v[152:155], v[188:191], v[82:85]
	s_waitcnt lgkmcnt(0)
	v_mfma_f32_16x16x32_bf16 v[110:113], v[192:195], v[160:163], v[110:113]
	v_mfma_f32_16x16x32_bf16 v[102:105], v[200:203], v[160:163], v[102:105]
	v_mfma_f32_16x16x32_bf16 v[94:97], v[192:195], v[168:171], v[94:97]
	v_mfma_f32_16x16x32_bf16 v[86:89], v[200:203], v[168:171], v[86:89]
	v_mfma_f32_16x16x32_bf16 v[78:81], v[192:195], v[176:179], v[78:81]
	v_mfma_f32_16x16x32_bf16 v[74:77], v[200:203], v[176:179], v[74:77]
	v_mfma_f32_16x16x32_bf16 v[70:73], v[192:195], v[184:187], v[70:73]
	v_mfma_f32_16x16x32_bf16 v[66:69], v[200:203], v[184:187], v[66:69]
	v_mfma_f32_16x16x32_bf16 v[110:113], v[196:199], v[164:167], v[110:113]
	v_mfma_f32_16x16x32_bf16 v[102:105], v[204:207], v[164:167], v[102:105]
	v_mfma_f32_16x16x32_bf16 v[94:97], v[196:199], v[172:175], v[94:97]
	v_mfma_f32_16x16x32_bf16 v[86:89], v[204:207], v[172:175], v[86:89]
	v_mfma_f32_16x16x32_bf16 v[78:81], v[196:199], v[180:183], v[78:81]
	v_mfma_f32_16x16x32_bf16 v[74:77], v[204:207], v[180:183], v[74:77]
	v_mfma_f32_16x16x32_bf16 v[70:73], v[196:199], v[188:191], v[70:73]
	v_mfma_f32_16x16x32_bf16 v[66:69], v[204:207], v[188:191], v[66:69]
	s_barrier
	s_add_i32 s38, s38, s63
	s_mov_b32 m0, s38
	s_nop 0
	global_load_lds_dwordx4 v0, s[54:55]
	s_add_i32 m0, s38, 0x2000
	s_nop 0
	global_load_lds_dwordx4 v130, s[54:55]
	s_mov_b32 m0, s25
	s_nop 0
	global_load_lds_dwordx4 v0, s[56:57]
	s_mov_b32 m0, s27
	s_nop 0
	global_load_lds_dwordx4 v130, s[56:57]
	ds_read_b128 v[160:163], v139 offset:16384
	ds_read_b128 v[164:167], v139 offset:17408
	ds_read_b128 v[168:171], v139 offset:18432
	ds_read_b128 v[172:175], v139 offset:19456
	ds_read_b128 v[176:179], v139 offset:20480
	ds_read_b128 v[180:183], v139 offset:21504
	ds_read_b128 v[184:187], v139 offset:22528
	ds_read_b128 v[188:191], v139 offset:23552
	s_waitcnt vmcnt(4)
	s_waitcnt lgkmcnt(0)
	s_barrier
	v_mfma_f32_16x16x32_bf16 v[62:65], v[140:143], v[160:163], v[62:65]
	v_mfma_f32_16x16x32_bf16 v[58:61], v[148:151], v[160:163], v[58:61]
	v_mfma_f32_16x16x32_bf16 v[54:57], v[140:143], v[168:171], v[54:57]
	v_mfma_f32_16x16x32_bf16 v[50:53], v[148:151], v[168:171], v[50:53]
	v_mfma_f32_16x16x32_bf16 v[38:41], v[140:143], v[176:179], v[38:41]
	v_mfma_f32_16x16x32_bf16 v[34:37], v[148:151], v[176:179], v[34:37]
	v_mfma_f32_16x16x32_bf16 v[22:25], v[140:143], v[184:187], v[22:25]
	v_mfma_f32_16x16x32_bf16 v[18:21], v[148:151], v[184:187], v[18:21]
	v_mfma_f32_16x16x32_bf16 v[62:65], v[144:147], v[164:167], v[62:65]
	v_mfma_f32_16x16x32_bf16 v[58:61], v[152:155], v[164:167], v[58:61]
	v_mfma_f32_16x16x32_bf16 v[54:57], v[144:147], v[172:175], v[54:57]
	v_mfma_f32_16x16x32_bf16 v[50:53], v[152:155], v[172:175], v[50:53]
	v_mfma_f32_16x16x32_bf16 v[38:41], v[144:147], v[180:183], v[38:41]
	v_mfma_f32_16x16x32_bf16 v[34:37], v[152:155], v[180:183], v[34:37]
	v_mfma_f32_16x16x32_bf16 v[22:25], v[144:147], v[188:191], v[22:25]
	v_mfma_f32_16x16x32_bf16 v[18:21], v[152:155], v[188:191], v[18:21]
	v_mfma_f32_16x16x32_bf16 v[46:49], v[192:195], v[160:163], v[46:49]
	v_mfma_f32_16x16x32_bf16 v[42:45], v[200:203], v[160:163], v[42:45]
	v_mfma_f32_16x16x32_bf16 v[30:33], v[192:195], v[168:171], v[30:33]
	v_mfma_f32_16x16x32_bf16 v[26:29], v[200:203], v[168:171], v[26:29]
	v_mfma_f32_16x16x32_bf16 v[14:17], v[192:195], v[176:179], v[14:17]
	v_mfma_f32_16x16x32_bf16 v[10:13], v[200:203], v[176:179], v[10:13]
	v_mfma_f32_16x16x32_bf16 v[6:9], v[192:195], v[184:187], v[6:9]
	v_mfma_f32_16x16x32_bf16 v[2:5], v[200:203], v[184:187], v[2:5]
	v_mfma_f32_16x16x32_bf16 v[46:49], v[196:199], v[164:167], v[46:49]
	v_mfma_f32_16x16x32_bf16 v[42:45], v[204:207], v[164:167], v[42:45]
	v_mfma_f32_16x16x32_bf16 v[30:33], v[196:199], v[172:175], v[30:33]
	v_mfma_f32_16x16x32_bf16 v[26:29], v[204:207], v[172:175], v[26:29]
	v_mfma_f32_16x16x32_bf16 v[14:17], v[196:199], v[180:183], v[14:17]
	v_mfma_f32_16x16x32_bf16 v[10:13], v[204:207], v[180:183], v[10:13]
	v_mfma_f32_16x16x32_bf16 v[6:9], v[196:199], v[188:191], v[6:9]
	v_mfma_f32_16x16x32_bf16 v[2:5], v[204:207], v[188:191], v[2:5]
	s_barrier
; #define PG8_STAGE(bufoff, gbase, voff) do { _Pragma("unroll") for (int _i = 0; _i < 2; ++_i) \
;         __builtin_amdgcn_global_load_lds((const unsigned*)((const char*)(gbase) + (voff)[_i]), (LAS unsigned*)(lds + (bufoff) + ldsw + _i * 8192), 16, 0, 0); } while (0)
; #define PG8_LDA(dst, b, h) do { _Pragma("unroll") for (int m = 0; m < 4; ++m) _Pragma("unroll") for (int k = 0; k < 2; ++k) dst[m][k] = *(const LAS bf16x8*)(lds + PG8_SA(b, h) + aoff + m * 2048 + k * 1024); } while (0)
; #define PG8_LDB(dst, b, h) do { _Pragma("unroll") for (int n = 0; n < 2; ++n) _Pragma("unroll") for (int k = 0; k < 2; ++k) dst[n][k] = *(const LAS bf16x8*)(lds + PG8_SB(b, h) + boff + n * 2048 + k * 1024); } while (0)
; #define PG8_MMA(ai, bj, At, Bt) do { __builtin_amdgcn_s_setprio(1); _Pragma("unroll") for (int m = 0; m < 4; ++m) _Pragma("unroll") for (int n = 0; n < 2; ++n) _Pragma("unroll") for (int k = 0; k < 2; ++k) \
;         acc[ai][bj][m][n] = __builtin_amdgcn_mfma_f32_16x16x32_bf16(Bt[n][k], At[m][k], acc[ai][bj][m][n], 0, 0, 0); __builtin_amdgcn_s_setprio(0); } while (0)
; #define PG8_WAIT_L(n) asm volatile("s_waitcnt lgkmcnt(" #n ")" ::: "memory")
; #define PG8_BAR __builtin_amdgcn_s_barrier()
; #define PG8_SCHED __builtin_amdgcn_sched_barrier(0)
; template <class Epi, class Sched>
; __device__ __forceinline__ void gemm_phase(LAS unsigned char* lds, const Gemm g, const Sched& S, const Epi& E) {
;     ...
;             PG8_LDB(B0, 1, 0); PG8_SCHED; PG8_LDA(At, 1, 0); PG8_STAGE(PG8_SA(0, 1), a2 + hstep, voffA);
;             PG8_WAIT_L(8); PG8_BAR; PG8_WAIT_L(0); PG8_MMA(0, 0, At, B0); PG8_BAR; PG8_SCHED;
;             PG8_LDB(B1, 1, 1); PG8_STAGE(PG8_SB(1, 0), b3, voffB);
;             PG8_BAR; PG8_WAIT_L(0); PG8_MMA(0, 1, At, B1); PG8_BAR;
;             PG8_LDA(At, 1, 1); PG8_STAGE(PG8_SA(1, 0), a3, voffA);
;             PG8_BAR; PG8_WAIT_L(0); PG8_MMA(1, 0, At, B0); PG8_BAR; PG8_SCHED;
	s_add_u32 s38, s54, 0x200000
	s_addc_u32 s39, s55, 0
	s_add_i32 s50, s50, s63
	s_mov_b32 m0, s50
	s_nop 0
	global_load_lds_dwordx4 v0, s[38:39]
	s_add_i32 m0, s50, 0x2000
	s_nop 0
	global_load_lds_dwordx4 v130, s[38:39]
	s_add_u32 s38, s56, 0x200000
	s_addc_u32 s39, s57, 0
	s_mov_b32 m0, s64
	s_nop 0
	global_load_lds_dwordx4 v0, s[38:39]
	s_mov_b32 m0, s65
	s_nop 0
	global_load_lds_dwordx4 v130, s[38:39]
	s_add_i32 s50, 0, 0x18000
	ds_read_b128 v[140:143], v226 offset:32768
	ds_read_b128 v[144:147], v226 offset:33792
	ds_read_b128 v[148:151], v226 offset:34816
	ds_read_b128 v[152:155], v226 offset:35840
	ds_read_b128 v[160:163], v139 offset:32768
	ds_read_b128 v[164:167], v139 offset:33792
	ds_read_b128 v[168:171], v139 offset:34816
	ds_read_b128 v[172:175], v139 offset:35840
	ds_read_b128 v[176:179], v139 offset:36864
	ds_read_b128 v[180:183], v139 offset:37888
	ds_read_b128 v[184:187], v139 offset:38912
	ds_read_b128 v[188:191], v139 offset:39936
	s_add_i32 s51, 0, 0x1c000
	s_waitcnt lgkmcnt(0)
	s_barrier
	v_mfma_f32_16x16x32_bf16 v[126:129], v[140:143], v[160:163], v[126:129]
	v_mfma_f32_16x16x32_bf16 v[122:125], v[148:151], v[160:163], v[122:125]
	ds_read_b128 v[192:195], v226 offset:49152
	v_mfma_f32_16x16x32_bf16 v[118:121], v[140:143], v[168:171], v[118:121]
	v_mfma_f32_16x16x32_bf16 v[114:117], v[148:151], v[168:171], v[114:117]
	ds_read_b128 v[196:199], v226 offset:50176
	v_mfma_f32_16x16x32_bf16 v[106:109], v[140:143], v[176:179], v[106:109]
	v_mfma_f32_16x16x32_bf16 v[98:101], v[148:151], v[176:179], v[98:101]
	ds_read_b128 v[200:203], v226 offset:51200
	v_mfma_f32_16x16x32_bf16 v[90:93], v[140:143], v[184:187], v[90:93]
	v_mfma_f32_16x16x32_bf16 v[82:85], v[148:151], v[184:187], v[82:85]
	ds_read_b128 v[204:207], v226 offset:52224
	v_mfma_f32_16x16x32_bf16 v[126:129], v[144:147], v[164:167], v[126:129]
	v_mfma_f32_16x16x32_bf16 v[122:125], v[152:155], v[164:167], v[122:125]
	v_mfma_f32_16x16x32_bf16 v[118:121], v[144:147], v[172:175], v[118:121]
	v_mfma_f32_16x16x32_bf16 v[114:117], v[152:155], v[172:175], v[114:117]
	v_mfma_f32_16x16x32_bf16 v[106:109], v[144:147], v[180:183], v[106:109]
	v_mfma_f32_16x16x32_bf16 v[98:101], v[152:155], v[180:183], v[98:101]
	v_mfma_f32_16x16x32_bf16 v[90:93], v[144:147], v[188:191], v[90:93]
	v_mfma_f32_16x16x32_bf16 v[82:85], v[152:155], v[188:191], v[82:85]
	s_waitcnt lgkmcnt(0)
	v_mfma_f32_16x16x32_bf16 v[110:113], v[192:195], v[160:163], v[110:113]
	v_mfma_f32_16x16x32_bf16 v[102:105], v[200:203], v[160:163], v[102:105]
	v_mfma_f32_16x16x32_bf16 v[94:97], v[192:195], v[168:171], v[94:97]
	v_mfma_f32_16x16x32_bf16 v[86:89], v[200:203], v[168:171], v[86:89]
	v_mfma_f32_16x16x32_bf16 v[78:81], v[192:195], v[176:179], v[78:81]
	v_mfma_f32_16x16x32_bf16 v[74:77], v[200:203], v[176:179], v[74:77]
	v_mfma_f32_16x16x32_bf16 v[70:73], v[192:195], v[184:187], v[70:73]
	v_mfma_f32_16x16x32_bf16 v[66:69], v[200:203], v[184:187], v[66:69]
	v_mfma_f32_16x16x32_bf16 v[110:113], v[196:199], v[164:167], v[110:113]
	v_mfma_f32_16x16x32_bf16 v[102:105], v[204:207], v[164:167], v[102:105]
	v_mfma_f32_16x16x32_bf16 v[94:97], v[196:199], v[172:175], v[94:97]
	v_mfma_f32_16x16x32_bf16 v[86:89], v[204:207], v[172:175], v[86:89]
	v_mfma_f32_16x16x32_bf16 v[78:81], v[196:199], v[180:183], v[78:81]
	v_mfma_f32_16x16x32_bf16 v[74:77], v[204:207], v[180:183], v[74:77]
	v_mfma_f32_16x16x32_bf16 v[70:73], v[196:199], v[188:191], v[70:73]
	v_mfma_f32_16x16x32_bf16 v[66:69], v[204:207], v[188:191], v[66:69]
	s_barrier
	s_add_i32 s38, s50, s63
	s_add_u32 s100, s54, s36
	s_addc_u32 s101, s55, s37
	s_mov_b32 m0, s38
	s_nop 0
	global_load_lds_dwordx4 v0, s[100:101]
	s_add_i32 m0, s38, 0x2000
	s_nop 0
	global_load_lds_dwordx4 v130, s[100:101]
	s_mov_b32 m0, s66
	s_add_u32 s100, s56, s36
	s_addc_u32 s101, s57, s37
	global_load_lds_dwordx4 v0, s[100:101]
	s_mov_b32 m0, s67
	s_nop 0
	global_load_lds_dwordx4 v130, s[100:101]
	ds_read_b128 v[160:163], v139 offset:49152
	ds_read_b128 v[164:167], v139 offset:50176
	ds_read_b128 v[168:171], v139 offset:51200
	ds_read_b128 v[172:175], v139 offset:52224
	ds_read_b128 v[176:179], v139 offset:53248
	ds_read_b128 v[180:183], v139 offset:54272
	ds_read_b128 v[184:187], v139 offset:55296
	ds_read_b128 v[188:191], v139 offset:56320
	s_waitcnt vmcnt(4)
	s_waitcnt lgkmcnt(0)
	s_barrier
; #define PG8_STAGE(bufoff, gbase, voff) do { _Pragma("unroll") for (int _i = 0; _i < 2; ++_i) \
;         __builtin_amdgcn_global_load_lds((const unsigned*)((const char*)(gbase) + (voff)[_i]), (LAS unsigned*)(lds + (bufoff) + ldsw + _i * 8192), 16, 0, 0); } while (0)
; #define PG8_MMA(ai, bj, At, Bt) do { __builtin_amdgcn_s_setprio(1); _Pragma("unroll") for (int m = 0; m < 4; ++m) _Pragma("unroll") for (int n = 0; n < 2; ++n) _Pragma("unroll") for (int k = 0; k < 2; ++k) \
;         acc[ai][bj][m][n] = __builtin_amdgcn_mfma_f32_16x16x32_bf16(Bt[n][k], At[m][k], acc[ai][bj][m][n], 0, 0, 0); __builtin_amdgcn_s_setprio(0); } while (0)
; #define PG8_WAIT_V(n) asm volatile("s_waitcnt vmcnt(" #n ")" ::: "memory")
; #define PG8_WAIT_L(n) asm volatile("s_waitcnt lgkmcnt(" #n ")" ::: "memory")
; #define PG8_BAR __builtin_amdgcn_s_barrier()
; #define PG8_SCHED __builtin_amdgcn_sched_barrier(0)
;     __device__ __forceinline__ void operator()(const f32x4 (&acc)[2][2][4][2], const Unit& u, int wr, int wc, int fr, int fq) const {
;         const int row0 = u.pm * BM + wr * 64 + fr, col0 = u.pn * BM + wc * 32 + 4 * fq;
;         float* base = part + (size_t)u.ks * Mp * ldc;
; #pragma unroll
;         for (int ai = 0; ai < 2; ++ai)
; #pragma unroll
;             for (int m = 0; m < 4; ++m) { float* rowp = base + (size_t)(row0 + ai * HALF + m * 16) * ldc + col0;
; #pragma unroll
;                 for (int bj = 0; bj < 2; ++bj)
; #pragma unroll
;                     for (int n = 0; n < 2; ++n) *(f32x4*)(rowp + bj * HALF + n * 16) = acc[ai][bj][m][n]; }
;     }
; template <class Epi, class Sched>
; __device__ __forceinline__ void gemm_phase(LAS unsigned char* lds, const Gemm g, const Sched& S, const Epi& E) {
;     ...
;             PG8_BAR; PG8_WAIT_L(0); PG8_MMA(1, 0, At, B0); PG8_BAR; PG8_SCHED;
;             PG8_STAGE(PG8_SB(1, 1), b3 + hstep, voffB);
;             PG8_WAIT_V(6); PG8_BAR; PG8_MMA(1, 1, At, B1); PG8_BAR;
	v_mfma_f32_16x16x32_bf16 v[62:65], v[140:143], v[160:163], v[62:65]
	v_mfma_f32_16x16x32_bf16 v[58:61], v[148:151], v[160:163], v[58:61]
	v_mfma_f32_16x16x32_bf16 v[54:57], v[140:143], v[168:171], v[54:57]
	v_mfma_f32_16x16x32_bf16 v[50:53], v[148:151], v[168:171], v[50:53]
	v_mfma_f32_16x16x32_bf16 v[38:41], v[140:143], v[176:179], v[38:41]
	v_mfma_f32_16x16x32_bf16 v[34:37], v[148:151], v[176:179], v[34:37]
	v_mfma_f32_16x16x32_bf16 v[22:25], v[140:143], v[184:187], v[22:25]
	v_mfma_f32_16x16x32_bf16 v[18:21], v[148:151], v[184:187], v[18:21]
	v_mfma_f32_16x16x32_bf16 v[62:65], v[144:147], v[164:167], v[62:65]
	v_mfma_f32_16x16x32_bf16 v[58:61], v[152:155], v[164:167], v[58:61]
	v_mfma_f32_16x16x32_bf16 v[54:57], v[144:147], v[172:175], v[54:57]
	v_mfma_f32_16x16x32_bf16 v[50:53], v[152:155], v[172:175], v[50:53]
	v_mfma_f32_16x16x32_bf16 v[38:41], v[144:147], v[180:183], v[38:41]
	v_mfma_f32_16x16x32_bf16 v[34:37], v[152:155], v[180:183], v[34:37]
	v_mfma_f32_16x16x32_bf16 v[22:25], v[144:147], v[188:191], v[22:25]
	v_mfma_f32_16x16x32_bf16 v[18:21], v[152:155], v[188:191], v[18:21]
	s_add_u32 s38, s54, 0x200080
	s_addc_u32 s39, s55, 0
	s_add_i32 s50, s51, s63
	s_mov_b32 m0, s50
	s_nop 0
	global_load_lds_dwordx4 v0, s[38:39]
	s_add_i32 m0, s50, 0x2000
	s_nop 0
	global_load_lds_dwordx4 v130, s[38:39]
	v_mfma_f32_16x16x32_bf16 v[46:49], v[192:195], v[160:163], v[46:49]
	v_mfma_f32_16x16x32_bf16 v[42:45], v[200:203], v[160:163], v[42:45]
	v_mfma_f32_16x16x32_bf16 v[30:33], v[192:195], v[168:171], v[30:33]
	v_mfma_f32_16x16x32_bf16 v[26:29], v[200:203], v[168:171], v[26:29]
	v_mfma_f32_16x16x32_bf16 v[14:17], v[192:195], v[176:179], v[14:17]
	v_mfma_f32_16x16x32_bf16 v[10:13], v[200:203], v[176:179], v[10:13]
	v_mfma_f32_16x16x32_bf16 v[6:9], v[192:195], v[184:187], v[6:9]
	v_mfma_f32_16x16x32_bf16 v[2:5], v[200:203], v[184:187], v[2:5]
	v_mfma_f32_16x16x32_bf16 v[46:49], v[196:199], v[164:167], v[46:49]
	v_mfma_f32_16x16x32_bf16 v[42:45], v[204:207], v[164:167], v[42:45]
	v_mfma_f32_16x16x32_bf16 v[30:33], v[196:199], v[172:175], v[30:33]
	v_mfma_f32_16x16x32_bf16 v[26:29], v[204:207], v[172:175], v[26:29]
	v_mfma_f32_16x16x32_bf16 v[14:17], v[196:199], v[180:183], v[14:17]
	v_mfma_f32_16x16x32_bf16 v[10:13], v[204:207], v[180:183], v[10:13]
	v_mfma_f32_16x16x32_bf16 v[6:9], v[196:199], v[188:191], v[6:9]
	v_mfma_f32_16x16x32_bf16 v[2:5], v[204:207], v[188:191], v[2:5]
	s_add_i32 s71, s71, 2
	s_add_u32 s69, s69, 0x100
	s_addc_u32 s70, s70, 0
	s_cmp_gt_u32 s71, 29
	s_mov_b64 s[50:51], s[52:53]
	s_barrier
	s_cbranch_scc0 .LBB0_58
	s_ashr_i32 s11, s10, 31
	s_lshl_b64 s[10:11], s[10:11], 24
	v_lshl_or_b32 v140, s26, 8, v138
	s_add_u32 s10, s8, s10
	v_lshl_add_u32 v142, s24, 8, v136
	s_addc_u32 s11, s9, s11
	v_ashrrev_i32_e32 v141, 31, v140
	v_ashrrev_i32_e32 v143, 31, v142
	v_lshl_add_u64 v[140:141], v[140:141], 2, s[10:11]
	v_lshlrev_b64 v[144:145], 13, v[142:143]
	v_lshl_add_u64 v[144:145], v[140:141], 0, v[144:145]
	global_store_dwordx4 v[144:145], v[126:129], off
	global_store_dwordx4 v[144:145], v[122:125], off offset:64
	global_store_dwordx4 v[144:145], v[110:113], off offset:512
	global_store_dwordx4 v[144:145], v[102:105], off offset:576
	s_mov_b64 s[10:11], 0x100000
	s_mov_b32 s26, s40
	v_or_b32_e32 v102, 16, v142
	v_ashrrev_i32_e32 v103, 31, v102
	v_lshlrev_b64 v[102:103], 13, v[102:103]
	v_lshl_add_u64 v[102:103], v[140:141], 0, v[102:103]
	global_store_dwordx4 v[102:103], v[118:121], off
	global_store_dwordx4 v[102:103], v[114:117], off offset:64
	global_store_dwordx4 v[102:103], v[94:97], off offset:512
	global_store_dwordx4 v[102:103], v[86:89], off offset:576
	s_mov_b32 s24, s42
	s_mov_b64 s[52:53], s[48:49]
	v_or_b32_e32 v86, 32, v142
	v_ashrrev_i32_e32 v87, 31, v86
	v_lshlrev_b64 v[86:87], 13, v[86:87]
	v_lshl_add_u64 v[86:87], v[140:141], 0, v[86:87]
	global_store_dwordx4 v[86:87], v[106:109], off
	global_store_dwordx4 v[86:87], v[98:101], off offset:64
	global_store_dwordx4 v[86:87], v[78:81], off offset:512
	global_store_dwordx4 v[86:87], v[74:77], off offset:576
	s_mov_b64 s[50:51], s[46:47]
	s_nop 0
	v_or_b32_e32 v74, 48, v142
	v_ashrrev_i32_e32 v75, 31, v74
	v_lshlrev_b64 v[74:75], 13, v[74:75]
	v_lshl_add_u64 v[74:75], v[140:141], 0, v[74:75]
	global_store_dwordx4 v[74:75], v[90:93], off
	global_store_dwordx4 v[74:75], v[82:85], off offset:64
	global_store_dwordx4 v[74:75], v[70:73], off offset:512
	global_store_dwordx4 v[74:75], v[66:69], off offset:576
	s_nop 1
	v_add_co_u32_e32 v68, vcc, s93, v144
	v_lshl_add_u64 v[66:67], v[144:145], 0, s[10:11]
	s_nop 0
	v_addc_co_u32_e32 v69, vcc, 0, v145, vcc
	s_mov_b64 s[10:11], 0x120000
	global_store_dwordx4 v[68:69], v[62:65], off
	global_store_dwordx4 v[66:67], v[58:61], off offset:64
	global_store_dwordx4 v[66:67], v[46:49], off offset:512
	global_store_dwordx4 v[66:67], v[42:45], off offset:576
	s_nop 1
	v_lshl_add_u64 v[42:43], v[144:145], 0, s[10:11]
	s_mov_b32 s10, 0x120000
	v_add_co_u32_e32 v44, vcc, s10, v144
	s_mov_b64 s[10:11], 0x140000
	s_nop 0
	v_addc_co_u32_e32 v45, vcc, 0, v145, vcc
	global_store_dwordx4 v[44:45], v[54:57], off
	global_store_dwordx4 v[42:43], v[50:53], off offset:64
	global_store_dwordx4 v[42:43], v[30:33], off offset:512
	global_store_dwordx4 v[42:43], v[26:29], off offset:576
	s_nop 1
	v_lshl_add_u64 v[26:27], v[144:145], 0, s[10:11]
	s_mov_b32 s10, 0x140000
	v_add_co_u32_e32 v28, vcc, s10, v144
	s_mov_b64 s[10:11], 0x160000
	s_nop 0
	v_addc_co_u32_e32 v29, vcc, 0, v145, vcc
	global_store_dwordx4 v[28:29], v[38:41], off
	global_store_dwordx4 v[26:27], v[34:37], off offset:64
	global_store_dwordx4 v[26:27], v[14:17], off offset:512
	global_store_dwordx4 v[26:27], v[10:13], off offset:576
	s_nop 1
	v_add_co_u32_e32 v12, vcc, 0x160000, v144
	v_lshl_add_u64 v[10:11], v[144:145], 0, s[10:11]
	s_nop 0
	v_addc_co_u32_e32 v13, vcc, 0, v145, vcc
	s_and_b64 vcc, exec, s[44:45]
	s_mov_b32 s10, s28
	global_store_dwordx4 v[12:13], v[22:25], off
	global_store_dwordx4 v[10:11], v[18:21], off offset:64
	global_store_dwordx4 v[10:11], v[6:9], off offset:512
	global_store_dwordx4 v[10:11], v[2:5], off offset:576
	s_cbranch_vccz .LBB0_55
	s_waitcnt vmcnt(0)
	s_cmpk_gt_u32 s60, 0xff
	s_cbranch_scc1 .LBB0_62
	s_barrier

; #define PG8_STAGE(bufoff, gbase, voff) do { _Pragma("unroll") for (int _i = 0; _i < 2; ++_i) \
;         __builtin_amdgcn_global_load_lds((const unsigned*)((const char*)(gbase) + (voff)[_i]), (LAS unsigned*)(lds + (bufoff) + ldsw + _i * 8192), 16, 0, 0); } while (0)
; #define PG8_LDA(dst, b, h) do { _Pragma("unroll") for (int m = 0; m < 4; ++m) _Pragma("unroll") for (int k = 0; k < 2; ++k) dst[m][k] = *(const LAS bf16x8*)(lds + PG8_SA(b, h) + aoff + m * 2048 + k * 1024); } while (0)
; #define PG8_LDB(dst, b, h) do { _Pragma("unroll") for (int n = 0; n < 2; ++n) _Pragma("unroll") for (int k = 0; k < 2; ++k) dst[n][k] = *(const LAS bf16x8*)(lds + PG8_SB(b, h) + boff + n * 2048 + k * 1024); } while (0)
; #define PG8_MMA(ai, bj, At, Bt) do { __builtin_amdgcn_s_setprio(1); _Pragma("unroll") for (int m = 0; m < 4; ++m) _Pragma("unroll") for (int n = 0; n < 2; ++n) _Pragma("unroll") for (int k = 0; k < 2; ++k) \
;         acc[ai][bj][m][n] = __builtin_amdgcn_mfma_f32_16x16x32_bf16(Bt[n][k], At[m][k], acc[ai][bj][m][n], 0, 0, 0); __builtin_amdgcn_s_setprio(0); } while (0)
; #define PG8_WAIT_V(n) asm volatile("s_waitcnt vmcnt(" #n ")" ::: "memory")
; #define PG8_WAIT_L(n) asm volatile("s_waitcnt lgkmcnt(" #n ")" ::: "memory")
; #define PG8_BAR __builtin_amdgcn_s_barrier()
; #define PG8_SCHED __builtin_amdgcn_sched_barrier(0)
; template <class Epi, class Sched>
; __device__ __forceinline__ void gemm_phase(LAS unsigned char* lds, const Gemm g, const Sched& S, const Epi& E) {
;     ...
;             PG8_LDB(B0, 0, 0); PG8_SCHED; PG8_LDA(At, 0, 0); PG8_STAGE(PG8_SA(1, 1), a1 + hstep, voffA);
;             PG8_WAIT_L(8); PG8_BAR; PG8_WAIT_L(0); PG8_MMA(0, 0, At, B0); PG8_BAR; PG8_SCHED;
;             PG8_LDB(B1, 0, 1); PG8_STAGE(PG8_SB(0, 0), b2, voffB);
;             PG8_BAR; PG8_WAIT_L(0); PG8_MMA(0, 1, At, B1); PG8_BAR;
;             PG8_LDA(At, 0, 1); PG8_STAGE(PG8_SA(0, 0), a2, voffA);
;             PG8_BAR; PG8_WAIT_L(0); PG8_MMA(1, 0, At, B0); PG8_BAR; PG8_SCHED;
;             PG8_STAGE(PG8_SB(0, 1), b2 + hstep, voffB);
;             PG8_WAIT_V(6); PG8_BAR; PG8_MMA(1, 1, At, B1); PG8_BAR;
.LBB0_73:
	s_add_u32 s38, s46, 0xfff80080
	s_addc_u32 s39, s47, -1
	s_cmp_eq_u32 s73, 28
	s_cselect_b32 s51, s29, s39
	s_cselect_b32 s50, s69, s38
	s_cselect_b32 s49, s27, s72
	s_cselect_b32 s48, s70, s71
	s_add_i32 m0, s9, 0xc000
	s_nop 0
	global_load_lds_dwordx4 v138, s[46:47]
	s_add_i32 m0, s9, 0xe000
	s_nop 0
	global_load_lds_dwordx4 v136, s[46:47]
	s_add_i32 s74, 0, 0x10000
	ds_read_b128 v[146:149], v226
	ds_read_b128 v[150:153], v226 offset:1024
	ds_read_b128 v[154:157], v226 offset:2048
	ds_read_b128 v[160:163], v226 offset:3072
	ds_read_b128 v[164:167], v145
	ds_read_b128 v[168:171], v145 offset:1024
	ds_read_b128 v[172:175], v145 offset:2048
	ds_read_b128 v[176:179], v145 offset:3072
	ds_read_b128 v[180:183], v145 offset:4096
	ds_read_b128 v[184:187], v145 offset:5120
	ds_read_b128 v[188:191], v145 offset:6144
	ds_read_b128 v[192:195], v145 offset:7168
	s_add_i32 s75, 0, 0x14000
	s_waitcnt lgkmcnt(0)
	s_barrier
	v_mfma_f32_16x16x32_bf16 v[126:129], v[146:149], v[164:167], v[126:129]
	v_mfma_f32_16x16x32_bf16 v[122:125], v[154:157], v[164:167], v[122:125]
	ds_read_b128 v[196:199], v226 offset:16384
	v_mfma_f32_16x16x32_bf16 v[110:113], v[146:149], v[172:175], v[110:113]
	v_mfma_f32_16x16x32_bf16 v[106:109], v[154:157], v[172:175], v[106:109]
	ds_read_b128 v[200:203], v226 offset:17408
	v_mfma_f32_16x16x32_bf16 v[94:97], v[146:149], v[180:183], v[94:97]
	v_mfma_f32_16x16x32_bf16 v[90:93], v[154:157], v[180:183], v[90:93]
	ds_read_b128 v[204:207], v226 offset:18432
	v_mfma_f32_16x16x32_bf16 v[78:81], v[146:149], v[188:191], v[78:81]
	v_mfma_f32_16x16x32_bf16 v[74:77], v[154:157], v[188:191], v[74:77]
	ds_read_b128 v[210:213], v226 offset:19456
	v_mfma_f32_16x16x32_bf16 v[126:129], v[150:153], v[168:171], v[126:129]
	v_mfma_f32_16x16x32_bf16 v[122:125], v[160:163], v[168:171], v[122:125]
	v_mfma_f32_16x16x32_bf16 v[110:113], v[150:153], v[176:179], v[110:113]
	v_mfma_f32_16x16x32_bf16 v[106:109], v[160:163], v[176:179], v[106:109]
	v_mfma_f32_16x16x32_bf16 v[94:97], v[150:153], v[184:187], v[94:97]
	v_mfma_f32_16x16x32_bf16 v[90:93], v[160:163], v[184:187], v[90:93]
	v_mfma_f32_16x16x32_bf16 v[78:81], v[150:153], v[192:195], v[78:81]
	v_mfma_f32_16x16x32_bf16 v[74:77], v[160:163], v[192:195], v[74:77]
	s_waitcnt lgkmcnt(0)
	v_mfma_f32_16x16x32_bf16 v[118:121], v[196:199], v[164:167], v[118:121]
	v_mfma_f32_16x16x32_bf16 v[114:117], v[204:207], v[164:167], v[114:117]
	v_mfma_f32_16x16x32_bf16 v[102:105], v[196:199], v[172:175], v[102:105]
	v_mfma_f32_16x16x32_bf16 v[98:101], v[204:207], v[172:175], v[98:101]
	v_mfma_f32_16x16x32_bf16 v[86:89], v[196:199], v[180:183], v[86:89]
	v_mfma_f32_16x16x32_bf16 v[82:85], v[204:207], v[180:183], v[82:85]
	v_mfma_f32_16x16x32_bf16 v[70:73], v[196:199], v[188:191], v[70:73]
	v_mfma_f32_16x16x32_bf16 v[66:69], v[204:207], v[188:191], v[66:69]
	v_mfma_f32_16x16x32_bf16 v[118:121], v[200:203], v[168:171], v[118:121]
	v_mfma_f32_16x16x32_bf16 v[114:117], v[210:213], v[168:171], v[114:117]
	v_mfma_f32_16x16x32_bf16 v[102:105], v[200:203], v[176:179], v[102:105]
	v_mfma_f32_16x16x32_bf16 v[98:101], v[210:213], v[176:179], v[98:101]
	v_mfma_f32_16x16x32_bf16 v[86:89], v[200:203], v[184:187], v[86:89]
	v_mfma_f32_16x16x32_bf16 v[82:85], v[210:213], v[184:187], v[82:85]
	v_mfma_f32_16x16x32_bf16 v[70:73], v[200:203], v[192:195], v[70:73]
	v_mfma_f32_16x16x32_bf16 v[66:69], v[210:213], v[192:195], v[66:69]
	s_barrier
	s_add_i32 s38, s74, s56
	s_mov_b32 m0, s38
	s_nop 0
	global_load_lds_dwordx4 v0, s[48:49]
	s_add_i32 m0, s38, 0x2000
	s_nop 0
	global_load_lds_dwordx4 v130, s[48:49]
	s_mov_b32 m0, s9
	s_nop 0
	global_load_lds_dwordx4 v134, s[50:51]
	s_mov_b32 m0, s60
	s_nop 0
	global_load_lds_dwordx4 v132, s[50:51]
	ds_read_b128 v[164:167], v145 offset:16384
	ds_read_b128 v[168:171], v145 offset:17408
	ds_read_b128 v[172:175], v145 offset:18432
	ds_read_b128 v[176:179], v145 offset:19456
	ds_read_b128 v[180:183], v145 offset:20480
	ds_read_b128 v[184:187], v145 offset:21504
	ds_read_b128 v[188:191], v145 offset:22528
	ds_read_b128 v[192:195], v145 offset:23552
	s_waitcnt vmcnt(4)
	s_waitcnt lgkmcnt(0)
	s_barrier
	v_mfma_f32_16x16x32_bf16 v[62:65], v[146:149], v[164:167], v[62:65]
	v_mfma_f32_16x16x32_bf16 v[58:61], v[154:157], v[164:167], v[58:61]
	v_mfma_f32_16x16x32_bf16 v[46:49], v[146:149], v[172:175], v[46:49]
	v_mfma_f32_16x16x32_bf16 v[42:45], v[154:157], v[172:175], v[42:45]
	v_mfma_f32_16x16x32_bf16 v[30:33], v[146:149], v[180:183], v[30:33]
	v_mfma_f32_16x16x32_bf16 v[26:29], v[154:157], v[180:183], v[26:29]
	v_mfma_f32_16x16x32_bf16 v[14:17], v[146:149], v[188:191], v[14:17]
	v_mfma_f32_16x16x32_bf16 v[10:13], v[154:157], v[188:191], v[10:13]
	v_mfma_f32_16x16x32_bf16 v[62:65], v[150:153], v[168:171], v[62:65]
	v_mfma_f32_16x16x32_bf16 v[58:61], v[160:163], v[168:171], v[58:61]
	v_mfma_f32_16x16x32_bf16 v[46:49], v[150:153], v[176:179], v[46:49]
	v_mfma_f32_16x16x32_bf16 v[42:45], v[160:163], v[176:179], v[42:45]
	v_mfma_f32_16x16x32_bf16 v[30:33], v[150:153], v[184:187], v[30:33]
	v_mfma_f32_16x16x32_bf16 v[26:29], v[160:163], v[184:187], v[26:29]
	v_mfma_f32_16x16x32_bf16 v[14:17], v[150:153], v[192:195], v[14:17]
	v_mfma_f32_16x16x32_bf16 v[10:13], v[160:163], v[192:195], v[10:13]
	v_mfma_f32_16x16x32_bf16 v[54:57], v[196:199], v[164:167], v[54:57]
	v_mfma_f32_16x16x32_bf16 v[50:53], v[204:207], v[164:167], v[50:53]
	v_mfma_f32_16x16x32_bf16 v[38:41], v[196:199], v[172:175], v[38:41]
	v_mfma_f32_16x16x32_bf16 v[34:37], v[204:207], v[172:175], v[34:37]
	v_mfma_f32_16x16x32_bf16 v[22:25], v[196:199], v[180:183], v[22:25]
	v_mfma_f32_16x16x32_bf16 v[18:21], v[204:207], v[180:183], v[18:21]
	v_mfma_f32_16x16x32_bf16 v[6:9], v[196:199], v[188:191], v[6:9]
	v_mfma_f32_16x16x32_bf16 v[2:5], v[204:207], v[188:191], v[2:5]
	v_mfma_f32_16x16x32_bf16 v[54:57], v[200:203], v[168:171], v[54:57]
	v_mfma_f32_16x16x32_bf16 v[50:53], v[210:213], v[168:171], v[50:53]
	v_mfma_f32_16x16x32_bf16 v[38:41], v[200:203], v[176:179], v[38:41]
	v_mfma_f32_16x16x32_bf16 v[34:37], v[210:213], v[176:179], v[34:37]
	v_mfma_f32_16x16x32_bf16 v[22:25], v[200:203], v[184:187], v[22:25]
	v_mfma_f32_16x16x32_bf16 v[18:21], v[210:213], v[184:187], v[18:21]
	v_mfma_f32_16x16x32_bf16 v[6:9], v[200:203], v[192:195], v[6:9]
	v_mfma_f32_16x16x32_bf16 v[2:5], v[210:213], v[192:195], v[2:5]
	s_barrier
; #define PG8_STAGE(bufoff, gbase, voff) do { _Pragma("unroll") for (int _i = 0; _i < 2; ++_i) \
;         __builtin_amdgcn_global_load_lds((const unsigned*)((const char*)(gbase) + (voff)[_i]), (LAS unsigned*)(lds + (bufoff) + ldsw + _i * 8192), 16, 0, 0); } while (0)
; #define PG8_LDA(dst, b, h) do { _Pragma("unroll") for (int m = 0; m < 4; ++m) _Pragma("unroll") for (int k = 0; k < 2; ++k) dst[m][k] = *(const LAS bf16x8*)(lds + PG8_SA(b, h) + aoff + m * 2048 + k * 1024); } while (0)
; #define PG8_LDB(dst, b, h) do { _Pragma("unroll") for (int n = 0; n < 2; ++n) _Pragma("unroll") for (int k = 0; k < 2; ++k) dst[n][k] = *(const LAS bf16x8*)(lds + PG8_SB(b, h) + boff + n * 2048 + k * 1024); } while (0)
; #define PG8_MMA(ai, bj, At, Bt) do { __builtin_amdgcn_s_setprio(1); _Pragma("unroll") for (int m = 0; m < 4; ++m) _Pragma("unroll") for (int n = 0; n < 2; ++n) _Pragma("unroll") for (int k = 0; k < 2; ++k) \
;         acc[ai][bj][m][n] = __builtin_amdgcn_mfma_f32_16x16x32_bf16(Bt[n][k], At[m][k], acc[ai][bj][m][n], 0, 0, 0); __builtin_amdgcn_s_setprio(0); } while (0)
; #define PG8_WAIT_V(n) asm volatile("s_waitcnt vmcnt(" #n ")" ::: "memory")
; #define PG8_WAIT_L(n) asm volatile("s_waitcnt lgkmcnt(" #n ")" ::: "memory")
; #define PG8_BAR __builtin_amdgcn_s_barrier()
; #define PG8_SCHED __builtin_amdgcn_sched_barrier(0)
; template <class Epi, class Sched>
; __device__ __forceinline__ void gemm_phase(LAS unsigned char* lds, const Gemm g, const Sched& S, const Epi& E) {
;     ...
;             PG8_LDB(B0, 1, 0); PG8_SCHED; PG8_LDA(At, 1, 0); PG8_STAGE(PG8_SA(0, 1), a2 + hstep, voffA);
;             PG8_WAIT_L(8); PG8_BAR; PG8_WAIT_L(0); PG8_MMA(0, 0, At, B0); PG8_BAR; PG8_SCHED;
;             PG8_LDB(B1, 1, 1); PG8_STAGE(PG8_SB(1, 0), b3, voffB);
;             PG8_BAR; PG8_WAIT_L(0); PG8_MMA(0, 1, At, B1); PG8_BAR;
;             PG8_LDA(At, 1, 1); PG8_STAGE(PG8_SA(1, 0), a3, voffA);
;             PG8_BAR; PG8_WAIT_L(0); PG8_MMA(1, 0, At, B0); PG8_BAR; PG8_SCHED;
;             PG8_STAGE(PG8_SB(1, 1), b3 + hstep, voffB);
;             PG8_WAIT_V(6); PG8_BAR; PG8_MMA(1, 1, At, B1); PG8_BAR;
	s_add_u32 s38, s48, 0x80000
	s_addc_u32 s39, s49, 0
	s_add_i32 s74, s75, s56
	s_mov_b32 m0, s74
	s_nop 0
	global_load_lds_dwordx4 v0, s[38:39]
	s_add_i32 m0, s74, 0x2000
	s_nop 0
	global_load_lds_dwordx4 v130, s[38:39]
	s_add_u32 s38, s50, 0x80000
	s_addc_u32 s39, s51, 0
	s_mov_b32 m0, s61
	s_nop 0
	global_load_lds_dwordx4 v134, s[38:39]
	s_mov_b32 m0, s62
	s_nop 0
	global_load_lds_dwordx4 v132, s[38:39]
	s_add_i32 s74, 0, 0x18000
	ds_read_b128 v[146:149], v226 offset:32768
	ds_read_b128 v[150:153], v226 offset:33792
	ds_read_b128 v[154:157], v226 offset:34816
	ds_read_b128 v[160:163], v226 offset:35840
	ds_read_b128 v[164:167], v145 offset:32768
	ds_read_b128 v[168:171], v145 offset:33792
	ds_read_b128 v[172:175], v145 offset:34816
	ds_read_b128 v[176:179], v145 offset:35840
	ds_read_b128 v[180:183], v145 offset:36864
	ds_read_b128 v[184:187], v145 offset:37888
	ds_read_b128 v[188:191], v145 offset:38912
	ds_read_b128 v[192:195], v145 offset:39936
	s_nop 0
	s_waitcnt lgkmcnt(0)
	s_barrier
	v_mfma_f32_16x16x32_bf16 v[126:129], v[146:149], v[164:167], v[126:129]
	v_mfma_f32_16x16x32_bf16 v[122:125], v[154:157], v[164:167], v[122:125]
	ds_read_b128 v[196:199], v226 offset:49152
	v_mfma_f32_16x16x32_bf16 v[110:113], v[146:149], v[172:175], v[110:113]
	v_mfma_f32_16x16x32_bf16 v[106:109], v[154:157], v[172:175], v[106:109]
	ds_read_b128 v[200:203], v226 offset:50176
	v_mfma_f32_16x16x32_bf16 v[94:97], v[146:149], v[180:183], v[94:97]
	v_mfma_f32_16x16x32_bf16 v[90:93], v[154:157], v[180:183], v[90:93]
	ds_read_b128 v[204:207], v226 offset:51200
	v_mfma_f32_16x16x32_bf16 v[78:81], v[146:149], v[188:191], v[78:81]
	v_mfma_f32_16x16x32_bf16 v[74:77], v[154:157], v[188:191], v[74:77]
	ds_read_b128 v[210:213], v226 offset:52224
	v_mfma_f32_16x16x32_bf16 v[126:129], v[150:153], v[168:171], v[126:129]
	v_mfma_f32_16x16x32_bf16 v[122:125], v[160:163], v[168:171], v[122:125]
	v_mfma_f32_16x16x32_bf16 v[110:113], v[150:153], v[176:179], v[110:113]
	v_mfma_f32_16x16x32_bf16 v[106:109], v[160:163], v[176:179], v[106:109]
	v_mfma_f32_16x16x32_bf16 v[94:97], v[150:153], v[184:187], v[94:97]
	v_mfma_f32_16x16x32_bf16 v[90:93], v[160:163], v[184:187], v[90:93]
	v_mfma_f32_16x16x32_bf16 v[78:81], v[150:153], v[192:195], v[78:81]
	v_mfma_f32_16x16x32_bf16 v[74:77], v[160:163], v[192:195], v[74:77]
	s_waitcnt lgkmcnt(0)
	v_mfma_f32_16x16x32_bf16 v[118:121], v[196:199], v[164:167], v[118:121]
	v_mfma_f32_16x16x32_bf16 v[114:117], v[204:207], v[164:167], v[114:117]
	v_mfma_f32_16x16x32_bf16 v[102:105], v[196:199], v[172:175], v[102:105]
	v_mfma_f32_16x16x32_bf16 v[98:101], v[204:207], v[172:175], v[98:101]
	v_mfma_f32_16x16x32_bf16 v[86:89], v[196:199], v[180:183], v[86:89]
	v_mfma_f32_16x16x32_bf16 v[82:85], v[204:207], v[180:183], v[82:85]
	v_mfma_f32_16x16x32_bf16 v[70:73], v[196:199], v[188:191], v[70:73]
	v_mfma_f32_16x16x32_bf16 v[66:69], v[204:207], v[188:191], v[66:69]
	v_mfma_f32_16x16x32_bf16 v[118:121], v[200:203], v[168:171], v[118:121]
	v_mfma_f32_16x16x32_bf16 v[114:117], v[210:213], v[168:171], v[114:117]
	v_mfma_f32_16x16x32_bf16 v[102:105], v[200:203], v[176:179], v[102:105]
	v_mfma_f32_16x16x32_bf16 v[98:101], v[210:213], v[176:179], v[98:101]
	v_mfma_f32_16x16x32_bf16 v[86:89], v[200:203], v[184:187], v[86:89]
	v_mfma_f32_16x16x32_bf16 v[82:85], v[210:213], v[184:187], v[82:85]
	v_mfma_f32_16x16x32_bf16 v[70:73], v[200:203], v[192:195], v[70:73]
	v_mfma_f32_16x16x32_bf16 v[66:69], v[210:213], v[192:195], v[66:69]
	s_barrier
	s_add_i32 s38, s74, s56
	s_add_u32 s100, s48, s36
	s_addc_u32 s101, s49, s37
	s_mov_b32 m0, s38
	s_nop 0
	global_load_lds_dwordx4 v0, s[100:101]
	s_add_i32 m0, s38, 0x2000
	s_nop 0
	global_load_lds_dwordx4 v130, s[100:101]
	s_mov_b32 m0, s64
	s_add_u32 s100, s50, s36
	s_addc_u32 s101, s51, s37
	global_load_lds_dwordx4 v134, s[100:101]
	s_mov_b32 m0, s65
	s_nop 0
	global_load_lds_dwordx4 v132, s[100:101]
	ds_read_b128 v[164:167], v145 offset:49152
	ds_read_b128 v[168:171], v145 offset:50176
	ds_read_b128 v[172:175], v145 offset:51200
	ds_read_b128 v[176:179], v145 offset:52224
	ds_read_b128 v[180:183], v145 offset:53248
	ds_read_b128 v[184:187], v145 offset:54272
	ds_read_b128 v[188:191], v145 offset:55296
	ds_read_b128 v[192:195], v145 offset:56320
	s_waitcnt vmcnt(4)
	s_waitcnt lgkmcnt(0)
	s_barrier
	v_mfma_f32_16x16x32_bf16 v[62:65], v[146:149], v[164:167], v[62:65]
	v_mfma_f32_16x16x32_bf16 v[58:61], v[154:157], v[164:167], v[58:61]
	v_mfma_f32_16x16x32_bf16 v[46:49], v[146:149], v[172:175], v[46:49]
	v_mfma_f32_16x16x32_bf16 v[42:45], v[154:157], v[172:175], v[42:45]
	v_mfma_f32_16x16x32_bf16 v[30:33], v[146:149], v[180:183], v[30:33]
	v_mfma_f32_16x16x32_bf16 v[26:29], v[154:157], v[180:183], v[26:29]
	v_mfma_f32_16x16x32_bf16 v[14:17], v[146:149], v[188:191], v[14:17]
	v_mfma_f32_16x16x32_bf16 v[10:13], v[154:157], v[188:191], v[10:13]
	v_mfma_f32_16x16x32_bf16 v[62:65], v[150:153], v[168:171], v[62:65]
	v_mfma_f32_16x16x32_bf16 v[58:61], v[160:163], v[168:171], v[58:61]
	v_mfma_f32_16x16x32_bf16 v[46:49], v[150:153], v[176:179], v[46:49]
	v_mfma_f32_16x16x32_bf16 v[42:45], v[160:163], v[176:179], v[42:45]
	v_mfma_f32_16x16x32_bf16 v[30:33], v[150:153], v[184:187], v[30:33]
	v_mfma_f32_16x16x32_bf16 v[26:29], v[160:163], v[184:187], v[26:29]
	v_mfma_f32_16x16x32_bf16 v[14:17], v[150:153], v[192:195], v[14:17]
	v_mfma_f32_16x16x32_bf16 v[10:13], v[160:163], v[192:195], v[10:13]
	s_add_u32 s38, s48, 0x80080
	s_addc_u32 s39, s49, 0
	s_add_i32 s48, s56, 0x1c000
	s_mov_b32 m0, s48
	s_nop 0
	global_load_lds_dwordx4 v0, s[38:39]
	s_add_i32 m0, s48, 0x2000
	s_nop 0
	global_load_lds_dwordx4 v130, s[38:39]
	v_mfma_f32_16x16x32_bf16 v[54:57], v[196:199], v[164:167], v[54:57]
	v_mfma_f32_16x16x32_bf16 v[50:53], v[204:207], v[164:167], v[50:53]
	v_mfma_f32_16x16x32_bf16 v[38:41], v[196:199], v[172:175], v[38:41]
	v_mfma_f32_16x16x32_bf16 v[34:37], v[204:207], v[172:175], v[34:37]
	v_mfma_f32_16x16x32_bf16 v[22:25], v[196:199], v[180:183], v[22:25]
	v_mfma_f32_16x16x32_bf16 v[18:21], v[204:207], v[180:183], v[18:21]
	v_mfma_f32_16x16x32_bf16 v[6:9], v[196:199], v[188:191], v[6:9]
	v_mfma_f32_16x16x32_bf16 v[2:5], v[204:207], v[188:191], v[2:5]
	v_mfma_f32_16x16x32_bf16 v[54:57], v[200:203], v[168:171], v[54:57]
	v_mfma_f32_16x16x32_bf16 v[50:53], v[210:213], v[168:171], v[50:53]
	v_mfma_f32_16x16x32_bf16 v[38:41], v[200:203], v[176:179], v[38:41]
	v_mfma_f32_16x16x32_bf16 v[34:37], v[210:213], v[176:179], v[34:37]
	v_mfma_f32_16x16x32_bf16 v[22:25], v[200:203], v[184:187], v[22:25]
	v_mfma_f32_16x16x32_bf16 v[18:21], v[210:213], v[184:187], v[18:21]
	v_mfma_f32_16x16x32_bf16 v[6:9], v[200:203], v[192:195], v[6:9]
	v_mfma_f32_16x16x32_bf16 v[2:5], v[210:213], v[192:195], v[2:5]
	s_add_i32 s73, s73, 2
	s_add_u32 s71, s71, 0x100
	s_addc_u32 s72, s72, 0
	s_add_u32 s46, s46, 0x100
	s_addc_u32 s47, s47, 0
	s_cmp_gt_u32 s73, 29
	s_barrier
; __device__ __forceinline__ unsigned cvt_pk_bf16(float lo, float hi) { unsigned r; asm("v_cvt_pk_bf16_f32 %0, %1, %2" : "=v"(r) : "v"(lo), "v"(hi)); return r; }
;     __device__ __forceinline__ void operator()(const f32x4 (&acc)[2][2][4][2], const Unit& u, int wr, int wc, int fr, int fq) const {
;         const int row0 = u.pm * BM + wr * 64 + fr, col0 = u.pn * BM + wc * 32 + 8 * fq;
; #pragma unroll
;         for (int ai = 0; ai < 2; ++ai)
; #pragma unroll
;             for (int m = 0; m < 4; ++m) { bf16_t* rowp = O + (size_t)(row0 + ai * HALF + m * 16) * ldc + col0;
; #pragma unroll
;                 for (int bj = 0; bj < 2; ++bj) { f32x4 v0 = acc[ai][bj][m][0], v1 = acc[ai][bj][m][1];
;                     if (ACT == 1) {
; #pragma unroll
;                         for (int j = 0; j < 4; ++j) { float a = fmaxf(v0[j], 0.f), b = fmaxf(v1[j], 0.f); v0[j] = a * a; v1[j] = b * b; } }
;                     u32x4 w; w.x = cvt_pk_bf16(v0[0], v0[1]); w.y = cvt_pk_bf16(v0[2], v0[3]); w.z = cvt_pk_bf16(v1[0], v1[1]); w.w = cvt_pk_bf16(v1[2], v1[3]);
;                     if (ACT == 1) __builtin_nontemporal_store(w, (u32x4*)(rowp + bj * HALF));
;                     else *(u32x4*)(rowp + bj * HALF) = w; } }
	s_cbranch_scc0 .LBB0_73
	v_lshl_add_u32 v146, s8, 8, v142
	v_max_f32_e32 v122, v122, v122
	v_ashrrev_i32_e32 v147, 31, v146
	v_max_f32_e32 v122, 0, v122
	v_max_f32_e32 v123, v123, v123
	v_max_f32_e32 v124, v124, v124
	v_lshl_or_b32 v140, s68, 8, v144
	v_lshlrev_b64 v[148:149], 14, v[146:147]
	v_mul_f32_e32 v147, v122, v122
	v_max_f32_e32 v122, v127, v127
	v_max_f32_e32 v123, 0, v123
	v_max_f32_e32 v124, 0, v124
	v_ashrrev_i32_e32 v141, 31, v140
	v_max_f32_e32 v126, v126, v126
	v_max_f32_e32 v122, 0, v122
	v_mul_f32_e32 v127, v123, v123
	v_max_f32_e32 v123, v128, v128
	v_mul_f32_e32 v128, v124, v124
	v_max_f32_e32 v124, v129, v129
	v_max_f32_e32 v125, v125, v125
	v_lshl_add_u64 v[148:149], s[24:25], 0, v[148:149]
	v_lshlrev_b64 v[150:151], 1, v[140:141]
	v_max_f32_e32 v126, 0, v126
	v_mul_f32_e32 v122, v122, v122
	v_max_f32_e32 v123, 0, v123
	v_max_f32_e32 v124, 0, v124
	v_max_f32_e32 v125, 0, v125
	v_max_f32_e32 v114, v114, v114
	v_lshl_add_u64 v[140:141], v[148:149], 0, v[150:151]
	v_mul_f32_e32 v126, v126, v126
	v_mul_f32_e32 v123, v123, v123
	v_mul_f32_e32 v124, v124, v124
	v_mul_f32_e32 v125, v125, v125
	v_cvt_pk_bf16_f32 v122, v126, v122
	v_max_f32_e32 v114, 0, v114
	v_max_f32_e32 v115, v115, v115
	v_max_f32_e32 v116, v116, v116
	v_cvt_pk_bf16_f32 v123, v123, v124
	v_cvt_pk_bf16_f32 v124, v147, v127
	v_cvt_pk_bf16_f32 v125, v128, v125
	global_store_dwordx4 v[140:141], v[122:125], off nt
	v_max_f32_e32 v115, 0, v115
	v_max_f32_e32 v116, 0, v116
	v_mul_f32_e32 v122, v114, v114
	v_max_f32_e32 v114, v119, v119
	v_max_f32_e32 v118, v118, v118
	v_max_f32_e32 v114, 0, v114
	v_mul_f32_e32 v119, v115, v115
	v_max_f32_e32 v115, v120, v120
	v_mul_f32_e32 v120, v116, v116
	v_max_f32_e32 v116, v121, v121
	v_max_f32_e32 v117, v117, v117
	v_max_f32_e32 v118, 0, v118
	v_mul_f32_e32 v114, v114, v114
	v_max_f32_e32 v115, 0, v115
	v_max_f32_e32 v116, 0, v116
	v_max_f32_e32 v117, 0, v117
	v_mul_f32_e32 v118, v118, v118
	v_mul_f32_e32 v115, v115, v115
	v_mul_f32_e32 v116, v116, v116
	v_mul_f32_e32 v117, v117, v117
	v_cvt_pk_bf16_f32 v114, v118, v114
	v_max_f32_e32 v106, v106, v106
	v_cvt_pk_bf16_f32 v115, v115, v116
	v_cvt_pk_bf16_f32 v116, v122, v119
	v_cvt_pk_bf16_f32 v117, v120, v117
	global_store_dwordx4 v[140:141], v[114:117], off offset:256 nt
	v_max_f32_e32 v106, 0, v106
	v_max_f32_e32 v107, v107, v107
	v_or_b32_e32 v114, 16, v146
	v_max_f32_e32 v108, v108, v108
	v_ashrrev_i32_e32 v115, 31, v114
	v_mul_f32_e32 v116, v106, v106
	v_max_f32_e32 v106, v111, v111
	v_max_f32_e32 v107, 0, v107
	v_max_f32_e32 v108, 0, v108
	v_lshlrev_b64 v[114:115], 14, v[114:115]
	v_max_f32_e32 v110, v110, v110
	v_max_f32_e32 v106, 0, v106
	v_mul_f32_e32 v111, v107, v107
	v_max_f32_e32 v107, v112, v112
	v_mul_f32_e32 v112, v108, v108
	v_max_f32_e32 v108, v113, v113
	v_max_f32_e32 v109, v109, v109
	v_lshl_add_u64 v[114:115], s[24:25], 0, v[114:115]
	v_max_f32_e32 v110, 0, v110
	v_mul_f32_e32 v106, v106, v106
	v_max_f32_e32 v107, 0, v107
	v_max_f32_e32 v108, 0, v108
	v_max_f32_e32 v109, 0, v109
	v_max_f32_e32 v98, v98, v98
	v_lshl_add_u64 v[114:115], v[114:115], 0, v[150:151]
	v_mul_f32_e32 v110, v110, v110
	v_mul_f32_e32 v107, v107, v107
	v_mul_f32_e32 v108, v108, v108
	v_mul_f32_e32 v109, v109, v109
	v_cvt_pk_bf16_f32 v106, v110, v106
	v_max_f32_e32 v98, 0, v98
	v_max_f32_e32 v99, v99, v99
	v_max_f32_e32 v100, v100, v100
	v_cvt_pk_bf16_f32 v107, v107, v108
	v_cvt_pk_bf16_f32 v108, v116, v111
	v_cvt_pk_bf16_f32 v109, v112, v109
	global_store_dwordx4 v[114:115], v[106:109], off nt
	v_max_f32_e32 v99, 0, v99
	v_max_f32_e32 v100, 0, v100
	v_mul_f32_e32 v106, v98, v98
	v_max_f32_e32 v98, v103, v103
	v_max_f32_e32 v102, v102, v102
	v_max_f32_e32 v98, 0, v98
	v_mul_f32_e32 v103, v99, v99
	v_max_f32_e32 v99, v104, v104
	v_mul_f32_e32 v104, v100, v100
	v_max_f32_e32 v100, v105, v105
	v_max_f32_e32 v101, v101, v101
	v_max_f32_e32 v102, 0, v102
	v_mul_f32_e32 v98, v98, v98
	v_max_f32_e32 v99, 0, v99
	v_max_f32_e32 v100, 0, v100
	v_max_f32_e32 v101, 0, v101
	v_mul_f32_e32 v102, v102, v102
	v_mul_f32_e32 v99, v99, v99
	v_mul_f32_e32 v100, v100, v100
	v_mul_f32_e32 v101, v101, v101
	v_cvt_pk_bf16_f32 v98, v102, v98
	v_max_f32_e32 v90, v90, v90
	v_cvt_pk_bf16_f32 v99, v99, v100
	v_cvt_pk_bf16_f32 v100, v106, v103
	v_cvt_pk_bf16_f32 v101, v104, v101
	global_store_dwordx4 v[114:115], v[98:101], off offset:256 nt
	v_max_f32_e32 v90, 0, v90
	v_max_f32_e32 v91, v91, v91
	v_or_b32_e32 v98, 32, v146
	v_max_f32_e32 v92, v92, v92
	v_ashrrev_i32_e32 v99, 31, v98
	v_mul_f32_e32 v100, v90, v90
	v_max_f32_e32 v90, v95, v95
	v_max_f32_e32 v91, 0, v91
	v_max_f32_e32 v92, 0, v92
	v_lshlrev_b64 v[98:99], 14, v[98:99]
	v_max_f32_e32 v94, v94, v94
	v_max_f32_e32 v90, 0, v90
	v_mul_f32_e32 v95, v91, v91
	v_max_f32_e32 v91, v96, v96
	v_mul_f32_e32 v96, v92, v92
	v_max_f32_e32 v92, v97, v97
	v_max_f32_e32 v93, v93, v93
	v_lshl_add_u64 v[98:99], s[24:25], 0, v[98:99]
	v_max_f32_e32 v94, 0, v94
	v_mul_f32_e32 v90, v90, v90
	v_max_f32_e32 v91, 0, v91
	v_max_f32_e32 v92, 0, v92
	v_max_f32_e32 v93, 0, v93
	v_max_f32_e32 v82, v82, v82
	v_lshl_add_u64 v[98:99], v[98:99], 0, v[150:151]
	v_mul_f32_e32 v94, v94, v94
	v_mul_f32_e32 v91, v91, v91
	v_mul_f32_e32 v92, v92, v92
	v_mul_f32_e32 v93, v93, v93
	v_cvt_pk_bf16_f32 v90, v94, v90
	v_max_f32_e32 v82, 0, v82
	v_max_f32_e32 v83, v83, v83
	v_max_f32_e32 v84, v84, v84
	v_cvt_pk_bf16_f32 v91, v91, v92
	v_cvt_pk_bf16_f32 v92, v100, v95
	v_cvt_pk_bf16_f32 v93, v96, v93
	global_store_dwordx4 v[98:99], v[90:93], off nt
	v_max_f32_e32 v83, 0, v83
	v_max_f32_e32 v84, 0, v84
	v_mul_f32_e32 v90, v82, v82
	v_max_f32_e32 v82, v87, v87
	v_max_f32_e32 v86, v86, v86
; __device__ __forceinline__ unsigned cvt_pk_bf16(float lo, float hi) { unsigned r; asm("v_cvt_pk_bf16_f32 %0, %1, %2" : "=v"(r) : "v"(lo), "v"(hi)); return r; }
;     __device__ __forceinline__ void operator()(const f32x4 (&acc)[2][2][4][2], const Unit& u, int wr, int wc, int fr, int fq) const {
;     ...
;             for (int m = 0; m < 4; ++m) { bf16_t* rowp = O + (size_t)(row0 + ai * HALF + m * 16) * ldc + col0;
; #pragma unroll
;                 for (int bj = 0; bj < 2; ++bj) { f32x4 v0 = acc[ai][bj][m][0], v1 = acc[ai][bj][m][1];
;                     if (ACT == 1) {
; #pragma unroll
;                         for (int j = 0; j < 4; ++j) { float a = fmaxf(v0[j], 0.f), b = fmaxf(v1[j], 0.f); v0[j] = a * a; v1[j] = b * b; } }
;                     u32x4 w; w.x = cvt_pk_bf16(v0[0], v0[1]); w.y = cvt_pk_bf16(v0[2], v0[3]); w.z = cvt_pk_bf16(v1[0], v1[1]); w.w = cvt_pk_bf16(v1[2], v1[3]);
;                     if (ACT == 1) __builtin_nontemporal_store(w, (u32x4*)(rowp + bj * HALF));
;                     else *(u32x4*)(rowp + bj * HALF) = w; } }
	v_max_f32_e32 v82, 0, v82
	v_mul_f32_e32 v87, v83, v83
	v_max_f32_e32 v83, v88, v88
	v_mul_f32_e32 v88, v84, v84
	v_max_f32_e32 v84, v89, v89
	v_max_f32_e32 v85, v85, v85
	v_max_f32_e32 v86, 0, v86
	v_mul_f32_e32 v82, v82, v82
	v_max_f32_e32 v83, 0, v83
	v_max_f32_e32 v84, 0, v84
	v_max_f32_e32 v85, 0, v85
	v_mul_f32_e32 v86, v86, v86
	v_mul_f32_e32 v83, v83, v83
	v_mul_f32_e32 v84, v84, v84
	v_mul_f32_e32 v85, v85, v85
	v_cvt_pk_bf16_f32 v82, v86, v82
	v_max_f32_e32 v74, v74, v74
	v_cvt_pk_bf16_f32 v83, v83, v84
	v_cvt_pk_bf16_f32 v84, v90, v87
	v_cvt_pk_bf16_f32 v85, v88, v85
	global_store_dwordx4 v[98:99], v[82:85], off offset:256 nt
	v_max_f32_e32 v74, 0, v74
	v_max_f32_e32 v75, v75, v75
	v_or_b32_e32 v82, 48, v146
	v_max_f32_e32 v76, v76, v76
	v_ashrrev_i32_e32 v83, 31, v82
	v_mul_f32_e32 v84, v74, v74
	v_max_f32_e32 v74, v79, v79
	v_max_f32_e32 v75, 0, v75
	v_max_f32_e32 v76, 0, v76
	v_lshlrev_b64 v[82:83], 14, v[82:83]
	v_max_f32_e32 v78, v78, v78
	v_max_f32_e32 v74, 0, v74
	v_mul_f32_e32 v79, v75, v75
	v_max_f32_e32 v75, v80, v80
	v_mul_f32_e32 v80, v76, v76
	v_max_f32_e32 v76, v81, v81
	v_max_f32_e32 v77, v77, v77
	v_lshl_add_u64 v[82:83], s[24:25], 0, v[82:83]
	v_max_f32_e32 v78, 0, v78
	v_mul_f32_e32 v74, v74, v74
	v_max_f32_e32 v75, 0, v75
	v_max_f32_e32 v76, 0, v76
	v_max_f32_e32 v77, 0, v77
	v_max_f32_e32 v66, v66, v66
	v_max_f32_e32 v67, v67, v67
	v_max_f32_e32 v68, v68, v68
	v_lshl_add_u64 v[82:83], v[82:83], 0, v[150:151]
	v_mul_f32_e32 v78, v78, v78
	v_mul_f32_e32 v75, v75, v75
	v_mul_f32_e32 v76, v76, v76
	v_mul_f32_e32 v77, v77, v77
	v_cvt_pk_bf16_f32 v74, v78, v74
	v_max_f32_e32 v66, 0, v66
	v_max_f32_e32 v67, 0, v67
	v_max_f32_e32 v68, 0, v68
	v_cvt_pk_bf16_f32 v75, v75, v76
	v_cvt_pk_bf16_f32 v76, v84, v79
	v_cvt_pk_bf16_f32 v77, v80, v77
	global_store_dwordx4 v[82:83], v[74:77], off nt
	v_max_f32_e32 v69, v69, v69
	v_max_f32_e32 v70, v70, v70
	v_mul_f32_e32 v74, v66, v66
	v_max_f32_e32 v66, v71, v71
	v_mul_f32_e32 v71, v67, v67
	v_max_f32_e32 v67, v72, v72
	v_mul_f32_e32 v72, v68, v68
	v_max_f32_e32 v68, v73, v73
	v_max_f32_e32 v67, 0, v67
	v_max_f32_e32 v68, 0, v68
	v_max_f32_e32 v66, 0, v66
	v_mul_f32_e32 v67, v67, v67
	v_max_f32_e32 v69, 0, v69
	v_mul_f32_e32 v68, v68, v68
	v_max_f32_e32 v58, v58, v58
	v_max_f32_e32 v70, 0, v70
	v_mul_f32_e32 v66, v66, v66
	v_mul_f32_e32 v69, v69, v69
	v_cvt_pk_bf16_f32 v67, v67, v68
	v_cvt_pk_bf16_f32 v68, v74, v71
	v_max_f32_e32 v58, 0, v58
	v_max_f32_e32 v59, v59, v59
	v_max_f32_e32 v60, v60, v60
	v_mul_f32_e32 v70, v70, v70
	v_cvt_pk_bf16_f32 v66, v70, v66
	v_cvt_pk_bf16_f32 v69, v72, v69
	global_store_dwordx4 v[82:83], v[66:69], off offset:256 nt
	v_max_f32_e32 v62, v62, v62
	v_max_f32_e32 v59, 0, v59
	v_mul_f32_e32 v68, v58, v58
	v_max_f32_e32 v58, v63, v63
	v_max_f32_e32 v60, 0, v60
	v_max_f32_e32 v62, 0, v62
	v_max_f32_e32 v58, 0, v58
	v_mul_f32_e32 v63, v59, v59
	v_max_f32_e32 v59, v64, v64
	v_mul_f32_e32 v64, v60, v60
	v_max_f32_e32 v60, v65, v65
	v_mul_f32_e32 v62, v62, v62
	v_mul_f32_e32 v58, v58, v58
	v_max_f32_e32 v59, 0, v59
	v_max_f32_e32 v60, 0, v60
	v_max_f32_e32 v61, v61, v61
	s_mov_b32 s8, 0x200000
	v_mul_f32_e32 v59, v59, v59
	v_max_f32_e32 v61, 0, v61
	v_mul_f32_e32 v60, v60, v60
	v_cvt_pk_bf16_f32 v58, v62, v58
	v_add_co_u32_e32 v62, vcc, s8, v140
	v_max_f32_e32 v50, v50, v50
	v_max_f32_e32 v51, v51, v51
	v_max_f32_e32 v52, v52, v52
	v_mul_f32_e32 v61, v61, v61
	v_cvt_pk_bf16_f32 v59, v59, v60
	v_cvt_pk_bf16_f32 v60, v68, v63
	v_addc_co_u32_e32 v63, vcc, 0, v141, vcc
	v_max_f32_e32 v50, 0, v50
	v_max_f32_e32 v51, 0, v51
	v_max_f32_e32 v52, 0, v52
	v_cvt_pk_bf16_f32 v61, v64, v61
	global_store_dwordx4 v[62:63], v[58:61], off nt
	v_max_f32_e32 v53, v53, v53
	s_mov_b64 s[38:39], 0x200000
	v_mul_f32_e32 v58, v50, v50
	v_max_f32_e32 v50, v55, v55
	v_mul_f32_e32 v55, v51, v51
	v_max_f32_e32 v51, v56, v56
	v_mul_f32_e32 v56, v52, v52
	v_max_f32_e32 v52, v57, v57
	v_max_f32_e32 v51, 0, v51
	v_max_f32_e32 v52, 0, v52
	v_max_f32_e32 v54, v54, v54
	v_max_f32_e32 v50, 0, v50
	v_mul_f32_e32 v51, v51, v51
	v_max_f32_e32 v53, 0, v53
	v_mul_f32_e32 v52, v52, v52
	v_max_f32_e32 v42, v42, v42
	v_lshl_add_u64 v[66:67], v[140:141], 0, s[38:39]
	v_max_f32_e32 v54, 0, v54
	v_mul_f32_e32 v50, v50, v50
	v_mul_f32_e32 v53, v53, v53
	v_cvt_pk_bf16_f32 v51, v51, v52
	v_cvt_pk_bf16_f32 v52, v58, v55
	v_max_f32_e32 v42, 0, v42
	v_max_f32_e32 v43, v43, v43
	v_max_f32_e32 v44, v44, v44
	v_mul_f32_e32 v54, v54, v54
	v_cvt_pk_bf16_f32 v50, v54, v50
	v_cvt_pk_bf16_f32 v53, v56, v53
	global_store_dwordx4 v[66:67], v[50:53], off offset:256 nt
	v_max_f32_e32 v46, v46, v46
	v_max_f32_e32 v43, 0, v43
	v_mul_f32_e32 v52, v42, v42
	v_max_f32_e32 v42, v47, v47
	v_max_f32_e32 v44, 0, v44
	v_max_f32_e32 v46, 0, v46
	v_max_f32_e32 v42, 0, v42
	v_mul_f32_e32 v47, v43, v43
	v_max_f32_e32 v43, v48, v48
	v_mul_f32_e32 v48, v44, v44
	v_max_f32_e32 v44, v49, v49
	v_mul_f32_e32 v46, v46, v46
	v_mul_f32_e32 v42, v42, v42
	v_max_f32_e32 v43, 0, v43
	v_max_f32_e32 v44, 0, v44
	v_max_f32_e32 v45, v45, v45
	s_mov_b32 s8, 0x240000
	v_mul_f32_e32 v43, v43, v43
	v_max_f32_e32 v45, 0, v45
	v_mul_f32_e32 v44, v44, v44
	v_cvt_pk_bf16_f32 v42, v46, v42
; __device__ __forceinline__ unsigned cvt_pk_bf16(float lo, float hi) { unsigned r; asm("v_cvt_pk_bf16_f32 %0, %1, %2" : "=v"(r) : "v"(lo), "v"(hi)); return r; }
; #define PG8_WAIT_V(n) asm volatile("s_waitcnt vmcnt(" #n ")" ::: "memory")
; #define PG8_BAR __builtin_amdgcn_s_barrier()
;     __device__ __forceinline__ void operator()(const f32x4 (&acc)[2][2][4][2], const Unit& u, int wr, int wc, int fr, int fq) const {
;     ...
;             for (int m = 0; m < 4; ++m) { bf16_t* rowp = O + (size_t)(row0 + ai * HALF + m * 16) * ldc + col0;
; #pragma unroll
;                 for (int bj = 0; bj < 2; ++bj) { f32x4 v0 = acc[ai][bj][m][0], v1 = acc[ai][bj][m][1];
;                     if (ACT == 1) {
; #pragma unroll
;                         for (int j = 0; j < 4; ++j) { float a = fmaxf(v0[j], 0.f), b = fmaxf(v1[j], 0.f); v0[j] = a * a; v1[j] = b * b; } }
;                     u32x4 w; w.x = cvt_pk_bf16(v0[0], v0[1]); w.y = cvt_pk_bf16(v0[2], v0[3]); w.z = cvt_pk_bf16(v1[0], v1[1]); w.w = cvt_pk_bf16(v1[2], v1[3]);
;                     if (ACT == 1) __builtin_nontemporal_store(w, (u32x4*)(rowp + bj * HALF));
;                     else *(u32x4*)(rowp + bj * HALF) = w; } }
; template <class Epi, class Sched>
; __device__ __forceinline__ void gemm_phase(LAS unsigned char* lds, const Gemm g, const Sched& S, const Epi& E) {
;     ...
;         E(acc, cur, wr, wc, fr, fq);
;         if (!has_next) break;
; #pragma unroll
;         for (int a = 0; a < 2; ++a)
; #pragma unroll
;             for (int b = 0; b < 2; ++b)
; #pragma unroll
;                 for (int m = 0; m < 4; ++m)
; #pragma unroll
;                     for (int n = 0; n < 2; ++n) acc[a][b][m][n] = (f32x4){0.f, 0.f, 0.f, 0.f};
;         cur = nxt; cA = nA; cB = nB; ++ui;
;     }
;     PG8_WAIT_V(0);
;     if (wr == 0) PG8_BAR;
;     PG8_BAR;
	v_add_co_u32_e32 v46, vcc, s8, v140
	v_max_f32_e32 v34, v34, v34
	v_max_f32_e32 v35, v35, v35
	v_max_f32_e32 v36, v36, v36
	v_mul_f32_e32 v45, v45, v45
	v_cvt_pk_bf16_f32 v43, v43, v44
	v_cvt_pk_bf16_f32 v44, v52, v47
	v_addc_co_u32_e32 v47, vcc, 0, v141, vcc
	v_max_f32_e32 v34, 0, v34
	v_max_f32_e32 v35, 0, v35
	v_max_f32_e32 v36, 0, v36
	v_cvt_pk_bf16_f32 v45, v48, v45
	global_store_dwordx4 v[46:47], v[42:45], off nt
	v_max_f32_e32 v37, v37, v37
	s_mov_b64 s[38:39], 0x240000
	v_mul_f32_e32 v42, v34, v34
	v_max_f32_e32 v34, v39, v39
	v_mul_f32_e32 v39, v35, v35
	v_max_f32_e32 v35, v40, v40
	v_mul_f32_e32 v40, v36, v36
	v_max_f32_e32 v36, v41, v41
	v_max_f32_e32 v35, 0, v35
	v_max_f32_e32 v36, 0, v36
	v_max_f32_e32 v38, v38, v38
	v_max_f32_e32 v34, 0, v34
	v_mul_f32_e32 v35, v35, v35
	v_max_f32_e32 v37, 0, v37
	v_mul_f32_e32 v36, v36, v36
	v_max_f32_e32 v26, v26, v26
	v_lshl_add_u64 v[50:51], v[140:141], 0, s[38:39]
	v_max_f32_e32 v38, 0, v38
	v_mul_f32_e32 v34, v34, v34
	v_mul_f32_e32 v37, v37, v37
	v_cvt_pk_bf16_f32 v35, v35, v36
	v_cvt_pk_bf16_f32 v36, v42, v39
	v_max_f32_e32 v26, 0, v26
	v_max_f32_e32 v27, v27, v27
	v_max_f32_e32 v28, v28, v28
	v_mul_f32_e32 v38, v38, v38
	v_cvt_pk_bf16_f32 v34, v38, v34
	v_cvt_pk_bf16_f32 v37, v40, v37
	global_store_dwordx4 v[50:51], v[34:37], off offset:256 nt
	v_max_f32_e32 v30, v30, v30
	v_max_f32_e32 v27, 0, v27
	v_mul_f32_e32 v36, v26, v26
	v_max_f32_e32 v26, v31, v31
	v_max_f32_e32 v28, 0, v28
	v_max_f32_e32 v30, 0, v30
	v_max_f32_e32 v26, 0, v26
	v_mul_f32_e32 v31, v27, v27
	v_max_f32_e32 v27, v32, v32
	v_mul_f32_e32 v32, v28, v28
	v_max_f32_e32 v28, v33, v33
	v_mul_f32_e32 v30, v30, v30
	v_mul_f32_e32 v26, v26, v26
	v_max_f32_e32 v27, 0, v27
	v_max_f32_e32 v28, 0, v28
	v_max_f32_e32 v29, v29, v29
	s_mov_b32 s8, 0x280000
	v_mul_f32_e32 v27, v27, v27
	v_max_f32_e32 v29, 0, v29
	v_mul_f32_e32 v28, v28, v28
	v_cvt_pk_bf16_f32 v26, v30, v26
	v_add_co_u32_e32 v30, vcc, s8, v140
	v_max_f32_e32 v18, v18, v18
	v_max_f32_e32 v19, v19, v19
	v_max_f32_e32 v20, v20, v20
	v_mul_f32_e32 v29, v29, v29
	v_cvt_pk_bf16_f32 v27, v27, v28
	v_cvt_pk_bf16_f32 v28, v36, v31
	v_addc_co_u32_e32 v31, vcc, 0, v141, vcc
	v_max_f32_e32 v18, 0, v18
	v_max_f32_e32 v19, 0, v19
	v_max_f32_e32 v20, 0, v20
	v_cvt_pk_bf16_f32 v29, v32, v29
	global_store_dwordx4 v[30:31], v[26:29], off nt
	v_max_f32_e32 v21, v21, v21
	s_mov_b64 s[38:39], 0x280000
	v_mul_f32_e32 v26, v18, v18
	v_max_f32_e32 v18, v23, v23
	v_mul_f32_e32 v23, v19, v19
	v_max_f32_e32 v19, v24, v24
	v_mul_f32_e32 v24, v20, v20
	v_max_f32_e32 v20, v25, v25
	v_max_f32_e32 v19, 0, v19
	v_max_f32_e32 v20, 0, v20
	v_max_f32_e32 v22, v22, v22
	v_max_f32_e32 v18, 0, v18
	v_mul_f32_e32 v19, v19, v19
	v_max_f32_e32 v21, 0, v21
	v_mul_f32_e32 v20, v20, v20
	v_max_f32_e32 v10, v10, v10
	v_lshl_add_u64 v[34:35], v[140:141], 0, s[38:39]
	v_max_f32_e32 v22, 0, v22
	v_mul_f32_e32 v18, v18, v18
	v_mul_f32_e32 v21, v21, v21
	v_cvt_pk_bf16_f32 v19, v19, v20
	v_cvt_pk_bf16_f32 v20, v26, v23
	v_max_f32_e32 v10, 0, v10
	v_max_f32_e32 v11, v11, v11
	v_max_f32_e32 v12, v12, v12
	v_mul_f32_e32 v22, v22, v22
	v_cvt_pk_bf16_f32 v18, v22, v18
	v_cvt_pk_bf16_f32 v21, v24, v21
	global_store_dwordx4 v[34:35], v[18:21], off offset:256 nt
	v_max_f32_e32 v14, v14, v14
	v_max_f32_e32 v11, 0, v11
	v_mul_f32_e32 v20, v10, v10
	v_max_f32_e32 v10, v15, v15
	v_max_f32_e32 v12, 0, v12
	v_max_f32_e32 v14, 0, v14
	v_max_f32_e32 v10, 0, v10
	v_mul_f32_e32 v15, v11, v11
	v_max_f32_e32 v11, v16, v16
	v_mul_f32_e32 v16, v12, v12
	v_max_f32_e32 v12, v17, v17
	v_mul_f32_e32 v14, v14, v14
	v_mul_f32_e32 v10, v10, v10
	v_max_f32_e32 v11, 0, v11
	v_max_f32_e32 v12, 0, v12
	v_max_f32_e32 v13, v13, v13
	s_mov_b32 s8, 0x2c0000
	v_mul_f32_e32 v11, v11, v11
	v_max_f32_e32 v13, 0, v13
	v_mul_f32_e32 v12, v12, v12
	v_cvt_pk_bf16_f32 v10, v14, v10
	v_add_co_u32_e32 v14, vcc, s8, v140
	v_max_f32_e32 v2, v2, v2
	v_max_f32_e32 v3, v3, v3
	v_max_f32_e32 v4, v4, v4
	v_mul_f32_e32 v13, v13, v13
	v_cvt_pk_bf16_f32 v11, v11, v12
	v_cvt_pk_bf16_f32 v12, v20, v15
	v_addc_co_u32_e32 v15, vcc, 0, v141, vcc
	v_max_f32_e32 v2, 0, v2
	v_max_f32_e32 v3, 0, v3
	v_max_f32_e32 v4, 0, v4
	v_cvt_pk_bf16_f32 v13, v16, v13
	global_store_dwordx4 v[14:15], v[10:13], off nt
	v_max_f32_e32 v5, v5, v5
	s_mov_b64 s[38:39], 0x2c0000
	v_mul_f32_e32 v10, v2, v2
	v_max_f32_e32 v2, v7, v7
	v_mul_f32_e32 v7, v3, v3
	v_max_f32_e32 v3, v8, v8
	v_mul_f32_e32 v8, v4, v4
	v_max_f32_e32 v4, v9, v9
	v_max_f32_e32 v6, v6, v6
	v_max_f32_e32 v2, 0, v2
	v_max_f32_e32 v3, 0, v3
	v_max_f32_e32 v4, 0, v4
	v_max_f32_e32 v5, 0, v5
	v_lshl_add_u64 v[18:19], v[140:141], 0, s[38:39]
	v_max_f32_e32 v6, 0, v6
	v_mul_f32_e32 v2, v2, v2
	v_mul_f32_e32 v3, v3, v3
	v_mul_f32_e32 v4, v4, v4
	v_mul_f32_e32 v5, v5, v5
	s_and_b64 vcc, exec, s[40:41]
	s_mov_b32 s68, s26
	s_mov_b32 s8, s28
	s_mov_b64 s[46:47], s[44:45]
	s_mov_b64 s[48:49], s[42:43]
	v_mul_f32_e32 v6, v6, v6
	v_cvt_pk_bf16_f32 v2, v6, v2
	v_cvt_pk_bf16_f32 v3, v3, v4
	v_cvt_pk_bf16_f32 v4, v10, v7
	v_cvt_pk_bf16_f32 v5, v8, v5
	global_store_dwordx4 v[18:19], v[2:5], off offset:256 nt
	s_cbranch_vccz .LBB0_70
	s_waitcnt vmcnt(0)
	s_cmpk_gt_u32 s52, 0xff
	s_cbranch_scc1 .LBB0_77
	s_barrier

; #define PG8_STAGE(bufoff, gbase, voff) do { _Pragma("unroll") for (int _i = 0; _i < 2; ++_i) \
;         __builtin_amdgcn_global_load_lds((const unsigned*)((const char*)(gbase) + (voff)[_i]), (LAS unsigned*)(lds + (bufoff) + ldsw + _i * 8192), 16, 0, 0); } while (0)
; #define PG8_LDA(dst, b, h) do { _Pragma("unroll") for (int m = 0; m < 4; ++m) _Pragma("unroll") for (int k = 0; k < 2; ++k) dst[m][k] = *(const LAS bf16x8*)(lds + PG8_SA(b, h) + aoff + m * 2048 + k * 1024); } while (0)
; #define PG8_LDB(dst, b, h) do { _Pragma("unroll") for (int n = 0; n < 2; ++n) _Pragma("unroll") for (int k = 0; k < 2; ++k) dst[n][k] = *(const LAS bf16x8*)(lds + PG8_SB(b, h) + boff + n * 2048 + k * 1024); } while (0)
; #define PG8_MMA(ai, bj, At, Bt) do { __builtin_amdgcn_s_setprio(1); _Pragma("unroll") for (int m = 0; m < 4; ++m) _Pragma("unroll") for (int n = 0; n < 2; ++n) _Pragma("unroll") for (int k = 0; k < 2; ++k) \
;         acc[ai][bj][m][n] = __builtin_amdgcn_mfma_f32_16x16x32_bf16(Bt[n][k], At[m][k], acc[ai][bj][m][n], 0, 0, 0); __builtin_amdgcn_s_setprio(0); } while (0)
; #define PG8_WAIT_V(n) asm volatile("s_waitcnt vmcnt(" #n ")" ::: "memory")
; #define PG8_WAIT_L(n) asm volatile("s_waitcnt lgkmcnt(" #n ")" ::: "memory")
; #define PG8_BAR __builtin_amdgcn_s_barrier()
; #define PG8_SCHED __builtin_amdgcn_sched_barrier(0)
; template <class Epi, class Sched>
; __device__ __forceinline__ void gemm_phase(LAS unsigned char* lds, const Gemm g, const Sched& S, const Epi& E) {
;     ...
;             PG8_LDB(B0, 0, 0); PG8_SCHED; PG8_LDA(At, 0, 0); PG8_STAGE(PG8_SA(1, 1), a1 + hstep, voffA);
;             PG8_WAIT_L(8); PG8_BAR; PG8_WAIT_L(0); PG8_MMA(0, 0, At, B0); PG8_BAR; PG8_SCHED;
;             PG8_LDB(B1, 0, 1); PG8_STAGE(PG8_SB(0, 0), b2, voffB);
;             PG8_BAR; PG8_WAIT_L(0); PG8_MMA(0, 1, At, B1); PG8_BAR;
;             PG8_LDA(At, 0, 1); PG8_STAGE(PG8_SA(0, 0), a2, voffA);
;             PG8_BAR; PG8_WAIT_L(0); PG8_MMA(1, 0, At, B0); PG8_BAR; PG8_SCHED;
;             PG8_STAGE(PG8_SB(0, 1), b2 + hstep, voffB);
;             PG8_WAIT_V(6); PG8_BAR; PG8_MMA(1, 1, At, B1); PG8_BAR;
.LBB0_99:
	s_add_u32 s56, s28, 0x100
	s_addc_u32 s57, s29, 0
	s_cmp_eq_u32 s81, 28
	s_cselect_b32 s61, s51, s57
	s_cselect_b32 s60, s77, s56
	s_cselect_b32 s59, s49, s80
	s_cselect_b32 s58, s78, s79
	s_add_i32 m0, s9, 0xc000
	s_nop 0
	global_load_lds_dwordx4 v150, s[28:29]
	s_add_i32 m0, s9, 0xe000
	s_nop 0
	global_load_lds_dwordx4 v148, s[28:29]
	s_add_i32 s38, 0, 0x10000
	ds_read_b128 v[98:101], v226
	ds_read_b128 v[102:105], v226 offset:1024
	ds_read_b128 v[106:109], v226 offset:2048
	ds_read_b128 v[110:113], v226 offset:3072
	ds_read_b128 v[152:155], v171
	ds_read_b128 v[160:163], v171 offset:1024
	ds_read_b128 v[164:167], v171 offset:2048
	ds_read_b128 v[172:175], v171 offset:3072
	ds_read_b128 v[176:179], v171 offset:4096
	ds_read_b128 v[180:183], v171 offset:5120
	ds_read_b128 v[184:187], v171 offset:6144
	ds_read_b128 v[188:191], v171 offset:7168
	s_add_i32 s39, 0, 0x14000
	s_waitcnt lgkmcnt(0)
	s_barrier
	v_mfma_f32_16x16x32_bf16 v[142:145], v[98:101], v[152:155], v[142:145]
	v_mfma_f32_16x16x32_bf16 v[138:141], v[106:109], v[152:155], v[138:141]
	ds_read_b128 v[192:195], v226 offset:16384
	v_mfma_f32_16x16x32_bf16 v[126:129], v[98:101], v[164:167], v[126:129]
	v_mfma_f32_16x16x32_bf16 v[122:125], v[106:109], v[164:167], v[122:125]
	ds_read_b128 v[196:199], v226 offset:17408
	v_mfma_f32_16x16x32_bf16 v[94:97], v[98:101], v[176:179], v[94:97]
	v_mfma_f32_16x16x32_bf16 v[90:93], v[106:109], v[176:179], v[90:93]
	ds_read_b128 v[200:203], v226 offset:18432
	v_mfma_f32_16x16x32_bf16 v[86:89], v[98:101], v[184:187], v[86:89]
	v_mfma_f32_16x16x32_bf16 v[82:85], v[106:109], v[184:187], v[82:85]
	ds_read_b128 v[204:207], v226 offset:19456
	v_mfma_f32_16x16x32_bf16 v[142:145], v[102:105], v[160:163], v[142:145]
	v_mfma_f32_16x16x32_bf16 v[138:141], v[110:113], v[160:163], v[138:141]
	v_mfma_f32_16x16x32_bf16 v[126:129], v[102:105], v[172:175], v[126:129]
	v_mfma_f32_16x16x32_bf16 v[122:125], v[110:113], v[172:175], v[122:125]
	v_mfma_f32_16x16x32_bf16 v[94:97], v[102:105], v[180:183], v[94:97]
	v_mfma_f32_16x16x32_bf16 v[90:93], v[110:113], v[180:183], v[90:93]
	v_mfma_f32_16x16x32_bf16 v[86:89], v[102:105], v[188:191], v[86:89]
	v_mfma_f32_16x16x32_bf16 v[82:85], v[110:113], v[188:191], v[82:85]
	s_waitcnt lgkmcnt(0)
	v_mfma_f32_16x16x32_bf16 v[134:137], v[192:195], v[152:155], v[134:137]
	v_mfma_f32_16x16x32_bf16 v[130:133], v[200:203], v[152:155], v[130:133]
	v_mfma_f32_16x16x32_bf16 v[118:121], v[192:195], v[164:167], v[118:121]
	v_mfma_f32_16x16x32_bf16 v[114:117], v[200:203], v[164:167], v[114:117]
	v_mfma_f32_16x16x32_bf16 v[78:81], v[192:195], v[176:179], v[78:81]
	v_mfma_f32_16x16x32_bf16 v[74:77], v[200:203], v[176:179], v[74:77]
	v_mfma_f32_16x16x32_bf16 v[70:73], v[192:195], v[184:187], v[70:73]
	v_mfma_f32_16x16x32_bf16 v[66:69], v[200:203], v[184:187], v[66:69]
	v_mfma_f32_16x16x32_bf16 v[134:137], v[196:199], v[160:163], v[134:137]
	v_mfma_f32_16x16x32_bf16 v[130:133], v[204:207], v[160:163], v[130:133]
	v_mfma_f32_16x16x32_bf16 v[118:121], v[196:199], v[172:175], v[118:121]
	v_mfma_f32_16x16x32_bf16 v[114:117], v[204:207], v[172:175], v[114:117]
	v_mfma_f32_16x16x32_bf16 v[78:81], v[196:199], v[180:183], v[78:81]
	v_mfma_f32_16x16x32_bf16 v[74:77], v[204:207], v[180:183], v[74:77]
	v_mfma_f32_16x16x32_bf16 v[70:73], v[196:199], v[188:191], v[70:73]
	v_mfma_f32_16x16x32_bf16 v[66:69], v[204:207], v[188:191], v[66:69]
	s_barrier
	s_add_i32 s28, s38, s67
	s_mov_b32 m0, s28
	s_nop 0
	global_load_lds_dwordx4 v0, s[58:59]
	s_add_i32 m0, s28, 0x2000
	s_nop 0
	global_load_lds_dwordx4 v146, s[58:59]
	s_mov_b32 m0, s9
	s_nop 0
	global_load_lds_dwordx4 v0, s[60:61]
	s_mov_b32 m0, s68
	s_nop 0
	global_load_lds_dwordx4 v146, s[60:61]
	ds_read_b128 v[152:155], v171 offset:16384
	ds_read_b128 v[160:163], v171 offset:17408
	ds_read_b128 v[164:167], v171 offset:18432
	ds_read_b128 v[172:175], v171 offset:19456
	ds_read_b128 v[176:179], v171 offset:20480
	ds_read_b128 v[180:183], v171 offset:21504
	ds_read_b128 v[184:187], v171 offset:22528
	ds_read_b128 v[188:191], v171 offset:23552
	s_waitcnt vmcnt(4)
	s_waitcnt lgkmcnt(0)
	s_barrier
	v_mfma_f32_16x16x32_bf16 v[62:65], v[98:101], v[152:155], v[62:65]
	v_mfma_f32_16x16x32_bf16 v[58:61], v[106:109], v[152:155], v[58:61]
	v_mfma_f32_16x16x32_bf16 v[46:49], v[98:101], v[164:167], v[46:49]
	v_mfma_f32_16x16x32_bf16 v[42:45], v[106:109], v[164:167], v[42:45]
	v_mfma_f32_16x16x32_bf16 v[30:33], v[98:101], v[176:179], v[30:33]
	v_mfma_f32_16x16x32_bf16 v[26:29], v[106:109], v[176:179], v[26:29]
	v_mfma_f32_16x16x32_bf16 v[22:25], v[98:101], v[184:187], v[22:25]
	v_mfma_f32_16x16x32_bf16 v[18:21], v[106:109], v[184:187], v[18:21]
	v_mfma_f32_16x16x32_bf16 v[62:65], v[102:105], v[160:163], v[62:65]
	v_mfma_f32_16x16x32_bf16 v[58:61], v[110:113], v[160:163], v[58:61]
	v_mfma_f32_16x16x32_bf16 v[46:49], v[102:105], v[172:175], v[46:49]
	v_mfma_f32_16x16x32_bf16 v[42:45], v[110:113], v[172:175], v[42:45]
	v_mfma_f32_16x16x32_bf16 v[30:33], v[102:105], v[180:183], v[30:33]
	v_mfma_f32_16x16x32_bf16 v[26:29], v[110:113], v[180:183], v[26:29]
	v_mfma_f32_16x16x32_bf16 v[22:25], v[102:105], v[188:191], v[22:25]
	v_mfma_f32_16x16x32_bf16 v[18:21], v[110:113], v[188:191], v[18:21]
	v_mfma_f32_16x16x32_bf16 v[54:57], v[192:195], v[152:155], v[54:57]
	v_mfma_f32_16x16x32_bf16 v[50:53], v[200:203], v[152:155], v[50:53]
	v_mfma_f32_16x16x32_bf16 v[38:41], v[192:195], v[164:167], v[38:41]
	v_mfma_f32_16x16x32_bf16 v[34:37], v[200:203], v[164:167], v[34:37]
	v_mfma_f32_16x16x32_bf16 v[14:17], v[192:195], v[176:179], v[14:17]
	v_mfma_f32_16x16x32_bf16 v[10:13], v[200:203], v[176:179], v[10:13]
	v_mfma_f32_16x16x32_bf16 v[6:9], v[192:195], v[184:187], v[6:9]
	v_mfma_f32_16x16x32_bf16 v[2:5], v[200:203], v[184:187], v[2:5]
	v_mfma_f32_16x16x32_bf16 v[54:57], v[196:199], v[160:163], v[54:57]
	v_mfma_f32_16x16x32_bf16 v[50:53], v[204:207], v[160:163], v[50:53]
	v_mfma_f32_16x16x32_bf16 v[38:41], v[196:199], v[172:175], v[38:41]
	v_mfma_f32_16x16x32_bf16 v[34:37], v[204:207], v[172:175], v[34:37]
	v_mfma_f32_16x16x32_bf16 v[14:17], v[196:199], v[180:183], v[14:17]
	v_mfma_f32_16x16x32_bf16 v[10:13], v[204:207], v[180:183], v[10:13]
	v_mfma_f32_16x16x32_bf16 v[6:9], v[196:199], v[188:191], v[6:9]
	v_mfma_f32_16x16x32_bf16 v[2:5], v[204:207], v[188:191], v[2:5]
	s_barrier
; #define PG8_STAGE(bufoff, gbase, voff) do { _Pragma("unroll") for (int _i = 0; _i < 2; ++_i) \
;         __builtin_amdgcn_global_load_lds((const unsigned*)((const char*)(gbase) + (voff)[_i]), (LAS unsigned*)(lds + (bufoff) + ldsw + _i * 8192), 16, 0, 0); } while (0)
; #define PG8_LDA(dst, b, h) do { _Pragma("unroll") for (int m = 0; m < 4; ++m) _Pragma("unroll") for (int k = 0; k < 2; ++k) dst[m][k] = *(const LAS bf16x8*)(lds + PG8_SA(b, h) + aoff + m * 2048 + k * 1024); } while (0)
; #define PG8_LDB(dst, b, h) do { _Pragma("unroll") for (int n = 0; n < 2; ++n) _Pragma("unroll") for (int k = 0; k < 2; ++k) dst[n][k] = *(const LAS bf16x8*)(lds + PG8_SB(b, h) + boff + n * 2048 + k * 1024); } while (0)
; #define PG8_MMA(ai, bj, At, Bt) do { __builtin_amdgcn_s_setprio(1); _Pragma("unroll") for (int m = 0; m < 4; ++m) _Pragma("unroll") for (int n = 0; n < 2; ++n) _Pragma("unroll") for (int k = 0; k < 2; ++k) \
;         acc[ai][bj][m][n] = __builtin_amdgcn_mfma_f32_16x16x32_bf16(Bt[n][k], At[m][k], acc[ai][bj][m][n], 0, 0, 0); __builtin_amdgcn_s_setprio(0); } while (0)
; #define PG8_WAIT_L(n) asm volatile("s_waitcnt lgkmcnt(" #n ")" ::: "memory")
; #define PG8_BAR __builtin_amdgcn_s_barrier()
; #define PG8_SCHED __builtin_amdgcn_sched_barrier(0)
; template <class Epi, class Sched>
; __device__ __forceinline__ void gemm_phase(LAS unsigned char* lds, const Gemm g, const Sched& S, const Epi& E) {
;     ...
;             PG8_LDB(B0, 1, 0); PG8_SCHED; PG8_LDA(At, 1, 0); PG8_STAGE(PG8_SA(0, 1), a2 + hstep, voffA);
;             PG8_WAIT_L(8); PG8_BAR; PG8_WAIT_L(0); PG8_MMA(0, 0, At, B0); PG8_BAR; PG8_SCHED;
;             PG8_LDB(B1, 1, 1); PG8_STAGE(PG8_SB(1, 0), b3, voffB);
;             PG8_BAR; PG8_WAIT_L(0); PG8_MMA(0, 1, At, B1); PG8_BAR;
	s_add_u32 s28, s58, 0x80000
	s_addc_u32 s29, s59, 0
	s_add_i32 s38, s39, s67
	s_mov_b32 m0, s38
	s_nop 0
	global_load_lds_dwordx4 v0, s[28:29]
	s_add_i32 m0, s38, 0x2000
	s_nop 0
	global_load_lds_dwordx4 v146, s[28:29]
	s_add_u32 s28, s60, 0x80000
	s_addc_u32 s29, s61, 0
	s_mov_b32 m0, s69
	s_nop 0
	global_load_lds_dwordx4 v0, s[28:29]
	s_mov_b32 m0, s70
	s_nop 0
	global_load_lds_dwordx4 v146, s[28:29]
	s_add_i32 s38, 0, 0x18000
	ds_read_b128 v[98:101], v226 offset:32768
	ds_read_b128 v[102:105], v226 offset:33792
	ds_read_b128 v[106:109], v226 offset:34816
	ds_read_b128 v[110:113], v226 offset:35840
	ds_read_b128 v[152:155], v171 offset:32768
	ds_read_b128 v[160:163], v171 offset:33792
	ds_read_b128 v[164:167], v171 offset:34816
	ds_read_b128 v[172:175], v171 offset:35840
	ds_read_b128 v[176:179], v171 offset:36864
	ds_read_b128 v[180:183], v171 offset:37888
	ds_read_b128 v[184:187], v171 offset:38912
	ds_read_b128 v[188:191], v171 offset:39936
	s_add_i32 s39, 0, 0x1c000
	s_waitcnt lgkmcnt(0)
	s_barrier
	v_mfma_f32_16x16x32_bf16 v[142:145], v[98:101], v[152:155], v[142:145]
	v_mfma_f32_16x16x32_bf16 v[138:141], v[106:109], v[152:155], v[138:141]
	ds_read_b128 v[192:195], v226 offset:49152
	v_mfma_f32_16x16x32_bf16 v[126:129], v[98:101], v[164:167], v[126:129]
	v_mfma_f32_16x16x32_bf16 v[122:125], v[106:109], v[164:167], v[122:125]
	ds_read_b128 v[196:199], v226 offset:50176
	v_mfma_f32_16x16x32_bf16 v[94:97], v[98:101], v[176:179], v[94:97]
	v_mfma_f32_16x16x32_bf16 v[90:93], v[106:109], v[176:179], v[90:93]
	ds_read_b128 v[200:203], v226 offset:51200
	v_mfma_f32_16x16x32_bf16 v[86:89], v[98:101], v[184:187], v[86:89]
	v_mfma_f32_16x16x32_bf16 v[82:85], v[106:109], v[184:187], v[82:85]
	ds_read_b128 v[204:207], v226 offset:52224
	v_mfma_f32_16x16x32_bf16 v[142:145], v[102:105], v[160:163], v[142:145]
	v_mfma_f32_16x16x32_bf16 v[138:141], v[110:113], v[160:163], v[138:141]
	v_mfma_f32_16x16x32_bf16 v[126:129], v[102:105], v[172:175], v[126:129]
	v_mfma_f32_16x16x32_bf16 v[122:125], v[110:113], v[172:175], v[122:125]
	v_mfma_f32_16x16x32_bf16 v[94:97], v[102:105], v[180:183], v[94:97]
	v_mfma_f32_16x16x32_bf16 v[90:93], v[110:113], v[180:183], v[90:93]
	v_mfma_f32_16x16x32_bf16 v[86:89], v[102:105], v[188:191], v[86:89]
	v_mfma_f32_16x16x32_bf16 v[82:85], v[110:113], v[188:191], v[82:85]
	s_waitcnt lgkmcnt(0)
	v_mfma_f32_16x16x32_bf16 v[134:137], v[192:195], v[152:155], v[134:137]
	v_mfma_f32_16x16x32_bf16 v[130:133], v[200:203], v[152:155], v[130:133]
	v_mfma_f32_16x16x32_bf16 v[118:121], v[192:195], v[164:167], v[118:121]
	v_mfma_f32_16x16x32_bf16 v[114:117], v[200:203], v[164:167], v[114:117]
	v_mfma_f32_16x16x32_bf16 v[78:81], v[192:195], v[176:179], v[78:81]
	v_mfma_f32_16x16x32_bf16 v[74:77], v[200:203], v[176:179], v[74:77]
	v_mfma_f32_16x16x32_bf16 v[70:73], v[192:195], v[184:187], v[70:73]
	v_mfma_f32_16x16x32_bf16 v[66:69], v[200:203], v[184:187], v[66:69]
	v_mfma_f32_16x16x32_bf16 v[134:137], v[196:199], v[160:163], v[134:137]
	v_mfma_f32_16x16x32_bf16 v[130:133], v[204:207], v[160:163], v[130:133]
	v_mfma_f32_16x16x32_bf16 v[118:121], v[196:199], v[172:175], v[118:121]
	v_mfma_f32_16x16x32_bf16 v[114:117], v[204:207], v[172:175], v[114:117]
	v_mfma_f32_16x16x32_bf16 v[78:81], v[196:199], v[180:183], v[78:81]
	v_mfma_f32_16x16x32_bf16 v[74:77], v[204:207], v[180:183], v[74:77]
	v_mfma_f32_16x16x32_bf16 v[70:73], v[196:199], v[188:191], v[70:73]
	v_mfma_f32_16x16x32_bf16 v[66:69], v[204:207], v[188:191], v[66:69]
	s_barrier
; #define PG8_STAGE(bufoff, gbase, voff) do { _Pragma("unroll") for (int _i = 0; _i < 2; ++_i) \
;         __builtin_amdgcn_global_load_lds((const unsigned*)((const char*)(gbase) + (voff)[_i]), (LAS unsigned*)(lds + (bufoff) + ldsw + _i * 8192), 16, 0, 0); } while (0)
; #define PG8_LDA(dst, b, h) do { _Pragma("unroll") for (int m = 0; m < 4; ++m) _Pragma("unroll") for (int k = 0; k < 2; ++k) dst[m][k] = *(const LAS bf16x8*)(lds + PG8_SA(b, h) + aoff + m * 2048 + k * 1024); } while (0)
; #define PG8_MMA(ai, bj, At, Bt) do { __builtin_amdgcn_s_setprio(1); _Pragma("unroll") for (int m = 0; m < 4; ++m) _Pragma("unroll") for (int n = 0; n < 2; ++n) _Pragma("unroll") for (int k = 0; k < 2; ++k) \
;         acc[ai][bj][m][n] = __builtin_amdgcn_mfma_f32_16x16x32_bf16(Bt[n][k], At[m][k], acc[ai][bj][m][n], 0, 0, 0); __builtin_amdgcn_s_setprio(0); } while (0)
; #define PG8_WAIT_V(n) asm volatile("s_waitcnt vmcnt(" #n ")" ::: "memory")
; #define PG8_WAIT_L(n) asm volatile("s_waitcnt lgkmcnt(" #n ")" ::: "memory")
; #define PG8_BAR __builtin_amdgcn_s_barrier()
; #define PG8_SCHED __builtin_amdgcn_sched_barrier(0)
; template <class Epi, class Sched>
; __device__ __forceinline__ void gemm_phase(LAS unsigned char* lds, const Gemm g, const Sched& S, const Epi& E) {
;     ...
;             PG8_LDA(At, 1, 1); PG8_STAGE(PG8_SA(1, 0), a3, voffA);
;             PG8_BAR; PG8_WAIT_L(0); PG8_MMA(1, 0, At, B0); PG8_BAR; PG8_SCHED;
;             PG8_STAGE(PG8_SB(1, 1), b3 + hstep, voffB);
;             PG8_WAIT_V(6); PG8_BAR; PG8_MMA(1, 1, At, B1); PG8_BAR;
	s_add_i32 s28, s38, s67
	s_add_u32 s100, s58, s36
	s_addc_u32 s101, s59, s37
	s_mov_b32 m0, s28
	s_nop 0
	global_load_lds_dwordx4 v0, s[100:101]
	s_add_i32 m0, s28, 0x2000
	s_nop 0
	global_load_lds_dwordx4 v146, s[100:101]
	s_mov_b32 m0, s72
	s_add_u32 s100, s60, s36
	s_addc_u32 s101, s61, s37
	global_load_lds_dwordx4 v0, s[100:101]
	s_mov_b32 m0, s73
	s_nop 0
	global_load_lds_dwordx4 v146, s[100:101]
	ds_read_b128 v[152:155], v171 offset:49152
	ds_read_b128 v[160:163], v171 offset:50176
	ds_read_b128 v[164:167], v171 offset:51200
	ds_read_b128 v[172:175], v171 offset:52224
	ds_read_b128 v[176:179], v171 offset:53248
	ds_read_b128 v[180:183], v171 offset:54272
	ds_read_b128 v[184:187], v171 offset:55296
	ds_read_b128 v[188:191], v171 offset:56320
	s_waitcnt vmcnt(4)
	s_waitcnt lgkmcnt(0)
	s_barrier
	v_mfma_f32_16x16x32_bf16 v[62:65], v[98:101], v[152:155], v[62:65]
	v_mfma_f32_16x16x32_bf16 v[58:61], v[106:109], v[152:155], v[58:61]
	v_mfma_f32_16x16x32_bf16 v[46:49], v[98:101], v[164:167], v[46:49]
	v_mfma_f32_16x16x32_bf16 v[42:45], v[106:109], v[164:167], v[42:45]
	v_mfma_f32_16x16x32_bf16 v[30:33], v[98:101], v[176:179], v[30:33]
	v_mfma_f32_16x16x32_bf16 v[26:29], v[106:109], v[176:179], v[26:29]
	v_mfma_f32_16x16x32_bf16 v[22:25], v[98:101], v[184:187], v[22:25]
	v_mfma_f32_16x16x32_bf16 v[18:21], v[106:109], v[184:187], v[18:21]
	v_mfma_f32_16x16x32_bf16 v[62:65], v[102:105], v[160:163], v[62:65]
	v_mfma_f32_16x16x32_bf16 v[58:61], v[110:113], v[160:163], v[58:61]
	v_mfma_f32_16x16x32_bf16 v[46:49], v[102:105], v[172:175], v[46:49]
	v_mfma_f32_16x16x32_bf16 v[42:45], v[110:113], v[172:175], v[42:45]
	v_mfma_f32_16x16x32_bf16 v[30:33], v[102:105], v[180:183], v[30:33]
	v_mfma_f32_16x16x32_bf16 v[26:29], v[110:113], v[180:183], v[26:29]
	v_mfma_f32_16x16x32_bf16 v[22:25], v[102:105], v[188:191], v[22:25]
	v_mfma_f32_16x16x32_bf16 v[18:21], v[110:113], v[188:191], v[18:21]
	s_add_u32 s28, s58, 0x80080
	s_addc_u32 s29, s59, 0
	s_add_i32 s38, s39, s67
	s_mov_b32 m0, s38
	s_nop 0
	global_load_lds_dwordx4 v0, s[28:29]
	s_add_i32 m0, s38, 0x2000
	s_nop 0
	global_load_lds_dwordx4 v146, s[28:29]
	v_mfma_f32_16x16x32_bf16 v[54:57], v[192:195], v[152:155], v[54:57]
	v_mfma_f32_16x16x32_bf16 v[50:53], v[200:203], v[152:155], v[50:53]
	v_mfma_f32_16x16x32_bf16 v[38:41], v[192:195], v[164:167], v[38:41]
	v_mfma_f32_16x16x32_bf16 v[34:37], v[200:203], v[164:167], v[34:37]
	v_mfma_f32_16x16x32_bf16 v[14:17], v[192:195], v[176:179], v[14:17]
	v_mfma_f32_16x16x32_bf16 v[10:13], v[200:203], v[176:179], v[10:13]
	v_mfma_f32_16x16x32_bf16 v[6:9], v[192:195], v[184:187], v[6:9]
	v_mfma_f32_16x16x32_bf16 v[2:5], v[200:203], v[184:187], v[2:5]
	v_mfma_f32_16x16x32_bf16 v[54:57], v[196:199], v[160:163], v[54:57]
	v_mfma_f32_16x16x32_bf16 v[50:53], v[204:207], v[160:163], v[50:53]
	v_mfma_f32_16x16x32_bf16 v[38:41], v[196:199], v[172:175], v[38:41]
	v_mfma_f32_16x16x32_bf16 v[34:37], v[204:207], v[172:175], v[34:37]
	v_mfma_f32_16x16x32_bf16 v[14:17], v[196:199], v[180:183], v[14:17]
	v_mfma_f32_16x16x32_bf16 v[10:13], v[204:207], v[180:183], v[10:13]
	v_mfma_f32_16x16x32_bf16 v[6:9], v[196:199], v[188:191], v[6:9]
	v_mfma_f32_16x16x32_bf16 v[2:5], v[204:207], v[188:191], v[2:5]
	s_add_i32 s81, s81, 2
	s_add_u32 s79, s79, 0x100
	s_addc_u32 s80, s80, 0
	s_cmp_gt_u32 s81, 29
	s_mov_b64 s[28:29], s[56:57]
	s_barrier
	s_cbranch_scc0 .LBB0_99
	s_cmp_lt_i32 s8, 64
	s_cselect_b64 s[58:59], -1, 0
	s_cmp_gt_i32 s8, 63
	s_cbranch_scc0 .LBB0_90
	s_mov_b64 s[60:61], 0x18000
	s_mov_b64 s[28:29], s[46:47]
	s_mov_b64 s[56:57], s[24:25]
	s_branch .LBB0_91

; #define PG8_STAGE(bufoff, gbase, voff) do { _Pragma("unroll") for (int _i = 0; _i < 2; ++_i) \
;         __builtin_amdgcn_global_load_lds((const unsigned*)((const char*)(gbase) + (voff)[_i]), (LAS unsigned*)(lds + (bufoff) + ldsw + _i * 8192), 16, 0, 0); } while (0)
; #define PG8_LDA(dst, b, h) do { _Pragma("unroll") for (int m = 0; m < 4; ++m) _Pragma("unroll") for (int k = 0; k < 2; ++k) dst[m][k] = *(const LAS bf16x8*)(lds + PG8_SA(b, h) + aoff + m * 2048 + k * 1024); } while (0)
; #define PG8_LDB(dst, b, h) do { _Pragma("unroll") for (int n = 0; n < 2; ++n) _Pragma("unroll") for (int k = 0; k < 2; ++k) dst[n][k] = *(const LAS bf16x8*)(lds + PG8_SB(b, h) + boff + n * 2048 + k * 1024); } while (0)
; #define PG8_MMA(ai, bj, At, Bt) do { __builtin_amdgcn_s_setprio(1); _Pragma("unroll") for (int m = 0; m < 4; ++m) _Pragma("unroll") for (int n = 0; n < 2; ++n) _Pragma("unroll") for (int k = 0; k < 2; ++k) \
;         acc[ai][bj][m][n] = __builtin_amdgcn_mfma_f32_16x16x32_bf16(Bt[n][k], At[m][k], acc[ai][bj][m][n], 0, 0, 0); __builtin_amdgcn_s_setprio(0); } while (0)
; #define PG8_WAIT_V(n) asm volatile("s_waitcnt vmcnt(" #n ")" ::: "memory")
; #define PG8_WAIT_L(n) asm volatile("s_waitcnt lgkmcnt(" #n ")" ::: "memory")
; template <class Epi, class Sched>
; __device__ __forceinline__ void gemm_phase(LAS unsigned char* lds, const Gemm g, const Sched& S, const Epi& E) {
;     ...
;         for (int t = 0; t < nt; t += 2) {
;             const bool last = (t == nt - 2);
;             const char* a1 = cA + (size_t)(t + 1) * kstep;
;             const char* a2 = last ? nA : cA + (size_t)(t + 2) * kstep; const char* b2 = last ? nB : cB + (size_t)(t + 2) * kstep;
;             const char* a3 = a2 + kstep; const char* b3 = b2 + kstep;
;             PG8_LDB(B0, 0, 0); PG8_SCHED; PG8_LDA(At, 0, 0); PG8_STAGE(PG8_SA(1, 1), a1 + hstep, voffA);
;             PG8_WAIT_L(8); PG8_BAR; PG8_WAIT_L(0); PG8_MMA(0, 0, At, B0); PG8_BAR; PG8_SCHED;
;             PG8_LDB(B1, 0, 1); PG8_STAGE(PG8_SB(0, 0), b2, voffB);
;             PG8_BAR; PG8_WAIT_L(0); PG8_MMA(0, 1, At, B1); PG8_BAR;
;             PG8_LDA(At, 0, 1); PG8_STAGE(PG8_SA(0, 0), a2, voffA);
;             PG8_BAR; PG8_WAIT_L(0); PG8_MMA(1, 0, At, B0); PG8_BAR; PG8_SCHED;
;             PG8_STAGE(PG8_SB(0, 1), b2 + hstep, voffB);
;             PG8_WAIT_V(6); PG8_BAR; PG8_MMA(1, 1, At, B1); PG8_BAR;
.LBB0_113:
	s_add_u32 s54, s52, 0x100
	s_addc_u32 s55, s53, 0
	s_cmp_eq_u32 s73, 4
	s_cselect_b32 s59, s11, s55
	s_cselect_b32 s58, s29, s54
	s_cselect_b32 s57, s41, s72
	s_cselect_b32 s56, s45, s71
	s_add_i32 m0, s25, 0xc000
	s_nop 0
	global_load_lds_dwordx4 v134, s[52:53]
	s_add_i32 m0, s25, 0xe000
	s_nop 0
	global_load_lds_dwordx4 v132, s[52:53]
	s_add_i32 s38, 0, 0x10000
	ds_read_b128 v[140:143], v226
	ds_read_b128 v[144:147], v226 offset:1024
	ds_read_b128 v[148:151], v226 offset:2048
	ds_read_b128 v[152:155], v226 offset:3072
	ds_read_b128 v[160:163], v139
	ds_read_b128 v[164:167], v139 offset:1024
	ds_read_b128 v[168:171], v139 offset:2048
	ds_read_b128 v[172:175], v139 offset:3072
	ds_read_b128 v[176:179], v139 offset:4096
	ds_read_b128 v[180:183], v139 offset:5120
	ds_read_b128 v[184:187], v139 offset:6144
	ds_read_b128 v[188:191], v139 offset:7168
	s_add_i32 s52, 0, 0x14000
	s_waitcnt lgkmcnt(0)
	s_barrier
	v_mfma_f32_16x16x32_bf16 v[126:129], v[140:143], v[160:163], v[126:129]
	v_mfma_f32_16x16x32_bf16 v[122:125], v[148:151], v[160:163], v[122:125]
	ds_read_b128 v[192:195], v226 offset:16384
	v_mfma_f32_16x16x32_bf16 v[118:121], v[140:143], v[168:171], v[118:121]
	v_mfma_f32_16x16x32_bf16 v[114:117], v[148:151], v[168:171], v[114:117]
	ds_read_b128 v[196:199], v226 offset:17408
	v_mfma_f32_16x16x32_bf16 v[106:109], v[140:143], v[176:179], v[106:109]
	v_mfma_f32_16x16x32_bf16 v[98:101], v[148:151], v[176:179], v[98:101]
	ds_read_b128 v[200:203], v226 offset:18432
	v_mfma_f32_16x16x32_bf16 v[90:93], v[140:143], v[184:187], v[90:93]
	v_mfma_f32_16x16x32_bf16 v[82:85], v[148:151], v[184:187], v[82:85]
	ds_read_b128 v[204:207], v226 offset:19456
	v_mfma_f32_16x16x32_bf16 v[126:129], v[144:147], v[164:167], v[126:129]
	v_mfma_f32_16x16x32_bf16 v[122:125], v[152:155], v[164:167], v[122:125]
	v_mfma_f32_16x16x32_bf16 v[118:121], v[144:147], v[172:175], v[118:121]
	v_mfma_f32_16x16x32_bf16 v[114:117], v[152:155], v[172:175], v[114:117]
	v_mfma_f32_16x16x32_bf16 v[106:109], v[144:147], v[180:183], v[106:109]
	v_mfma_f32_16x16x32_bf16 v[98:101], v[152:155], v[180:183], v[98:101]
	v_mfma_f32_16x16x32_bf16 v[90:93], v[144:147], v[188:191], v[90:93]
	v_mfma_f32_16x16x32_bf16 v[82:85], v[152:155], v[188:191], v[82:85]
	s_waitcnt lgkmcnt(0)
	v_mfma_f32_16x16x32_bf16 v[110:113], v[192:195], v[160:163], v[110:113]
	v_mfma_f32_16x16x32_bf16 v[102:105], v[200:203], v[160:163], v[102:105]
	v_mfma_f32_16x16x32_bf16 v[94:97], v[192:195], v[168:171], v[94:97]
	v_mfma_f32_16x16x32_bf16 v[86:89], v[200:203], v[168:171], v[86:89]
	v_mfma_f32_16x16x32_bf16 v[78:81], v[192:195], v[176:179], v[78:81]
	v_mfma_f32_16x16x32_bf16 v[74:77], v[200:203], v[176:179], v[74:77]
	v_mfma_f32_16x16x32_bf16 v[70:73], v[192:195], v[184:187], v[70:73]
	v_mfma_f32_16x16x32_bf16 v[66:69], v[200:203], v[184:187], v[66:69]
	v_mfma_f32_16x16x32_bf16 v[110:113], v[196:199], v[164:167], v[110:113]
	v_mfma_f32_16x16x32_bf16 v[102:105], v[204:207], v[164:167], v[102:105]
	v_mfma_f32_16x16x32_bf16 v[94:97], v[196:199], v[172:175], v[94:97]
	v_mfma_f32_16x16x32_bf16 v[86:89], v[204:207], v[172:175], v[86:89]
	v_mfma_f32_16x16x32_bf16 v[78:81], v[196:199], v[180:183], v[78:81]
	v_mfma_f32_16x16x32_bf16 v[74:77], v[204:207], v[180:183], v[74:77]
	v_mfma_f32_16x16x32_bf16 v[70:73], v[196:199], v[188:191], v[70:73]
	v_mfma_f32_16x16x32_bf16 v[66:69], v[204:207], v[188:191], v[66:69]
	s_barrier
	s_add_i32 s38, s38, s65
	s_mov_b32 m0, s38
	s_nop 0
	global_load_lds_dwordx4 v0, s[56:57]
	s_add_i32 m0, s38, 0x2000
	s_nop 0
	global_load_lds_dwordx4 v130, s[56:57]
	s_mov_b32 m0, s25
	s_nop 0
	global_load_lds_dwordx4 v0, s[58:59]
	s_mov_b32 m0, s27
	s_nop 0
	global_load_lds_dwordx4 v130, s[58:59]
	ds_read_b128 v[160:163], v139 offset:16384
	ds_read_b128 v[164:167], v139 offset:17408
	ds_read_b128 v[168:171], v139 offset:18432
	ds_read_b128 v[172:175], v139 offset:19456
	ds_read_b128 v[176:179], v139 offset:20480
	ds_read_b128 v[180:183], v139 offset:21504
	ds_read_b128 v[184:187], v139 offset:22528
	ds_read_b128 v[188:191], v139 offset:23552
	s_waitcnt vmcnt(4)
	s_waitcnt lgkmcnt(0)
	s_barrier
	v_mfma_f32_16x16x32_bf16 v[62:65], v[140:143], v[160:163], v[62:65]
	v_mfma_f32_16x16x32_bf16 v[58:61], v[148:151], v[160:163], v[58:61]
	v_mfma_f32_16x16x32_bf16 v[54:57], v[140:143], v[168:171], v[54:57]
	v_mfma_f32_16x16x32_bf16 v[50:53], v[148:151], v[168:171], v[50:53]
	v_mfma_f32_16x16x32_bf16 v[38:41], v[140:143], v[176:179], v[38:41]
	v_mfma_f32_16x16x32_bf16 v[34:37], v[148:151], v[176:179], v[34:37]
	v_mfma_f32_16x16x32_bf16 v[22:25], v[140:143], v[184:187], v[22:25]
	v_mfma_f32_16x16x32_bf16 v[18:21], v[148:151], v[184:187], v[18:21]
	v_mfma_f32_16x16x32_bf16 v[62:65], v[144:147], v[164:167], v[62:65]
	v_mfma_f32_16x16x32_bf16 v[58:61], v[152:155], v[164:167], v[58:61]
	v_mfma_f32_16x16x32_bf16 v[54:57], v[144:147], v[172:175], v[54:57]
	v_mfma_f32_16x16x32_bf16 v[50:53], v[152:155], v[172:175], v[50:53]
	v_mfma_f32_16x16x32_bf16 v[38:41], v[144:147], v[180:183], v[38:41]
	v_mfma_f32_16x16x32_bf16 v[34:37], v[152:155], v[180:183], v[34:37]
	v_mfma_f32_16x16x32_bf16 v[22:25], v[144:147], v[188:191], v[22:25]
	v_mfma_f32_16x16x32_bf16 v[18:21], v[152:155], v[188:191], v[18:21]
	v_mfma_f32_16x16x32_bf16 v[46:49], v[192:195], v[160:163], v[46:49]
	v_mfma_f32_16x16x32_bf16 v[42:45], v[200:203], v[160:163], v[42:45]
	v_mfma_f32_16x16x32_bf16 v[30:33], v[192:195], v[168:171], v[30:33]
	v_mfma_f32_16x16x32_bf16 v[26:29], v[200:203], v[168:171], v[26:29]
	v_mfma_f32_16x16x32_bf16 v[14:17], v[192:195], v[176:179], v[14:17]
	v_mfma_f32_16x16x32_bf16 v[10:13], v[200:203], v[176:179], v[10:13]
	v_mfma_f32_16x16x32_bf16 v[6:9], v[192:195], v[184:187], v[6:9]
	v_mfma_f32_16x16x32_bf16 v[2:5], v[200:203], v[184:187], v[2:5]
	v_mfma_f32_16x16x32_bf16 v[46:49], v[196:199], v[164:167], v[46:49]
	v_mfma_f32_16x16x32_bf16 v[42:45], v[204:207], v[164:167], v[42:45]
	v_mfma_f32_16x16x32_bf16 v[30:33], v[196:199], v[172:175], v[30:33]
	v_mfma_f32_16x16x32_bf16 v[26:29], v[204:207], v[172:175], v[26:29]
	v_mfma_f32_16x16x32_bf16 v[14:17], v[196:199], v[180:183], v[14:17]
	v_mfma_f32_16x16x32_bf16 v[10:13], v[204:207], v[180:183], v[10:13]
	v_mfma_f32_16x16x32_bf16 v[6:9], v[196:199], v[188:191], v[6:9]
	v_mfma_f32_16x16x32_bf16 v[2:5], v[204:207], v[188:191], v[2:5]
	s_barrier
; #define PG8_STAGE(bufoff, gbase, voff) do { _Pragma("unroll") for (int _i = 0; _i < 2; ++_i) \
;         __builtin_amdgcn_global_load_lds((const unsigned*)((const char*)(gbase) + (voff)[_i]), (LAS unsigned*)(lds + (bufoff) + ldsw + _i * 8192), 16, 0, 0); } while (0)
; #define PG8_LDA(dst, b, h) do { _Pragma("unroll") for (int m = 0; m < 4; ++m) _Pragma("unroll") for (int k = 0; k < 2; ++k) dst[m][k] = *(const LAS bf16x8*)(lds + PG8_SA(b, h) + aoff + m * 2048 + k * 1024); } while (0)
; #define PG8_LDB(dst, b, h) do { _Pragma("unroll") for (int n = 0; n < 2; ++n) _Pragma("unroll") for (int k = 0; k < 2; ++k) dst[n][k] = *(const LAS bf16x8*)(lds + PG8_SB(b, h) + boff + n * 2048 + k * 1024); } while (0)
; #define PG8_MMA(ai, bj, At, Bt) do { __builtin_amdgcn_s_setprio(1); _Pragma("unroll") for (int m = 0; m < 4; ++m) _Pragma("unroll") for (int n = 0; n < 2; ++n) _Pragma("unroll") for (int k = 0; k < 2; ++k) \
;         acc[ai][bj][m][n] = __builtin_amdgcn_mfma_f32_16x16x32_bf16(Bt[n][k], At[m][k], acc[ai][bj][m][n], 0, 0, 0); __builtin_amdgcn_s_setprio(0); } while (0)
; #define PG8_WAIT_L(n) asm volatile("s_waitcnt lgkmcnt(" #n ")" ::: "memory")
; #define PG8_BAR __builtin_amdgcn_s_barrier()
; #define PG8_SCHED __builtin_amdgcn_sched_barrier(0)
; template <class Epi, class Sched>
; __device__ __forceinline__ void gemm_phase(LAS unsigned char* lds, const Gemm g, const Sched& S, const Epi& E) {
;     ...
;             PG8_LDB(B0, 1, 0); PG8_SCHED; PG8_LDA(At, 1, 0); PG8_STAGE(PG8_SA(0, 1), a2 + hstep, voffA);
;             PG8_WAIT_L(8); PG8_BAR; PG8_WAIT_L(0); PG8_MMA(0, 0, At, B0); PG8_BAR; PG8_SCHED;
;             PG8_LDB(B1, 1, 1); PG8_STAGE(PG8_SB(1, 0), b3, voffB);
;             PG8_BAR; PG8_WAIT_L(0); PG8_MMA(0, 1, At, B1); PG8_BAR;
;             PG8_LDA(At, 1, 1); PG8_STAGE(PG8_SA(1, 0), a3, voffA);
;             PG8_BAR; PG8_WAIT_L(0); PG8_MMA(1, 0, At, B0); PG8_BAR; PG8_SCHED;
	s_add_u32 s38, s56, 0x80000
	s_addc_u32 s39, s57, 0
	s_add_i32 s52, s52, s65
	s_mov_b32 m0, s52
	s_nop 0
	global_load_lds_dwordx4 v0, s[38:39]
	s_add_i32 m0, s52, 0x2000
	s_nop 0
	global_load_lds_dwordx4 v130, s[38:39]
	s_add_u32 s38, s58, 0x80000
	s_addc_u32 s39, s59, 0
	s_mov_b32 m0, s66
	s_nop 0
	global_load_lds_dwordx4 v0, s[38:39]
	s_mov_b32 m0, s67
	s_nop 0
	global_load_lds_dwordx4 v130, s[38:39]
	s_add_i32 s52, 0, 0x18000
	ds_read_b128 v[140:143], v226 offset:32768
	ds_read_b128 v[144:147], v226 offset:33792
	ds_read_b128 v[148:151], v226 offset:34816
	ds_read_b128 v[152:155], v226 offset:35840
	ds_read_b128 v[160:163], v139 offset:32768
	ds_read_b128 v[164:167], v139 offset:33792
	ds_read_b128 v[168:171], v139 offset:34816
	ds_read_b128 v[172:175], v139 offset:35840
	ds_read_b128 v[176:179], v139 offset:36864
	ds_read_b128 v[180:183], v139 offset:37888
	ds_read_b128 v[184:187], v139 offset:38912
	ds_read_b128 v[188:191], v139 offset:39936
	s_add_i32 s53, 0, 0x1c000
	s_waitcnt lgkmcnt(0)
	s_barrier
	v_mfma_f32_16x16x32_bf16 v[126:129], v[140:143], v[160:163], v[126:129]
	v_mfma_f32_16x16x32_bf16 v[122:125], v[148:151], v[160:163], v[122:125]
	ds_read_b128 v[192:195], v226 offset:49152
	v_mfma_f32_16x16x32_bf16 v[118:121], v[140:143], v[168:171], v[118:121]
	v_mfma_f32_16x16x32_bf16 v[114:117], v[148:151], v[168:171], v[114:117]
	ds_read_b128 v[196:199], v226 offset:50176
	v_mfma_f32_16x16x32_bf16 v[106:109], v[140:143], v[176:179], v[106:109]
	v_mfma_f32_16x16x32_bf16 v[98:101], v[148:151], v[176:179], v[98:101]
	ds_read_b128 v[200:203], v226 offset:51200
	v_mfma_f32_16x16x32_bf16 v[90:93], v[140:143], v[184:187], v[90:93]
	v_mfma_f32_16x16x32_bf16 v[82:85], v[148:151], v[184:187], v[82:85]
	ds_read_b128 v[204:207], v226 offset:52224
	v_mfma_f32_16x16x32_bf16 v[126:129], v[144:147], v[164:167], v[126:129]
	v_mfma_f32_16x16x32_bf16 v[122:125], v[152:155], v[164:167], v[122:125]
	v_mfma_f32_16x16x32_bf16 v[118:121], v[144:147], v[172:175], v[118:121]
	v_mfma_f32_16x16x32_bf16 v[114:117], v[152:155], v[172:175], v[114:117]
	v_mfma_f32_16x16x32_bf16 v[106:109], v[144:147], v[180:183], v[106:109]
	v_mfma_f32_16x16x32_bf16 v[98:101], v[152:155], v[180:183], v[98:101]
	v_mfma_f32_16x16x32_bf16 v[90:93], v[144:147], v[188:191], v[90:93]
	v_mfma_f32_16x16x32_bf16 v[82:85], v[152:155], v[188:191], v[82:85]
	s_waitcnt lgkmcnt(0)
	v_mfma_f32_16x16x32_bf16 v[110:113], v[192:195], v[160:163], v[110:113]
	v_mfma_f32_16x16x32_bf16 v[102:105], v[200:203], v[160:163], v[102:105]
	v_mfma_f32_16x16x32_bf16 v[94:97], v[192:195], v[168:171], v[94:97]
	v_mfma_f32_16x16x32_bf16 v[86:89], v[200:203], v[168:171], v[86:89]
	v_mfma_f32_16x16x32_bf16 v[78:81], v[192:195], v[176:179], v[78:81]
	v_mfma_f32_16x16x32_bf16 v[74:77], v[200:203], v[176:179], v[74:77]
	v_mfma_f32_16x16x32_bf16 v[70:73], v[192:195], v[184:187], v[70:73]
	v_mfma_f32_16x16x32_bf16 v[66:69], v[200:203], v[184:187], v[66:69]
	v_mfma_f32_16x16x32_bf16 v[110:113], v[196:199], v[164:167], v[110:113]
	v_mfma_f32_16x16x32_bf16 v[102:105], v[204:207], v[164:167], v[102:105]
	v_mfma_f32_16x16x32_bf16 v[94:97], v[196:199], v[172:175], v[94:97]
	v_mfma_f32_16x16x32_bf16 v[86:89], v[204:207], v[172:175], v[86:89]
	v_mfma_f32_16x16x32_bf16 v[78:81], v[196:199], v[180:183], v[78:81]
	v_mfma_f32_16x16x32_bf16 v[74:77], v[204:207], v[180:183], v[74:77]
	v_mfma_f32_16x16x32_bf16 v[70:73], v[196:199], v[188:191], v[70:73]
	v_mfma_f32_16x16x32_bf16 v[66:69], v[204:207], v[188:191], v[66:69]
	s_barrier
	s_add_i32 s38, s52, s65
	s_add_u32 s100, s56, s36
	s_addc_u32 s101, s57, s37
	s_mov_b32 m0, s38
	s_nop 0
	global_load_lds_dwordx4 v0, s[100:101]
	s_add_i32 m0, s38, 0x2000
	s_nop 0
	global_load_lds_dwordx4 v130, s[100:101]
	s_mov_b32 m0, s68
	s_add_u32 s100, s58, s36
	s_addc_u32 s101, s59, s37
	global_load_lds_dwordx4 v0, s[100:101]
	s_mov_b32 m0, s69
	s_nop 0
	global_load_lds_dwordx4 v130, s[100:101]
	ds_read_b128 v[160:163], v139 offset:49152
	ds_read_b128 v[164:167], v139 offset:50176
	ds_read_b128 v[168:171], v139 offset:51200
	ds_read_b128 v[172:175], v139 offset:52224
	ds_read_b128 v[176:179], v139 offset:53248
	ds_read_b128 v[180:183], v139 offset:54272
	ds_read_b128 v[184:187], v139 offset:55296
	ds_read_b128 v[188:191], v139 offset:56320
	s_waitcnt vmcnt(4)
	s_waitcnt lgkmcnt(0)
	s_barrier
; #define PG8_STAGE(bufoff, gbase, voff) do { _Pragma("unroll") for (int _i = 0; _i < 2; ++_i) \
;         __builtin_amdgcn_global_load_lds((const unsigned*)((const char*)(gbase) + (voff)[_i]), (LAS unsigned*)(lds + (bufoff) + ldsw + _i * 8192), 16, 0, 0); } while (0)
; #define PG8_MMA(ai, bj, At, Bt) do { __builtin_amdgcn_s_setprio(1); _Pragma("unroll") for (int m = 0; m < 4; ++m) _Pragma("unroll") for (int n = 0; n < 2; ++n) _Pragma("unroll") for (int k = 0; k < 2; ++k) \
;         acc[ai][bj][m][n] = __builtin_amdgcn_mfma_f32_16x16x32_bf16(Bt[n][k], At[m][k], acc[ai][bj][m][n], 0, 0, 0); __builtin_amdgcn_s_setprio(0); } while (0)
; #define PG8_WAIT_V(n) asm volatile("s_waitcnt vmcnt(" #n ")" ::: "memory")
; #define PG8_BAR __builtin_amdgcn_s_barrier()
;     __device__ __forceinline__ void operator()(const f32x4 (&acc)[2][2][4][2], const Unit& u, int wr, int wc, int fr, int fq) const {
;         const int row0 = u.pm * BM + wr * 64 + fr, col0 = u.pn * BM + wc * 32 + 4 * fq;
;         float* base = part + (size_t)u.ks * Mp * ldc;
; #pragma unroll
;         for (int ai = 0; ai < 2; ++ai)
; #pragma unroll
;             for (int m = 0; m < 4; ++m) { float* rowp = base + (size_t)(row0 + ai * HALF + m * 16) * ldc + col0;
; #pragma unroll
;                 for (int bj = 0; bj < 2; ++bj)
; #pragma unroll
;                     for (int n = 0; n < 2; ++n) *(f32x4*)(rowp + bj * HALF + n * 16) = acc[ai][bj][m][n]; }
;     }
; template <class Epi, class Sched>
; __device__ __forceinline__ void gemm_phase(LAS unsigned char* lds, const Gemm g, const Sched& S, const Epi& E) {
;     ...
;             PG8_STAGE(PG8_SB(1, 1), b3 + hstep, voffB);
;             PG8_WAIT_V(6); PG8_BAR; PG8_MMA(1, 1, At, B1); PG8_BAR;
;         }
;         E(acc, cur, wr, wc, fr, fq);
;         if (!has_next) break;
	v_mfma_f32_16x16x32_bf16 v[62:65], v[140:143], v[160:163], v[62:65]
	v_mfma_f32_16x16x32_bf16 v[58:61], v[148:151], v[160:163], v[58:61]
	v_mfma_f32_16x16x32_bf16 v[54:57], v[140:143], v[168:171], v[54:57]
	v_mfma_f32_16x16x32_bf16 v[50:53], v[148:151], v[168:171], v[50:53]
	v_mfma_f32_16x16x32_bf16 v[38:41], v[140:143], v[176:179], v[38:41]
	v_mfma_f32_16x16x32_bf16 v[34:37], v[148:151], v[176:179], v[34:37]
	v_mfma_f32_16x16x32_bf16 v[22:25], v[140:143], v[184:187], v[22:25]
	v_mfma_f32_16x16x32_bf16 v[18:21], v[148:151], v[184:187], v[18:21]
	v_mfma_f32_16x16x32_bf16 v[62:65], v[144:147], v[164:167], v[62:65]
	v_mfma_f32_16x16x32_bf16 v[58:61], v[152:155], v[164:167], v[58:61]
	v_mfma_f32_16x16x32_bf16 v[54:57], v[144:147], v[172:175], v[54:57]
	v_mfma_f32_16x16x32_bf16 v[50:53], v[152:155], v[172:175], v[50:53]
	v_mfma_f32_16x16x32_bf16 v[38:41], v[144:147], v[180:183], v[38:41]
	v_mfma_f32_16x16x32_bf16 v[34:37], v[152:155], v[180:183], v[34:37]
	v_mfma_f32_16x16x32_bf16 v[22:25], v[144:147], v[188:191], v[22:25]
	v_mfma_f32_16x16x32_bf16 v[18:21], v[152:155], v[188:191], v[18:21]
	s_add_u32 s38, s56, 0x80080
	s_addc_u32 s39, s57, 0
	s_add_i32 s52, s53, s65
	s_mov_b32 m0, s52
	s_nop 0
	global_load_lds_dwordx4 v0, s[38:39]
	s_add_i32 m0, s52, 0x2000
	s_nop 0
	global_load_lds_dwordx4 v130, s[38:39]
	v_mfma_f32_16x16x32_bf16 v[46:49], v[192:195], v[160:163], v[46:49]
	v_mfma_f32_16x16x32_bf16 v[42:45], v[200:203], v[160:163], v[42:45]
	v_mfma_f32_16x16x32_bf16 v[30:33], v[192:195], v[168:171], v[30:33]
	v_mfma_f32_16x16x32_bf16 v[26:29], v[200:203], v[168:171], v[26:29]
	v_mfma_f32_16x16x32_bf16 v[14:17], v[192:195], v[176:179], v[14:17]
	v_mfma_f32_16x16x32_bf16 v[10:13], v[200:203], v[176:179], v[10:13]
	v_mfma_f32_16x16x32_bf16 v[6:9], v[192:195], v[184:187], v[6:9]
	v_mfma_f32_16x16x32_bf16 v[2:5], v[200:203], v[184:187], v[2:5]
	v_mfma_f32_16x16x32_bf16 v[46:49], v[196:199], v[164:167], v[46:49]
	v_mfma_f32_16x16x32_bf16 v[42:45], v[204:207], v[164:167], v[42:45]
	v_mfma_f32_16x16x32_bf16 v[30:33], v[196:199], v[172:175], v[30:33]
	v_mfma_f32_16x16x32_bf16 v[26:29], v[204:207], v[172:175], v[26:29]
	v_mfma_f32_16x16x32_bf16 v[14:17], v[196:199], v[180:183], v[14:17]
	v_mfma_f32_16x16x32_bf16 v[10:13], v[204:207], v[180:183], v[10:13]
	v_mfma_f32_16x16x32_bf16 v[6:9], v[196:199], v[188:191], v[6:9]
	v_mfma_f32_16x16x32_bf16 v[2:5], v[204:207], v[188:191], v[2:5]
	s_add_i32 s73, s73, 2
	s_add_u32 s71, s71, 0x100
	s_addc_u32 s72, s72, 0
	s_cmp_gt_u32 s73, 5
	s_mov_b64 s[52:53], s[54:55]
	s_barrier
	s_cbranch_scc0 .LBB0_113
	s_ashr_i32 s11, s10, 31
	s_lshl_b64 s[10:11], s[10:11], 24
	v_lshl_or_b32 v140, s26, 8, v138
	s_add_u32 s10, s8, s10
	v_lshl_add_u32 v142, s24, 8, v136
	s_addc_u32 s11, s9, s11
	v_ashrrev_i32_e32 v141, 31, v140
	v_ashrrev_i32_e32 v143, 31, v142
	v_lshl_add_u64 v[140:141], v[140:141], 2, s[10:11]
	v_lshlrev_b64 v[144:145], 13, v[142:143]
	v_lshl_add_u64 v[144:145], v[140:141], 0, v[144:145]
	global_store_dwordx4 v[144:145], v[126:129], off
	global_store_dwordx4 v[144:145], v[122:125], off offset:64
	global_store_dwordx4 v[144:145], v[110:113], off offset:512
	global_store_dwordx4 v[144:145], v[102:105], off offset:576
	s_mov_b64 s[10:11], 0x100000
	s_mov_b32 s26, s40
	v_or_b32_e32 v102, 16, v142
	v_ashrrev_i32_e32 v103, 31, v102
	v_lshlrev_b64 v[102:103], 13, v[102:103]
	v_lshl_add_u64 v[102:103], v[140:141], 0, v[102:103]
	global_store_dwordx4 v[102:103], v[118:121], off
	global_store_dwordx4 v[102:103], v[114:117], off offset:64
	global_store_dwordx4 v[102:103], v[94:97], off offset:512
	global_store_dwordx4 v[102:103], v[86:89], off offset:576
	s_mov_b32 s24, s44
	s_mov_b64 s[54:55], s[50:51]
	v_or_b32_e32 v86, 32, v142
	v_ashrrev_i32_e32 v87, 31, v86
	v_lshlrev_b64 v[86:87], 13, v[86:87]
	v_lshl_add_u64 v[86:87], v[140:141], 0, v[86:87]
	global_store_dwordx4 v[86:87], v[106:109], off
	global_store_dwordx4 v[86:87], v[98:101], off offset:64
	global_store_dwordx4 v[86:87], v[78:81], off offset:512
	global_store_dwordx4 v[86:87], v[74:77], off offset:576
	s_mov_b64 s[52:53], s[48:49]
	s_nop 0
	v_or_b32_e32 v74, 48, v142
	v_ashrrev_i32_e32 v75, 31, v74
	v_lshlrev_b64 v[74:75], 13, v[74:75]
	v_lshl_add_u64 v[74:75], v[140:141], 0, v[74:75]
	global_store_dwordx4 v[74:75], v[90:93], off
	global_store_dwordx4 v[74:75], v[82:85], off offset:64
	global_store_dwordx4 v[74:75], v[70:73], off offset:512
	global_store_dwordx4 v[74:75], v[66:69], off offset:576
	s_nop 1
	v_add_co_u32_e32 v68, vcc, s93, v144
	v_lshl_add_u64 v[66:67], v[144:145], 0, s[10:11]
	s_nop 0
	v_addc_co_u32_e32 v69, vcc, 0, v145, vcc
	s_mov_b64 s[10:11], 0x120000
	global_store_dwordx4 v[68:69], v[62:65], off
	global_store_dwordx4 v[66:67], v[58:61], off offset:64
	global_store_dwordx4 v[66:67], v[46:49], off offset:512
	global_store_dwordx4 v[66:67], v[42:45], off offset:576
	s_nop 1
	v_lshl_add_u64 v[42:43], v[144:145], 0, s[10:11]
	s_mov_b32 s10, 0x120000
	v_add_co_u32_e32 v44, vcc, s10, v144
	s_mov_b64 s[10:11], 0x140000
	s_nop 0
	v_addc_co_u32_e32 v45, vcc, 0, v145, vcc
	global_store_dwordx4 v[44:45], v[54:57], off
	global_store_dwordx4 v[42:43], v[50:53], off offset:64
	global_store_dwordx4 v[42:43], v[30:33], off offset:512
	global_store_dwordx4 v[42:43], v[26:29], off offset:576
	s_nop 1
	v_lshl_add_u64 v[26:27], v[144:145], 0, s[10:11]
	s_mov_b32 s10, 0x140000
	v_add_co_u32_e32 v28, vcc, s10, v144
	s_mov_b64 s[10:11], 0x160000
	s_nop 0
	v_addc_co_u32_e32 v29, vcc, 0, v145, vcc
	global_store_dwordx4 v[28:29], v[38:41], off
	global_store_dwordx4 v[26:27], v[34:37], off offset:64
	global_store_dwordx4 v[26:27], v[14:17], off offset:512
	global_store_dwordx4 v[26:27], v[10:13], off offset:576
	s_nop 1
	v_add_co_u32_e32 v12, vcc, 0x160000, v144
	v_lshl_add_u64 v[10:11], v[144:145], 0, s[10:11]
	s_nop 0
	v_addc_co_u32_e32 v13, vcc, 0, v145, vcc
	s_and_b64 vcc, exec, s[46:47]
	s_mov_b32 s10, s28
	global_store_dwordx4 v[12:13], v[22:25], off
	global_store_dwordx4 v[10:11], v[18:21], off offset:64
	global_store_dwordx4 v[10:11], v[6:9], off offset:512
	global_store_dwordx4 v[10:11], v[2:5], off offset:576
	s_cbranch_vccz .LBB0_110
	s_waitcnt vmcnt(0)
	s_cmpk_gt_u32 s60, 0xff
	s_cbranch_scc1 .LBB0_117
	s_barrier

; #define PG8_STAGE(bufoff, gbase, voff) do { _Pragma("unroll") for (int _i = 0; _i < 2; ++_i) \
;         __builtin_amdgcn_global_load_lds((const unsigned*)((const char*)(gbase) + (voff)[_i]), (LAS unsigned*)(lds + (bufoff) + ldsw + _i * 8192), 16, 0, 0); } while (0)
; #define PG8_LDA(dst, b, h) do { _Pragma("unroll") for (int m = 0; m < 4; ++m) _Pragma("unroll") for (int k = 0; k < 2; ++k) dst[m][k] = *(const LAS bf16x8*)(lds + PG8_SA(b, h) + aoff + m * 2048 + k * 1024); } while (0)
; #define PG8_LDB(dst, b, h) do { _Pragma("unroll") for (int n = 0; n < 2; ++n) _Pragma("unroll") for (int k = 0; k < 2; ++k) dst[n][k] = *(const LAS bf16x8*)(lds + PG8_SB(b, h) + boff + n * 2048 + k * 1024); } while (0)
; #define PG8_WAIT_V(n) asm volatile("s_waitcnt vmcnt(" #n ")" ::: "memory")
; #define PG8_WAIT_L(n) asm volatile("s_waitcnt lgkmcnt(" #n ")" ::: "memory")
; #define PG8_BAR __builtin_amdgcn_s_barrier()
; #define PG8_SCHED __builtin_amdgcn_sched_barrier(0)
; template <class Epi, class Sched>
; __device__ __forceinline__ void gemm_phase(LAS unsigned char* lds, const Gemm g, const Sched& S, const Epi& E) {
;     ...
;     for (;;) {
;         const bool has_next = S.next(ui + 1, nxt);
;         const char* nA = has_next ? (const char*)g.A + (size_t)nxt.pm * tstep + (size_t)nxt.ks * sstep : cA; const char* nB = has_next ? (const char*)g.Bt + (size_t)nxt.pn * tstep + (size_t)nxt.ks * sstep : cB;
;         for (int t = 0; t < nt; t += 2) {
;             const bool last = (t == nt - 2);
;             const char* a1 = cA + (size_t)(t + 1) * kstep;
;             const char* a2 = last ? nA : cA + (size_t)(t + 2) * kstep; const char* b2 = last ? nB : cB + (size_t)(t + 2) * kstep;
;             const char* a3 = a2 + kstep; const char* b3 = b2 + kstep;
;             PG8_LDB(B0, 0, 0); PG8_SCHED; PG8_LDA(At, 0, 0); PG8_STAGE(PG8_SA(1, 1), a1 + hstep, voffA);
;             PG8_WAIT_L(8); PG8_BAR; PG8_WAIT_L(0); PG8_MMA(0, 0, At, B0); PG8_BAR; PG8_SCHED;
;             PG8_LDB(B1, 0, 1); PG8_STAGE(PG8_SB(0, 0), b2, voffB);
;             PG8_BAR; PG8_WAIT_L(0); PG8_MMA(0, 1, At, B1); PG8_BAR;
;             PG8_LDA(At, 0, 1); PG8_STAGE(PG8_SA(0, 0), a2, voffA);
;             PG8_BAR; PG8_WAIT_L(0); PG8_MMA(1, 0, At, B0); PG8_BAR; PG8_SCHED;
;             PG8_STAGE(PG8_SB(0, 1), b2 + hstep, voffB);
;             PG8_WAIT_V(6); PG8_BAR; PG8_MMA(1, 1, At, B1); PG8_BAR;
.LBB0_354:
	s_add_u32 s38, s50, 0xfff80080
	s_addc_u32 s39, s51, -1
	s_cmp_eq_u32 s70, 28
	s_cselect_b32 s55, s9, s39
	s_cselect_b32 s54, s66, s38
	s_cselect_b32 s53, s43, s69
	s_cselect_b32 s52, s67, s68
	s_add_i32 m0, s29, 0xc000
	s_nop 0
	global_load_lds_dwordx4 v138, s[50:51]
	s_add_i32 m0, s29, 0xe000
	s_nop 0
	global_load_lds_dwordx4 v136, s[50:51]
	s_add_i32 s71, 0, 0x10000
	ds_read_b128 v[140:143], v226
	ds_read_b128 v[148:151], v226 offset:1024
	ds_read_b128 v[152:155], v226 offset:2048
	ds_read_b128 v[160:163], v226 offset:3072
	ds_read_b128 v[164:167], v147
	ds_read_b128 v[168:171], v147 offset:1024
	ds_read_b128 v[172:175], v147 offset:2048
	ds_read_b128 v[176:179], v147 offset:3072
	ds_read_b128 v[180:183], v147 offset:4096
	ds_read_b128 v[184:187], v147 offset:5120
	ds_read_b128 v[188:191], v147 offset:6144
	ds_read_b128 v[192:195], v147 offset:7168
	s_add_i32 s38, 0, 0x14000
	s_waitcnt lgkmcnt(0)
	s_barrier
	v_mfma_f32_16x16x32_bf16 v[126:129], v[140:143], v[164:167], v[126:129]
	v_mfma_f32_16x16x32_bf16 v[122:125], v[152:155], v[164:167], v[122:125]
	ds_read_b128 v[196:199], v226 offset:16384
	v_mfma_f32_16x16x32_bf16 v[118:121], v[140:143], v[172:175], v[118:121]
	v_mfma_f32_16x16x32_bf16 v[110:113], v[152:155], v[172:175], v[110:113]
	ds_read_b128 v[200:203], v226 offset:17408
	v_mfma_f32_16x16x32_bf16 v[102:105], v[140:143], v[180:183], v[102:105]
	v_mfma_f32_16x16x32_bf16 v[94:97], v[152:155], v[180:183], v[94:97]
	ds_read_b128 v[204:207], v226 offset:18432
	v_mfma_f32_16x16x32_bf16 v[86:89], v[140:143], v[188:191], v[86:89]
	v_mfma_f32_16x16x32_bf16 v[78:81], v[152:155], v[188:191], v[78:81]
	ds_read_b128 v[210:213], v226 offset:19456
	v_mfma_f32_16x16x32_bf16 v[126:129], v[148:151], v[168:171], v[126:129]
	v_mfma_f32_16x16x32_bf16 v[122:125], v[160:163], v[168:171], v[122:125]
	v_mfma_f32_16x16x32_bf16 v[118:121], v[148:151], v[176:179], v[118:121]
	v_mfma_f32_16x16x32_bf16 v[110:113], v[160:163], v[176:179], v[110:113]
	v_mfma_f32_16x16x32_bf16 v[102:105], v[148:151], v[184:187], v[102:105]
	v_mfma_f32_16x16x32_bf16 v[94:97], v[160:163], v[184:187], v[94:97]
	v_mfma_f32_16x16x32_bf16 v[86:89], v[148:151], v[192:195], v[86:89]
	v_mfma_f32_16x16x32_bf16 v[78:81], v[160:163], v[192:195], v[78:81]
	s_waitcnt lgkmcnt(0)
	v_mfma_f32_16x16x32_bf16 v[114:117], v[196:199], v[164:167], v[114:117]
	v_mfma_f32_16x16x32_bf16 v[106:109], v[204:207], v[164:167], v[106:109]
	v_mfma_f32_16x16x32_bf16 v[98:101], v[196:199], v[172:175], v[98:101]
	v_mfma_f32_16x16x32_bf16 v[90:93], v[204:207], v[172:175], v[90:93]
	v_mfma_f32_16x16x32_bf16 v[82:85], v[196:199], v[180:183], v[82:85]
	v_mfma_f32_16x16x32_bf16 v[74:77], v[204:207], v[180:183], v[74:77]
	v_mfma_f32_16x16x32_bf16 v[70:73], v[196:199], v[188:191], v[70:73]
	v_mfma_f32_16x16x32_bf16 v[66:69], v[204:207], v[188:191], v[66:69]
	v_mfma_f32_16x16x32_bf16 v[114:117], v[200:203], v[168:171], v[114:117]
	v_mfma_f32_16x16x32_bf16 v[106:109], v[210:213], v[168:171], v[106:109]
	v_mfma_f32_16x16x32_bf16 v[98:101], v[200:203], v[176:179], v[98:101]
	v_mfma_f32_16x16x32_bf16 v[90:93], v[210:213], v[176:179], v[90:93]
	v_mfma_f32_16x16x32_bf16 v[82:85], v[200:203], v[184:187], v[82:85]
	v_mfma_f32_16x16x32_bf16 v[74:77], v[210:213], v[184:187], v[74:77]
	v_mfma_f32_16x16x32_bf16 v[70:73], v[200:203], v[192:195], v[70:73]
	v_mfma_f32_16x16x32_bf16 v[66:69], v[210:213], v[192:195], v[66:69]
	s_barrier
	s_add_i32 s39, s71, s56
	s_mov_b32 m0, s39
	s_nop 0
	global_load_lds_dwordx4 v0, s[52:53]
	s_add_i32 m0, s39, 0x2000
	s_nop 0
	global_load_lds_dwordx4 v134, s[52:53]
	s_mov_b32 m0, s29
	s_nop 0
	global_load_lds_dwordx4 v130, s[54:55]
	s_mov_b32 m0, s41
	s_nop 0
	global_load_lds_dwordx4 v132, s[54:55]
	ds_read_b128 v[164:167], v147 offset:16384
	ds_read_b128 v[168:171], v147 offset:17408
	ds_read_b128 v[172:175], v147 offset:18432
	ds_read_b128 v[176:179], v147 offset:19456
	ds_read_b128 v[180:183], v147 offset:20480
	ds_read_b128 v[184:187], v147 offset:21504
	ds_read_b128 v[188:191], v147 offset:22528
	ds_read_b128 v[192:195], v147 offset:23552
	s_waitcnt vmcnt(4)
	s_waitcnt lgkmcnt(0)
	s_barrier
	v_mfma_f32_16x16x32_bf16 v[62:65], v[140:143], v[164:167], v[62:65]
	v_mfma_f32_16x16x32_bf16 v[58:61], v[152:155], v[164:167], v[58:61]
	v_mfma_f32_16x16x32_bf16 v[54:57], v[140:143], v[172:175], v[54:57]
	v_mfma_f32_16x16x32_bf16 v[46:49], v[152:155], v[172:175], v[46:49]
	v_mfma_f32_16x16x32_bf16 v[38:41], v[140:143], v[180:183], v[38:41]
	v_mfma_f32_16x16x32_bf16 v[30:33], v[152:155], v[180:183], v[30:33]
	v_mfma_f32_16x16x32_bf16 v[22:25], v[140:143], v[188:191], v[22:25]
	v_mfma_f32_16x16x32_bf16 v[14:17], v[152:155], v[188:191], v[14:17]
	v_mfma_f32_16x16x32_bf16 v[62:65], v[148:151], v[168:171], v[62:65]
	v_mfma_f32_16x16x32_bf16 v[58:61], v[160:163], v[168:171], v[58:61]
	v_mfma_f32_16x16x32_bf16 v[54:57], v[148:151], v[176:179], v[54:57]
	v_mfma_f32_16x16x32_bf16 v[46:49], v[160:163], v[176:179], v[46:49]
	v_mfma_f32_16x16x32_bf16 v[38:41], v[148:151], v[184:187], v[38:41]
	v_mfma_f32_16x16x32_bf16 v[30:33], v[160:163], v[184:187], v[30:33]
	v_mfma_f32_16x16x32_bf16 v[22:25], v[148:151], v[192:195], v[22:25]
	v_mfma_f32_16x16x32_bf16 v[14:17], v[160:163], v[192:195], v[14:17]
	v_mfma_f32_16x16x32_bf16 v[50:53], v[196:199], v[164:167], v[50:53]
	v_mfma_f32_16x16x32_bf16 v[42:45], v[204:207], v[164:167], v[42:45]
	v_mfma_f32_16x16x32_bf16 v[34:37], v[196:199], v[172:175], v[34:37]
	v_mfma_f32_16x16x32_bf16 v[26:29], v[204:207], v[172:175], v[26:29]
	v_mfma_f32_16x16x32_bf16 v[18:21], v[196:199], v[180:183], v[18:21]
	v_mfma_f32_16x16x32_bf16 v[10:13], v[204:207], v[180:183], v[10:13]
	v_mfma_f32_16x16x32_bf16 v[6:9], v[196:199], v[188:191], v[6:9]
	v_mfma_f32_16x16x32_bf16 v[2:5], v[204:207], v[188:191], v[2:5]
	v_mfma_f32_16x16x32_bf16 v[50:53], v[200:203], v[168:171], v[50:53]
	v_mfma_f32_16x16x32_bf16 v[42:45], v[210:213], v[168:171], v[42:45]
	v_mfma_f32_16x16x32_bf16 v[34:37], v[200:203], v[176:179], v[34:37]
	v_mfma_f32_16x16x32_bf16 v[26:29], v[210:213], v[176:179], v[26:29]
	v_mfma_f32_16x16x32_bf16 v[18:21], v[200:203], v[184:187], v[18:21]
	v_mfma_f32_16x16x32_bf16 v[10:13], v[210:213], v[184:187], v[10:13]
	v_mfma_f32_16x16x32_bf16 v[6:9], v[200:203], v[192:195], v[6:9]
	v_mfma_f32_16x16x32_bf16 v[2:5], v[210:213], v[192:195], v[2:5]
	s_barrier
; #define PG8_STAGE(bufoff, gbase, voff) do { _Pragma("unroll") for (int _i = 0; _i < 2; ++_i) \
;         __builtin_amdgcn_global_load_lds((const unsigned*)((const char*)(gbase) + (voff)[_i]), (LAS unsigned*)(lds + (bufoff) + ldsw + _i * 8192), 16, 0, 0); } while (0)
; #define PG8_LDA(dst, b, h) do { _Pragma("unroll") for (int m = 0; m < 4; ++m) _Pragma("unroll") for (int k = 0; k < 2; ++k) dst[m][k] = *(const LAS bf16x8*)(lds + PG8_SA(b, h) + aoff + m * 2048 + k * 1024); } while (0)
; #define PG8_LDB(dst, b, h) do { _Pragma("unroll") for (int n = 0; n < 2; ++n) _Pragma("unroll") for (int k = 0; k < 2; ++k) dst[n][k] = *(const LAS bf16x8*)(lds + PG8_SB(b, h) + boff + n * 2048 + k * 1024); } while (0)
; #define PG8_MMA(ai, bj, At, Bt) do { __builtin_amdgcn_s_setprio(1); _Pragma("unroll") for (int m = 0; m < 4; ++m) _Pragma("unroll") for (int n = 0; n < 2; ++n) _Pragma("unroll") for (int k = 0; k < 2; ++k) \
;         acc[ai][bj][m][n] = __builtin_amdgcn_mfma_f32_16x16x32_bf16(Bt[n][k], At[m][k], acc[ai][bj][m][n], 0, 0, 0); __builtin_amdgcn_s_setprio(0); } while (0)
; #define PG8_WAIT_L(n) asm volatile("s_waitcnt lgkmcnt(" #n ")" ::: "memory")
; #define PG8_BAR __builtin_amdgcn_s_barrier()
; #define PG8_SCHED __builtin_amdgcn_sched_barrier(0)
; template <class Epi, class Sched>
; __device__ __forceinline__ void gemm_phase(LAS unsigned char* lds, const Gemm g, const Sched& S, const Epi& E) {
;     ...
;             PG8_LDB(B0, 1, 0); PG8_SCHED; PG8_LDA(At, 1, 0); PG8_STAGE(PG8_SA(0, 1), a2 + hstep, voffA);
;             PG8_WAIT_L(8); PG8_BAR; PG8_WAIT_L(0); PG8_MMA(0, 0, At, B0); PG8_BAR; PG8_SCHED;
;             PG8_LDB(B1, 1, 1); PG8_STAGE(PG8_SB(1, 0), b3, voffB);
;             PG8_BAR; PG8_WAIT_L(0); PG8_MMA(0, 1, At, B1); PG8_BAR;
;             PG8_LDA(At, 1, 1); PG8_STAGE(PG8_SA(1, 0), a3, voffA);
;             PG8_BAR; PG8_WAIT_L(0); PG8_MMA(1, 0, At, B0); PG8_BAR; PG8_SCHED;
	s_add_u32 s72, s52, 0x80000
	s_addc_u32 s73, s53, 0
	s_add_i32 s38, s38, s56
	s_mov_b32 m0, s38
	s_nop 0
	global_load_lds_dwordx4 v0, s[72:73]
	s_add_i32 m0, s38, 0x2000
	s_nop 0
	global_load_lds_dwordx4 v134, s[72:73]
	s_add_u32 s54, s54, 0x80000
	s_addc_u32 s55, s55, 0
	s_mov_b32 m0, s57
	s_nop 0
	global_load_lds_dwordx4 v130, s[54:55]
	s_mov_b32 m0, s58
	s_nop 0
	global_load_lds_dwordx4 v132, s[54:55]
	s_add_i32 s38, 0, 0x18000
	ds_read_b128 v[140:143], v226 offset:32768
	ds_read_b128 v[148:151], v226 offset:33792
	ds_read_b128 v[152:155], v226 offset:34816
	ds_read_b128 v[160:163], v226 offset:35840
	ds_read_b128 v[164:167], v147 offset:32768
	ds_read_b128 v[168:171], v147 offset:33792
	ds_read_b128 v[172:175], v147 offset:34816
	ds_read_b128 v[176:179], v147 offset:35840
	ds_read_b128 v[180:183], v147 offset:36864
	ds_read_b128 v[184:187], v147 offset:37888
	ds_read_b128 v[188:191], v147 offset:38912
	ds_read_b128 v[192:195], v147 offset:39936
	s_add_i32 s39, 0, 0x1c000
	s_waitcnt lgkmcnt(0)
	s_barrier
	v_mfma_f32_16x16x32_bf16 v[126:129], v[140:143], v[164:167], v[126:129]
	v_mfma_f32_16x16x32_bf16 v[122:125], v[152:155], v[164:167], v[122:125]
	ds_read_b128 v[196:199], v226 offset:49152
	v_mfma_f32_16x16x32_bf16 v[118:121], v[140:143], v[172:175], v[118:121]
	v_mfma_f32_16x16x32_bf16 v[110:113], v[152:155], v[172:175], v[110:113]
	ds_read_b128 v[200:203], v226 offset:50176
	v_mfma_f32_16x16x32_bf16 v[102:105], v[140:143], v[180:183], v[102:105]
	v_mfma_f32_16x16x32_bf16 v[94:97], v[152:155], v[180:183], v[94:97]
	ds_read_b128 v[204:207], v226 offset:51200
	v_mfma_f32_16x16x32_bf16 v[86:89], v[140:143], v[188:191], v[86:89]
	v_mfma_f32_16x16x32_bf16 v[78:81], v[152:155], v[188:191], v[78:81]
	ds_read_b128 v[210:213], v226 offset:52224
	v_mfma_f32_16x16x32_bf16 v[126:129], v[148:151], v[168:171], v[126:129]
	v_mfma_f32_16x16x32_bf16 v[122:125], v[160:163], v[168:171], v[122:125]
	v_mfma_f32_16x16x32_bf16 v[118:121], v[148:151], v[176:179], v[118:121]
	v_mfma_f32_16x16x32_bf16 v[110:113], v[160:163], v[176:179], v[110:113]
	v_mfma_f32_16x16x32_bf16 v[102:105], v[148:151], v[184:187], v[102:105]
	v_mfma_f32_16x16x32_bf16 v[94:97], v[160:163], v[184:187], v[94:97]
	v_mfma_f32_16x16x32_bf16 v[86:89], v[148:151], v[192:195], v[86:89]
	v_mfma_f32_16x16x32_bf16 v[78:81], v[160:163], v[192:195], v[78:81]
	s_waitcnt lgkmcnt(0)
	v_mfma_f32_16x16x32_bf16 v[114:117], v[196:199], v[164:167], v[114:117]
	v_mfma_f32_16x16x32_bf16 v[106:109], v[204:207], v[164:167], v[106:109]
	v_mfma_f32_16x16x32_bf16 v[98:101], v[196:199], v[172:175], v[98:101]
	v_mfma_f32_16x16x32_bf16 v[90:93], v[204:207], v[172:175], v[90:93]
	v_mfma_f32_16x16x32_bf16 v[82:85], v[196:199], v[180:183], v[82:85]
	v_mfma_f32_16x16x32_bf16 v[74:77], v[204:207], v[180:183], v[74:77]
	v_mfma_f32_16x16x32_bf16 v[70:73], v[196:199], v[188:191], v[70:73]
	v_mfma_f32_16x16x32_bf16 v[66:69], v[204:207], v[188:191], v[66:69]
	v_mfma_f32_16x16x32_bf16 v[114:117], v[200:203], v[168:171], v[114:117]
	v_mfma_f32_16x16x32_bf16 v[106:109], v[210:213], v[168:171], v[106:109]
	v_mfma_f32_16x16x32_bf16 v[98:101], v[200:203], v[176:179], v[98:101]
	v_mfma_f32_16x16x32_bf16 v[90:93], v[210:213], v[176:179], v[90:93]
	v_mfma_f32_16x16x32_bf16 v[82:85], v[200:203], v[184:187], v[82:85]
	v_mfma_f32_16x16x32_bf16 v[74:77], v[210:213], v[184:187], v[74:77]
	v_mfma_f32_16x16x32_bf16 v[70:73], v[200:203], v[192:195], v[70:73]
	v_mfma_f32_16x16x32_bf16 v[66:69], v[210:213], v[192:195], v[66:69]
	s_barrier
	s_add_i32 s38, s38, s56
	s_add_u32 s100, s52, s36
	s_addc_u32 s101, s53, s37
	s_mov_b32 m0, s38
	s_nop 0
	global_load_lds_dwordx4 v0, s[100:101]
	s_add_i32 m0, s38, 0x2000
	s_nop 0
	global_load_lds_dwordx4 v134, s[100:101]
	s_mov_b32 m0, s59
	s_add_u32 s100, s54, s36
	s_addc_u32 s101, s55, s37
	s_sub_u32 s100, s100, 0x80000
	s_subb_u32 s101, s101, 0
	global_load_lds_dwordx4 v130, s[100:101]
	s_mov_b32 m0, s60
	s_nop 0
	global_load_lds_dwordx4 v132, s[100:101]
	ds_read_b128 v[164:167], v147 offset:49152
	ds_read_b128 v[168:171], v147 offset:50176
	ds_read_b128 v[172:175], v147 offset:51200
	ds_read_b128 v[176:179], v147 offset:52224
	ds_read_b128 v[180:183], v147 offset:53248
	ds_read_b128 v[184:187], v147 offset:54272
	ds_read_b128 v[188:191], v147 offset:55296
	ds_read_b128 v[192:195], v147 offset:56320
	s_waitcnt vmcnt(4)
	s_waitcnt lgkmcnt(0)
	s_barrier
; #define PG8_STAGE(bufoff, gbase, voff) do { _Pragma("unroll") for (int _i = 0; _i < 2; ++_i) \
;         __builtin_amdgcn_global_load_lds((const unsigned*)((const char*)(gbase) + (voff)[_i]), (LAS unsigned*)(lds + (bufoff) + ldsw + _i * 8192), 16, 0, 0); } while (0)
; #define PG8_MMA(ai, bj, At, Bt) do { __builtin_amdgcn_s_setprio(1); _Pragma("unroll") for (int m = 0; m < 4; ++m) _Pragma("unroll") for (int n = 0; n < 2; ++n) _Pragma("unroll") for (int k = 0; k < 2; ++k) \
;         acc[ai][bj][m][n] = __builtin_amdgcn_mfma_f32_16x16x32_bf16(Bt[n][k], At[m][k], acc[ai][bj][m][n], 0, 0, 0); __builtin_amdgcn_s_setprio(0); } while (0)
; #define PG8_WAIT_V(n) asm volatile("s_waitcnt vmcnt(" #n ")" ::: "memory")
; #define PG8_BAR __builtin_amdgcn_s_barrier()
; template <class Epi, class Sched>
; __device__ __forceinline__ void gemm_phase(LAS unsigned char* lds, const Gemm g, const Sched& S, const Epi& E) {
;     ...
;             PG8_STAGE(PG8_SB(1, 1), b3 + hstep, voffB);
;             PG8_WAIT_V(6); PG8_BAR; PG8_MMA(1, 1, At, B1); PG8_BAR;
;         }
	v_mfma_f32_16x16x32_bf16 v[62:65], v[140:143], v[164:167], v[62:65]
	v_mfma_f32_16x16x32_bf16 v[58:61], v[152:155], v[164:167], v[58:61]
	v_mfma_f32_16x16x32_bf16 v[54:57], v[140:143], v[172:175], v[54:57]
	v_mfma_f32_16x16x32_bf16 v[46:49], v[152:155], v[172:175], v[46:49]
	v_mfma_f32_16x16x32_bf16 v[38:41], v[140:143], v[180:183], v[38:41]
	v_mfma_f32_16x16x32_bf16 v[30:33], v[152:155], v[180:183], v[30:33]
	v_mfma_f32_16x16x32_bf16 v[22:25], v[140:143], v[188:191], v[22:25]
	v_mfma_f32_16x16x32_bf16 v[14:17], v[152:155], v[188:191], v[14:17]
	v_mfma_f32_16x16x32_bf16 v[62:65], v[148:151], v[168:171], v[62:65]
	v_mfma_f32_16x16x32_bf16 v[58:61], v[160:163], v[168:171], v[58:61]
	v_mfma_f32_16x16x32_bf16 v[54:57], v[148:151], v[176:179], v[54:57]
	v_mfma_f32_16x16x32_bf16 v[46:49], v[160:163], v[176:179], v[46:49]
	v_mfma_f32_16x16x32_bf16 v[38:41], v[148:151], v[184:187], v[38:41]
	v_mfma_f32_16x16x32_bf16 v[30:33], v[160:163], v[184:187], v[30:33]
	v_mfma_f32_16x16x32_bf16 v[22:25], v[148:151], v[192:195], v[22:25]
	v_mfma_f32_16x16x32_bf16 v[14:17], v[160:163], v[192:195], v[14:17]
	s_add_u32 s52, s52, 0x80080
	s_addc_u32 s53, s53, 0
	s_add_i32 s38, s39, s56
	s_mov_b32 m0, s38
	s_nop 0
	global_load_lds_dwordx4 v0, s[52:53]
	s_add_i32 m0, s38, 0x2000
	s_nop 0
	global_load_lds_dwordx4 v134, s[52:53]
	v_mfma_f32_16x16x32_bf16 v[50:53], v[196:199], v[164:167], v[50:53]
	v_mfma_f32_16x16x32_bf16 v[42:45], v[204:207], v[164:167], v[42:45]
	v_mfma_f32_16x16x32_bf16 v[34:37], v[196:199], v[172:175], v[34:37]
	v_mfma_f32_16x16x32_bf16 v[26:29], v[204:207], v[172:175], v[26:29]
	v_mfma_f32_16x16x32_bf16 v[18:21], v[196:199], v[180:183], v[18:21]
	v_mfma_f32_16x16x32_bf16 v[10:13], v[204:207], v[180:183], v[10:13]
	v_mfma_f32_16x16x32_bf16 v[6:9], v[196:199], v[188:191], v[6:9]
	v_mfma_f32_16x16x32_bf16 v[2:5], v[204:207], v[188:191], v[2:5]
	v_mfma_f32_16x16x32_bf16 v[50:53], v[200:203], v[168:171], v[50:53]
	v_mfma_f32_16x16x32_bf16 v[42:45], v[210:213], v[168:171], v[42:45]
	v_mfma_f32_16x16x32_bf16 v[34:37], v[200:203], v[176:179], v[34:37]
	v_mfma_f32_16x16x32_bf16 v[26:29], v[210:213], v[176:179], v[26:29]
	v_mfma_f32_16x16x32_bf16 v[18:21], v[200:203], v[184:187], v[18:21]
	v_mfma_f32_16x16x32_bf16 v[10:13], v[210:213], v[184:187], v[10:13]
	v_mfma_f32_16x16x32_bf16 v[6:9], v[200:203], v[192:195], v[6:9]
	v_mfma_f32_16x16x32_bf16 v[2:5], v[210:213], v[192:195], v[2:5]
	s_add_i32 s70, s70, 2
	s_add_u32 s68, s68, 0x100
	s_addc_u32 s69, s69, 0
	s_add_u32 s50, s50, 0x100
	s_addc_u32 s51, s51, 0
	s_cmp_gt_u32 s70, 29
	s_barrier
	s_cbranch_scc0 .LBB0_354
; __device__ __forceinline__ unsigned cvt_pk_bf16(float lo, float hi) { unsigned r; asm("v_cvt_pk_bf16_f32 %0, %1, %2" : "=v"(r) : "v"(lo), "v"(hi)); return r; }
;     __device__ __forceinline__ void operator()(const f32x4 (&acc)[2][2][4][2], const Unit& u, int wr, int wc, int fr, int fq) const {
;         const int row0 = u.pm * BM + wr * 64 + fr, col0 = u.pn * BM + wc * 32 + 8 * fq;
; #pragma unroll
;         for (int ai = 0; ai < 2; ++ai)
; #pragma unroll
;             for (int m = 0; m < 4; ++m) { bf16_t* rowp = O + (size_t)(row0 + ai * HALF + m * 16) * ldc + col0;
; #pragma unroll
;                 for (int bj = 0; bj < 2; ++bj) { f32x4 v0 = acc[ai][bj][m][0], v1 = acc[ai][bj][m][1];
;                     if (ACT == 1) {
; #pragma unroll
;                         for (int j = 0; j < 4; ++j) { float a = fmaxf(v0[j], 0.f), b = fmaxf(v1[j], 0.f); v0[j] = a * a; v1[j] = b * b; } }
;                     u32x4 w; w.x = cvt_pk_bf16(v0[0], v0[1]); w.y = cvt_pk_bf16(v0[2], v0[3]); w.z = cvt_pk_bf16(v1[0], v1[1]); w.w = cvt_pk_bf16(v1[2], v1[3]);
;                     if (ACT == 1) __builtin_nontemporal_store(w, (u32x4*)(rowp + bj * HALF));
;                     else *(u32x4*)(rowp + bj * HALF) = w; } }
;     }
; template <class Epi, class Sched>
; __device__ __forceinline__ void gemm_phase(LAS unsigned char* lds, const Gemm g, const Sched& S, const Epi& E) {
;     ...
;         E(acc, cur, wr, wc, fr, fq);
;         if (!has_next) break;
	s_load_dwordx2 s[50:51], s[0:1], 0xc0
	v_lshl_add_u32 v150, s28, 8, v144
	v_lshl_or_b32 v142, s40, 8, v146
	v_ashrrev_i32_e32 v143, 31, v142
	v_cvt_pk_bf16_f32 v70, v70, v71
	s_waitcnt lgkmcnt(0)
	v_mov_b64_e32 v[140:141], s[50:51]
	v_cvt_pk_bf16_f32 v71, v72, v73
	v_cvt_pk_bf16_f32 v72, v66, v67
	v_add_u32_e32 v66, 0x80, v150
	v_mad_i64_i32 v[148:149], s[50:51], v150, s17, v[140:141]
	v_lshlrev_b64 v[142:143], 1, v[142:143]
	v_cvt_pk_bf16_f32 v114, v114, v115
	v_cvt_pk_bf16_f32 v115, v116, v117
	v_cvt_pk_bf16_f32 v116, v106, v107
	v_or_b32_e32 v106, 16, v150
	v_mad_i64_i32 v[66:67], s[50:51], v66, s17, v[140:141]
	v_cvt_pk_bf16_f32 v50, v50, v51
	v_cvt_pk_bf16_f32 v51, v52, v53
	v_cvt_pk_bf16_f32 v52, v42, v43
	v_add_u32_e32 v42, 0x90, v150
	v_lshl_add_u64 v[148:149], v[148:149], 0, v[142:143]
	v_mad_i64_i32 v[106:107], s[50:51], v106, s17, v[140:141]
	v_cvt_pk_bf16_f32 v98, v98, v99
	v_cvt_pk_bf16_f32 v99, v100, v101
	v_cvt_pk_bf16_f32 v100, v90, v91
	v_or_b32_e32 v90, 32, v150
	v_lshl_add_u64 v[66:67], v[66:67], 0, v[142:143]
	v_mad_i64_i32 v[42:43], s[50:51], v42, s17, v[140:141]
	v_cvt_pk_bf16_f32 v34, v34, v35
	v_cvt_pk_bf16_f32 v35, v36, v37
	v_cvt_pk_bf16_f32 v36, v26, v27
	v_add_u32_e32 v26, 0xa0, v150
	v_cvt_pk_bf16_f32 v117, v108, v109
	global_store_dwordx4 v[148:149], v[114:117], off offset:256
	v_mad_i64_i32 v[90:91], s[50:51], v90, s17, v[140:141]
	s_nop 0
	v_lshl_add_u64 v[114:115], v[106:107], 0, v[142:143]
	v_cvt_pk_bf16_f32 v82, v82, v83
	v_cvt_pk_bf16_f32 v83, v84, v85
	v_cvt_pk_bf16_f32 v84, v74, v75
	v_or_b32_e32 v74, 48, v150
	v_cvt_pk_bf16_f32 v53, v44, v45
	global_store_dwordx4 v[66:67], v[50:53], off offset:256
	v_mad_i64_i32 v[26:27], s[50:51], v26, s17, v[140:141]
	s_nop 0
	v_lshl_add_u64 v[50:51], v[42:43], 0, v[142:143]
	v_cvt_pk_bf16_f32 v18, v18, v19
	v_cvt_pk_bf16_f32 v19, v20, v21
	v_cvt_pk_bf16_f32 v20, v10, v11
	v_add_u32_e32 v10, 0xb0, v150
	v_cvt_pk_bf16_f32 v101, v92, v93
	global_store_dwordx4 v[114:115], v[98:101], off offset:256
	v_mad_i64_i32 v[74:75], s[50:51], v74, s17, v[140:141]
	s_nop 0
	v_lshl_add_u64 v[98:99], v[90:91], 0, v[142:143]
	v_cvt_pk_bf16_f32 v37, v28, v29
	global_store_dwordx4 v[50:51], v[34:37], off offset:256
	v_mad_i64_i32 v[10:11], s[50:51], v10, s17, v[140:141]
	s_nop 0
	v_lshl_add_u64 v[34:35], v[26:27], 0, v[142:143]
	v_cvt_pk_bf16_f32 v85, v76, v77
	global_store_dwordx4 v[98:99], v[82:85], off offset:256
	v_cvt_pk_bf16_f32 v21, v12, v13
	global_store_dwordx4 v[34:35], v[18:21], off offset:256
	s_and_b64 vcc, exec, s[46:47]
	v_lshl_add_u64 v[82:83], v[74:75], 0, v[142:143]
	v_lshl_add_u64 v[18:19], v[10:11], 0, v[142:143]
	s_mov_b32 s40, s42
	s_mov_b32 s28, s8
	s_mov_b32 s43, s42
	s_mov_b32 s46, s8
	s_mov_b64 s[50:51], s[48:49]
	s_mov_b64 s[52:53], s[44:45]
	v_cvt_pk_bf16_f32 v126, v126, v127
	v_cvt_pk_bf16_f32 v127, v128, v129
	v_cvt_pk_bf16_f32 v128, v122, v123
	v_cvt_pk_bf16_f32 v129, v124, v125
	global_store_dwordx4 v[148:149], v[126:129], off
	v_cvt_pk_bf16_f32 v106, v118, v119
	v_cvt_pk_bf16_f32 v107, v120, v121
	v_cvt_pk_bf16_f32 v108, v110, v111
	v_cvt_pk_bf16_f32 v109, v112, v113
	global_store_dwordx4 v[114:115], v[106:109], off
	v_cvt_pk_bf16_f32 v90, v102, v103
	v_cvt_pk_bf16_f32 v91, v104, v105
	v_cvt_pk_bf16_f32 v92, v94, v95
	v_cvt_pk_bf16_f32 v93, v96, v97
	global_store_dwordx4 v[98:99], v[90:93], off
	v_cvt_pk_bf16_f32 v74, v86, v87
	v_cvt_pk_bf16_f32 v75, v88, v89
	v_cvt_pk_bf16_f32 v76, v78, v79
	v_cvt_pk_bf16_f32 v77, v80, v81
	global_store_dwordx4 v[82:83], v[74:77], off
	v_cvt_pk_bf16_f32 v73, v68, v69
	global_store_dwordx4 v[82:83], v[70:73], off offset:256
	v_cvt_pk_bf16_f32 v62, v62, v63
	v_cvt_pk_bf16_f32 v63, v64, v65
	v_cvt_pk_bf16_f32 v64, v58, v59
	v_cvt_pk_bf16_f32 v65, v60, v61
	global_store_dwordx4 v[66:67], v[62:65], off
	v_cvt_pk_bf16_f32 v42, v54, v55
	v_cvt_pk_bf16_f32 v43, v56, v57
	v_cvt_pk_bf16_f32 v44, v46, v47
	v_cvt_pk_bf16_f32 v45, v48, v49
	global_store_dwordx4 v[50:51], v[42:45], off
	v_cvt_pk_bf16_f32 v26, v38, v39
	v_cvt_pk_bf16_f32 v27, v40, v41
	v_cvt_pk_bf16_f32 v28, v30, v31
	v_cvt_pk_bf16_f32 v29, v32, v33
	global_store_dwordx4 v[34:35], v[26:29], off
	v_cvt_pk_bf16_f32 v10, v22, v23
	v_cvt_pk_bf16_f32 v11, v24, v25
	v_cvt_pk_bf16_f32 v12, v14, v15
	v_cvt_pk_bf16_f32 v13, v16, v17
	global_store_dwordx4 v[18:19], v[10:13], off
	v_cvt_pk_bf16_f32 v6, v6, v7
	v_cvt_pk_bf16_f32 v7, v8, v9
	v_cvt_pk_bf16_f32 v8, v2, v3
	v_cvt_pk_bf16_f32 v9, v4, v5
	global_store_dwordx4 v[18:19], v[6:9], off offset:256
	s_cbranch_vccz .LBB0_346
	s_waitcnt vmcnt(0)
	s_cmpk_gt_u32 s25, 0xff
	s_cbranch_scc1 .LBB0_358
	s_barrier
